# GEMM 8-phase loops: per-phase vmcnt(10) waits instead of two vmcnt(6) per iteration (each LDS-DMA stage gets 5 phases to land instead of 3)
# speedup vs baseline: 1.0056x; 1.0056x over previous
.LBB0_190:
	ds_read_b128 v[180:183], v172
	ds_read_b128 v[184:187], v172 offset:1024
	ds_read_b128 v[188:191], v172 offset:2048
	ds_read_b128 v[192:195], v172 offset:3072
	v_add_u32_e32 v178, 0xc000, v152
	v_lshl_add_u64 v[244:245], s[20:21], 0, v[146:147]
	v_readfirstlane_b32 s1, v178
	v_add_u32_e32 v179, 0xe000, v152
	v_lshl_add_u64 v[224:225], v[244:245], 0, s[48:49]
	s_mov_b32 m0, s1
	v_lshl_add_u64 v[246:247], s[20:21], 0, v[148:149]
	v_readfirstlane_b32 s1, v179
	ds_read_b128 v[174:177], v161
	ds_read_b128 v[196:199], v161 offset:1024
	ds_read_b128 v[200:203], v160
	ds_read_b128 v[204:207], v160 offset:1024
	ds_read_b128 v[208:211], v159
	ds_read_b128 v[212:215], v159 offset:1024
	ds_read_b128 v[216:219], v158
	ds_read_b128 v[220:223], v158 offset:1024
	global_load_lds_dwordx4 v[224:225], off
	v_lshl_add_u64 v[224:225], v[246:247], 0, s[48:49]
	s_mov_b32 m0, s1
	s_nop 0
	global_load_lds_dwordx4 v[224:225], off
	s_waitcnt vmcnt(10)
	s_waitcnt lgkmcnt(8)
	s_barrier
	s_waitcnt lgkmcnt(0)
	s_setprio 1
	s_waitcnt lgkmcnt(0)
	v_mfma_f32_16x16x32_bf16 v[124:127], v[180:183], v[174:177], v[124:127]
	v_mfma_f32_16x16x32_bf16 v[120:123], v[188:191], v[174:177], v[120:123]
	v_mfma_f32_16x16x32_bf16 v[116:119], v[180:183], v[200:203], v[116:119]
	v_mfma_f32_16x16x32_bf16 v[112:115], v[188:191], v[200:203], v[112:115]
	v_mfma_f32_16x16x32_bf16 v[108:111], v[180:183], v[208:211], v[108:111]
	v_mfma_f32_16x16x32_bf16 v[104:107], v[188:191], v[208:211], v[104:107]
	v_mfma_f32_16x16x32_bf16 v[100:103], v[180:183], v[216:219], v[100:103]
	v_mfma_f32_16x16x32_bf16 v[96:99], v[188:191], v[216:219], v[96:99]
	v_mfma_f32_16x16x32_bf16 v[124:127], v[184:187], v[196:199], v[124:127]
	v_mfma_f32_16x16x32_bf16 v[120:123], v[192:195], v[196:199], v[120:123]
	v_mfma_f32_16x16x32_bf16 v[116:119], v[184:187], v[204:207], v[116:119]
	v_mfma_f32_16x16x32_bf16 v[112:115], v[192:195], v[204:207], v[112:115]
	v_mfma_f32_16x16x32_bf16 v[108:111], v[184:187], v[212:215], v[108:111]
	v_mfma_f32_16x16x32_bf16 v[104:107], v[192:195], v[212:215], v[104:107]
	v_mfma_f32_16x16x32_bf16 v[100:103], v[184:187], v[220:223], v[100:103]
	v_mfma_f32_16x16x32_bf16 v[96:99], v[192:195], v[220:223], v[96:99]
	s_setprio 0
	s_barrier
	v_lshl_add_u64 v[248:249], s[20:21], 0, v[142:143]
	v_readfirstlane_b32 s1, v153
	v_add_u32_e32 v173, 0x2000, v153
	v_lshl_add_u64 v[240:241], v[248:249], 0, s[50:51]
	s_mov_b32 m0, s1
	v_lshl_add_u64 v[250:251], s[20:21], 0, v[144:145]
	v_readfirstlane_b32 s1, v173
	ds_read_b128 v[224:227], v169
	ds_read_b128 v[228:231], v169 offset:1024
	ds_read_b128 v[232:235], v169 offset:2048
	ds_read_b128 v[236:239], v169 offset:3072
	global_load_lds_dwordx4 v[240:241], off
	v_lshl_add_u64 v[240:241], v[250:251], 0, s[50:51]
	s_mov_b32 m0, s1
	s_nop 0
	global_load_lds_dwordx4 v[240:241], off
	s_waitcnt vmcnt(10)
	s_barrier
	s_waitcnt lgkmcnt(0)
	s_setprio 1
	s_waitcnt lgkmcnt(0)
	v_mfma_f32_16x16x32_bf16 v[92:95], v[224:227], v[174:177], v[92:95]
	v_mfma_f32_16x16x32_bf16 v[88:91], v[232:235], v[174:177], v[88:91]
	v_mfma_f32_16x16x32_bf16 v[84:87], v[224:227], v[200:203], v[84:87]
	v_mfma_f32_16x16x32_bf16 v[80:83], v[232:235], v[200:203], v[80:83]
	v_mfma_f32_16x16x32_bf16 v[76:79], v[224:227], v[208:211], v[76:79]
	v_mfma_f32_16x16x32_bf16 v[72:75], v[232:235], v[208:211], v[72:75]
	v_mfma_f32_16x16x32_bf16 v[68:71], v[224:227], v[216:219], v[68:71]
	v_mfma_f32_16x16x32_bf16 v[64:67], v[232:235], v[216:219], v[64:67]
	v_mfma_f32_16x16x32_bf16 v[92:95], v[228:231], v[196:199], v[92:95]
	v_mfma_f32_16x16x32_bf16 v[88:91], v[236:239], v[196:199], v[88:91]
	v_mfma_f32_16x16x32_bf16 v[84:87], v[228:231], v[204:207], v[84:87]
	v_mfma_f32_16x16x32_bf16 v[80:83], v[236:239], v[204:207], v[80:83]
	v_mfma_f32_16x16x32_bf16 v[76:79], v[228:231], v[212:215], v[76:79]
	v_mfma_f32_16x16x32_bf16 v[72:75], v[236:239], v[212:215], v[72:75]
	v_mfma_f32_16x16x32_bf16 v[68:71], v[228:231], v[220:223], v[68:71]
	v_mfma_f32_16x16x32_bf16 v[64:67], v[236:239], v[220:223], v[64:67]
	s_setprio 0
	v_readfirstlane_b32 s1, v152
	v_lshl_add_u64 v[174:175], v[244:245], 0, s[52:53]
	s_mov_b32 m0, s1
	s_barrier
	ds_read_b128 v[196:199], v161 offset:16384
	ds_read_b128 v[200:203], v161 offset:17408
	ds_read_b128 v[204:207], v160 offset:16384
	ds_read_b128 v[208:211], v160 offset:17408
	ds_read_b128 v[212:215], v159 offset:16384
	ds_read_b128 v[216:219], v159 offset:17408
	ds_read_b128 v[220:223], v158 offset:16384
	ds_read_b128 v[240:243], v158 offset:17408
	global_load_lds_dwordx4 v[174:175], off
	v_add_u32_e32 v174, 0x2000, v152
	v_lshl_add_u64 v[176:177], v[246:247], 0, s[52:53]
	v_readfirstlane_b32 s1, v174
	s_mov_b32 m0, s1
	s_nop 0
	global_load_lds_dwordx4 v[176:177], off
	s_barrier
	s_waitcnt lgkmcnt(0)
	s_setprio 1
	s_waitcnt lgkmcnt(0)
	v_mfma_f32_16x16x32_bf16 v[60:63], v[180:183], v[196:199], v[60:63]
	v_mfma_f32_16x16x32_bf16 v[56:59], v[188:191], v[196:199], v[56:59]
	v_mfma_f32_16x16x32_bf16 v[52:55], v[180:183], v[204:207], v[52:55]
	v_mfma_f32_16x16x32_bf16 v[48:51], v[188:191], v[204:207], v[48:51]
	v_mfma_f32_16x16x32_bf16 v[44:47], v[180:183], v[212:215], v[44:47]
	v_mfma_f32_16x16x32_bf16 v[40:43], v[188:191], v[212:215], v[40:43]
	v_mfma_f32_16x16x32_bf16 v[36:39], v[180:183], v[220:223], v[36:39]
	v_mfma_f32_16x16x32_bf16 v[32:35], v[188:191], v[220:223], v[32:35]
	v_mfma_f32_16x16x32_bf16 v[60:63], v[184:187], v[200:203], v[60:63]
	v_mfma_f32_16x16x32_bf16 v[56:59], v[192:195], v[200:203], v[56:59]
	v_mfma_f32_16x16x32_bf16 v[52:55], v[184:187], v[208:211], v[52:55]
	v_mfma_f32_16x16x32_bf16 v[48:51], v[192:195], v[208:211], v[48:51]
	v_mfma_f32_16x16x32_bf16 v[44:47], v[184:187], v[216:219], v[44:47]
	v_mfma_f32_16x16x32_bf16 v[40:43], v[192:195], v[216:219], v[40:43]
	v_mfma_f32_16x16x32_bf16 v[36:39], v[184:187], v[240:243], v[36:39]
	v_mfma_f32_16x16x32_bf16 v[32:35], v[192:195], v[240:243], v[32:35]
	s_setprio 0
	s_barrier
	v_readfirstlane_b32 s1, v151
	v_add_u32_e32 v175, 0x2000, v151
	v_lshl_add_u64 v[176:177], v[248:249], 0, s[54:55]
	s_mov_b32 m0, s1
	v_readfirstlane_b32 s1, v175
	global_load_lds_dwordx4 v[176:177], off
	v_lshl_add_u64 v[176:177], v[250:251], 0, s[54:55]
	s_mov_b32 m0, s1
	s_nop 0
	global_load_lds_dwordx4 v[176:177], off
	s_waitcnt vmcnt(10)
	s_barrier
	s_setprio 1
	v_mfma_f32_16x16x32_bf16 v[28:31], v[224:227], v[196:199], v[28:31]
	v_mfma_f32_16x16x32_bf16 v[24:27], v[232:235], v[196:199], v[24:27]
	v_mfma_f32_16x16x32_bf16 v[20:23], v[224:227], v[204:207], v[20:23]
	v_mfma_f32_16x16x32_bf16 v[16:19], v[232:235], v[204:207], v[16:19]
	v_mfma_f32_16x16x32_bf16 v[12:15], v[224:227], v[212:215], v[12:15]
	v_mfma_f32_16x16x32_bf16 v[8:11], v[232:235], v[212:215], v[8:11]
	v_mfma_f32_16x16x32_bf16 v[4:7], v[224:227], v[220:223], v[4:7]
	v_mfma_f32_16x16x32_bf16 v[0:3], v[232:235], v[220:223], v[0:3]
	v_mfma_f32_16x16x32_bf16 v[28:31], v[228:231], v[200:203], v[28:31]
	v_mfma_f32_16x16x32_bf16 v[24:27], v[236:239], v[200:203], v[24:27]
	v_mfma_f32_16x16x32_bf16 v[20:23], v[228:231], v[208:211], v[20:23]
	v_mfma_f32_16x16x32_bf16 v[16:19], v[236:239], v[208:211], v[16:19]
	v_mfma_f32_16x16x32_bf16 v[12:15], v[228:231], v[216:219], v[12:15]
	v_mfma_f32_16x16x32_bf16 v[8:11], v[236:239], v[216:219], v[8:11]
	v_mfma_f32_16x16x32_bf16 v[4:7], v[228:231], v[240:243], v[4:7]
	v_mfma_f32_16x16x32_bf16 v[0:3], v[236:239], v[240:243], v[0:3]
	s_setprio 0
	s_barrier
	ds_read_b128 v[180:183], v163
	ds_read_b128 v[184:187], v163 offset:1024
	ds_read_b128 v[188:191], v163 offset:2048
	ds_read_b128 v[192:195], v163 offset:3072
	v_add_u32_e32 v176, 0x4000, v152
	v_add_u32_e32 v177, 0x6000, v152
	v_readfirstlane_b32 s1, v176
	v_lshl_add_u64 v[228:229], v[244:245], 0, s[56:57]
	s_mov_b32 m0, s1
	v_readfirstlane_b32 s1, v177
	ds_read_b128 v[196:199], v161 offset:32768
	ds_read_b128 v[200:203], v161 offset:33792
	ds_read_b128 v[204:207], v160 offset:32768
	ds_read_b128 v[208:211], v160 offset:33792
	ds_read_b128 v[212:215], v159 offset:32768
	ds_read_b128 v[216:219], v159 offset:33792
	ds_read_b128 v[220:223], v158 offset:32768
	ds_read_b128 v[224:227], v158 offset:33792
	global_load_lds_dwordx4 v[228:229], off
	v_lshl_add_u64 v[228:229], v[246:247], 0, s[56:57]
	s_mov_b32 m0, s1
	s_nop 0
	global_load_lds_dwordx4 v[228:229], off
	s_waitcnt vmcnt(10)
	s_waitcnt lgkmcnt(8)
	s_barrier
	s_waitcnt lgkmcnt(0)
	s_setprio 1
	s_waitcnt lgkmcnt(0)
	v_mfma_f32_16x16x32_bf16 v[124:127], v[180:183], v[196:199], v[124:127]
	v_mfma_f32_16x16x32_bf16 v[120:123], v[188:191], v[196:199], v[120:123]
	v_mfma_f32_16x16x32_bf16 v[116:119], v[180:183], v[204:207], v[116:119]
	v_mfma_f32_16x16x32_bf16 v[112:115], v[188:191], v[204:207], v[112:115]
	v_mfma_f32_16x16x32_bf16 v[108:111], v[180:183], v[212:215], v[108:111]
	v_mfma_f32_16x16x32_bf16 v[104:107], v[188:191], v[212:215], v[104:107]
	v_mfma_f32_16x16x32_bf16 v[100:103], v[180:183], v[220:223], v[100:103]
	v_mfma_f32_16x16x32_bf16 v[96:99], v[188:191], v[220:223], v[96:99]
	v_mfma_f32_16x16x32_bf16 v[124:127], v[184:187], v[200:203], v[124:127]
	v_mfma_f32_16x16x32_bf16 v[120:123], v[192:195], v[200:203], v[120:123]
	v_mfma_f32_16x16x32_bf16 v[116:119], v[184:187], v[208:211], v[116:119]
	v_mfma_f32_16x16x32_bf16 v[112:115], v[192:195], v[208:211], v[112:115]
	v_mfma_f32_16x16x32_bf16 v[108:111], v[184:187], v[216:219], v[108:111]
	v_mfma_f32_16x16x32_bf16 v[104:107], v[192:195], v[216:219], v[104:107]
	v_mfma_f32_16x16x32_bf16 v[100:103], v[184:187], v[224:227], v[100:103]
	v_mfma_f32_16x16x32_bf16 v[96:99], v[192:195], v[224:227], v[96:99]
	s_setprio 0
	s_barrier
	v_readfirstlane_b32 s1, v167
	v_add_u32_e32 v254, 0x2000, v167
	v_lshl_add_u64 v[252:253], v[248:249], 0, s[58:59]
	s_mov_b32 m0, s1
	v_readfirstlane_b32 s1, v254
	ds_read_b128 v[228:231], v162
	ds_read_b128 v[232:235], v162 offset:1024
	ds_read_b128 v[236:239], v162 offset:2048
	ds_read_b128 v[240:243], v162 offset:3072
	global_load_lds_dwordx4 v[252:253], off
	v_lshl_add_u64 v[252:253], v[250:251], 0, s[58:59]
	s_mov_b32 m0, s1
	s_nop 0
	global_load_lds_dwordx4 v[252:253], off
	s_waitcnt vmcnt(10)
	s_barrier
	s_waitcnt lgkmcnt(0)
	s_setprio 1
	s_waitcnt lgkmcnt(0)
	v_mfma_f32_16x16x32_bf16 v[92:95], v[228:231], v[196:199], v[92:95]
	v_mfma_f32_16x16x32_bf16 v[88:91], v[236:239], v[196:199], v[88:91]
	v_mfma_f32_16x16x32_bf16 v[84:87], v[228:231], v[204:207], v[84:87]
	v_mfma_f32_16x16x32_bf16 v[80:83], v[236:239], v[204:207], v[80:83]
	v_mfma_f32_16x16x32_bf16 v[76:79], v[228:231], v[212:215], v[76:79]
	v_mfma_f32_16x16x32_bf16 v[72:75], v[236:239], v[212:215], v[72:75]
	v_mfma_f32_16x16x32_bf16 v[68:71], v[228:231], v[220:223], v[68:71]
	v_mfma_f32_16x16x32_bf16 v[64:67], v[236:239], v[220:223], v[64:67]
	v_mfma_f32_16x16x32_bf16 v[92:95], v[232:235], v[200:203], v[92:95]
	v_mfma_f32_16x16x32_bf16 v[88:91], v[240:243], v[200:203], v[88:91]
	v_mfma_f32_16x16x32_bf16 v[84:87], v[232:235], v[208:211], v[84:87]
	v_mfma_f32_16x16x32_bf16 v[80:83], v[240:243], v[208:211], v[80:83]
	v_mfma_f32_16x16x32_bf16 v[76:79], v[232:235], v[216:219], v[76:79]
	v_mfma_f32_16x16x32_bf16 v[72:75], v[240:243], v[216:219], v[72:75]
	v_mfma_f32_16x16x32_bf16 v[68:71], v[232:235], v[224:227], v[68:71]
	v_mfma_f32_16x16x32_bf16 v[64:67], v[240:243], v[224:227], v[64:67]
	s_setprio 0
	v_readfirstlane_b32 s1, v168
	v_lshl_add_u64 v[244:245], v[244:245], 0, s[60:61]
	s_mov_b32 m0, s1
	v_readfirstlane_b32 s1, v170
	s_barrier
	ds_read_b128 v[196:199], v161 offset:49152
	ds_read_b128 v[200:203], v161 offset:50176
	ds_read_b128 v[204:207], v160 offset:49152
	ds_read_b128 v[208:211], v160 offset:50176
	ds_read_b128 v[212:215], v159 offset:49152
	ds_read_b128 v[216:219], v159 offset:50176
	ds_read_b128 v[220:223], v158 offset:49152
	ds_read_b128 v[224:227], v158 offset:50176
	global_load_lds_dwordx4 v[244:245], off
	v_lshl_add_u64 v[244:245], v[246:247], 0, s[60:61]
	s_mov_b32 m0, s1
	s_nop 0
	global_load_lds_dwordx4 v[244:245], off
	s_barrier
	s_waitcnt lgkmcnt(0)
	s_setprio 1
	s_waitcnt lgkmcnt(0)
	v_mfma_f32_16x16x32_bf16 v[60:63], v[180:183], v[196:199], v[60:63]
	v_mfma_f32_16x16x32_bf16 v[56:59], v[188:191], v[196:199], v[56:59]
	v_mfma_f32_16x16x32_bf16 v[52:55], v[180:183], v[204:207], v[52:55]
	v_mfma_f32_16x16x32_bf16 v[48:51], v[188:191], v[204:207], v[48:51]
	v_mfma_f32_16x16x32_bf16 v[44:47], v[180:183], v[212:215], v[44:47]
	v_mfma_f32_16x16x32_bf16 v[40:43], v[188:191], v[212:215], v[40:43]
	v_mfma_f32_16x16x32_bf16 v[36:39], v[180:183], v[220:223], v[36:39]
	v_mfma_f32_16x16x32_bf16 v[32:35], v[188:191], v[220:223], v[32:35]
	v_mfma_f32_16x16x32_bf16 v[60:63], v[184:187], v[200:203], v[60:63]
	v_mfma_f32_16x16x32_bf16 v[56:59], v[192:195], v[200:203], v[56:59]
	v_mfma_f32_16x16x32_bf16 v[52:55], v[184:187], v[208:211], v[52:55]
	v_mfma_f32_16x16x32_bf16 v[48:51], v[192:195], v[208:211], v[48:51]
	v_mfma_f32_16x16x32_bf16 v[44:47], v[184:187], v[216:219], v[44:47]
	v_mfma_f32_16x16x32_bf16 v[40:43], v[192:195], v[216:219], v[40:43]
	v_mfma_f32_16x16x32_bf16 v[36:39], v[184:187], v[224:227], v[36:39]
	v_mfma_f32_16x16x32_bf16 v[32:35], v[192:195], v[224:227], v[32:35]
	s_setprio 0
	s_barrier
	v_readfirstlane_b32 s1, v171
	v_add_u32_e32 v182, 0x2000, v171
	v_lshl_add_u64 v[180:181], v[248:249], 0, s[62:63]
	s_mov_b32 m0, s1
	v_readfirstlane_b32 s1, v182
	global_load_lds_dwordx4 v[180:181], off
	v_lshl_add_u64 v[180:181], v[250:251], 0, s[62:63]
	s_mov_b32 m0, s1
	s_nop 0
	global_load_lds_dwordx4 v[180:181], off
	s_waitcnt vmcnt(10)
	s_barrier
	s_setprio 1
	v_mfma_f32_16x16x32_bf16 v[28:31], v[228:231], v[196:199], v[28:31]
	v_mfma_f32_16x16x32_bf16 v[24:27], v[236:239], v[196:199], v[24:27]
	v_mfma_f32_16x16x32_bf16 v[20:23], v[228:231], v[204:207], v[20:23]
	v_mfma_f32_16x16x32_bf16 v[16:19], v[236:239], v[204:207], v[16:19]
	v_mfma_f32_16x16x32_bf16 v[12:15], v[228:231], v[212:215], v[12:15]
	v_mfma_f32_16x16x32_bf16 v[8:11], v[236:239], v[212:215], v[8:11]
	v_mfma_f32_16x16x32_bf16 v[4:7], v[228:231], v[220:223], v[4:7]
	v_mfma_f32_16x16x32_bf16 v[0:3], v[236:239], v[220:223], v[0:3]
	v_mfma_f32_16x16x32_bf16 v[28:31], v[232:235], v[200:203], v[28:31]
	v_mfma_f32_16x16x32_bf16 v[24:27], v[240:243], v[200:203], v[24:27]
	v_mfma_f32_16x16x32_bf16 v[20:23], v[232:235], v[208:211], v[20:23]
	v_mfma_f32_16x16x32_bf16 v[16:19], v[240:243], v[208:211], v[16:19]
	v_mfma_f32_16x16x32_bf16 v[12:15], v[232:235], v[216:219], v[12:15]
	v_mfma_f32_16x16x32_bf16 v[8:11], v[240:243], v[216:219], v[8:11]
	v_mfma_f32_16x16x32_bf16 v[4:7], v[232:235], v[224:227], v[4:7]
	v_mfma_f32_16x16x32_bf16 v[0:3], v[240:243], v[224:227], v[0:3]
	s_setprio 0
	s_add_i32 s0, s0, 2
	v_lshl_add_u64 v[142:143], v[142:143], 0, s[50:51]
	v_lshl_add_u64 v[144:145], v[144:145], 0, s[50:51]
	v_lshl_add_u64 v[146:147], v[146:147], 0, s[50:51]
	s_cmp_lt_u32 s0, 12
	v_lshl_add_u64 v[148:149], v[148:149], 0, s[50:51]
	s_barrier
	s_cbranch_scc1 .LBB0_190
	s_or_b32 s0, s6, 0x80
	s_ashr_i32 s1, s0, 31
	s_lshl_b64 s[0:1], s[0:1], 11
	s_add_u32 s0, s45, s0
	s_addc_u32 s1, s46, s1
	v_lshl_add_u64 v[170:171], s[0:1], 0, v[130:131]
	v_lshl_add_u64 v[138:139], v[138:139], 1, v[170:171]
	v_readfirstlane_b32 s2, v178
	v_lshl_add_u64 v[138:139], v[138:139], 0, s[64:65]
	s_mov_b32 m0, s2
	ds_read_b128 v[142:145], v172
	ds_read_b128 v[146:149], v172 offset:1024
	ds_read_b128 v[180:183], v172 offset:2048
	ds_read_b128 v[184:187], v172 offset:3072
	ds_read_b128 v[188:191], v161
	ds_read_b128 v[192:195], v161 offset:1024
	ds_read_b128 v[196:199], v160
	ds_read_b128 v[200:203], v160 offset:1024
	ds_read_b128 v[204:207], v159
	ds_read_b128 v[208:211], v159 offset:1024
	ds_read_b128 v[212:215], v158
	ds_read_b128 v[216:219], v158 offset:1024
	global_load_lds_dwordx4 v[138:139], off
	v_lshl_add_u64 v[138:139], s[0:1], 0, v[134:135]
	v_lshl_add_u64 v[138:139], v[140:141], 1, v[138:139]
	v_readfirstlane_b32 s0, v179
	v_lshl_add_u64 v[138:139], v[138:139], 0, s[64:65]
	s_mov_b32 m0, s0
	v_readlane_b32 s0, v255, 11
	global_load_lds_dwordx4 v[138:139], off
	s_waitcnt vmcnt(10)
	s_add_i32 s82, s82, s0
	s_barrier
	s_waitcnt lgkmcnt(0)
	s_cmpk_gt_i32 s82, 0x54
	s_cselect_b64 s[66:67], -1, 0
	s_setprio 1
	s_waitcnt lgkmcnt(0)
	v_mfma_f32_16x16x32_bf16 v[124:127], v[142:145], v[188:191], v[124:127]
	v_mfma_f32_16x16x32_bf16 v[116:119], v[142:145], v[196:199], v[116:119]
	v_mfma_f32_16x16x32_bf16 v[108:111], v[142:145], v[204:207], v[108:111]
	v_mfma_f32_16x16x32_bf16 v[100:103], v[142:145], v[212:215], v[100:103]
	v_mfma_f32_16x16x32_bf16 v[124:127], v[146:149], v[192:195], v[124:127]
	v_mfma_f32_16x16x32_bf16 v[120:123], v[180:183], v[188:191], v[120:123]
	v_mfma_f32_16x16x32_bf16 v[116:119], v[146:149], v[200:203], v[116:119]
	v_mfma_f32_16x16x32_bf16 v[112:115], v[180:183], v[196:199], v[112:115]
	v_mfma_f32_16x16x32_bf16 v[108:111], v[146:149], v[208:211], v[108:111]
	v_mfma_f32_16x16x32_bf16 v[104:107], v[180:183], v[204:207], v[104:107]
	v_mfma_f32_16x16x32_bf16 v[100:103], v[146:149], v[216:219], v[100:103]
	v_mfma_f32_16x16x32_bf16 v[96:99], v[180:183], v[212:215], v[96:99]
	v_mfma_f32_16x16x32_bf16 v[138:141], v[184:187], v[192:195], v[120:123]
	v_mfma_f32_16x16x32_bf16 v[220:223], v[184:187], v[200:203], v[112:115]
	v_mfma_f32_16x16x32_bf16 v[224:227], v[184:187], v[208:211], v[104:107]
	v_mfma_f32_16x16x32_bf16 v[228:231], v[184:187], v[216:219], v[96:99]
	s_setprio 0
	s_barrier
	s_nop 1
	ds_read_b128 v[96:99], v169
	ds_read_b128 v[104:107], v169 offset:1024
	ds_read_b128 v[112:115], v169 offset:2048
	ds_read_b128 v[120:123], v169 offset:3072
	s_waitcnt vmcnt(8)
	s_barrier
	s_waitcnt lgkmcnt(0)
	s_setprio 1
	s_waitcnt lgkmcnt(0)
	v_mfma_f32_16x16x32_bf16 v[92:95], v[96:99], v[188:191], v[92:95]
	v_mfma_f32_16x16x32_bf16 v[88:91], v[112:115], v[188:191], v[88:91]
	v_mfma_f32_16x16x32_bf16 v[84:87], v[96:99], v[196:199], v[84:87]
	v_mfma_f32_16x16x32_bf16 v[80:83], v[112:115], v[196:199], v[80:83]
	v_mfma_f32_16x16x32_bf16 v[76:79], v[96:99], v[204:207], v[76:79]
	v_mfma_f32_16x16x32_bf16 v[72:75], v[112:115], v[204:207], v[72:75]
	v_mfma_f32_16x16x32_bf16 v[68:71], v[96:99], v[212:215], v[68:71]
	v_mfma_f32_16x16x32_bf16 v[64:67], v[112:115], v[212:215], v[64:67]
	v_mfma_f32_16x16x32_bf16 v[92:95], v[104:107], v[192:195], v[92:95]
	v_mfma_f32_16x16x32_bf16 v[88:91], v[120:123], v[192:195], v[88:91]
	v_mfma_f32_16x16x32_bf16 v[84:87], v[104:107], v[200:203], v[84:87]
	v_mfma_f32_16x16x32_bf16 v[80:83], v[120:123], v[200:203], v[80:83]
	v_mfma_f32_16x16x32_bf16 v[76:79], v[104:107], v[208:211], v[76:79]
	v_mfma_f32_16x16x32_bf16 v[72:75], v[120:123], v[208:211], v[72:75]
	v_mfma_f32_16x16x32_bf16 v[68:71], v[104:107], v[216:219], v[68:71]
	v_mfma_f32_16x16x32_bf16 v[64:67], v[120:123], v[216:219], v[64:67]
	s_setprio 0
	s_barrier
	ds_read_b128 v[168:171], v161 offset:16384
	ds_read_b128 v[188:191], v161 offset:17408
	ds_read_b128 v[192:195], v160 offset:16384
	ds_read_b128 v[196:199], v160 offset:17408
	ds_read_b128 v[200:203], v159 offset:16384
	ds_read_b128 v[204:207], v159 offset:17408
	ds_read_b128 v[208:211], v158 offset:16384
	ds_read_b128 v[212:215], v158 offset:17408
	s_waitcnt vmcnt(4)
	s_barrier
	s_waitcnt lgkmcnt(0)
	s_setprio 1
	s_waitcnt lgkmcnt(0)
	v_mfma_f32_16x16x32_bf16 v[60:63], v[142:145], v[168:171], v[60:63]
	v_mfma_f32_16x16x32_bf16 v[52:55], v[142:145], v[192:195], v[52:55]
	v_mfma_f32_16x16x32_bf16 v[44:47], v[142:145], v[200:203], v[44:47]
	v_mfma_f32_16x16x32_bf16 v[36:39], v[142:145], v[208:211], v[36:39]
	v_mfma_f32_16x16x32_bf16 v[60:63], v[146:149], v[188:191], v[60:63]
	v_mfma_f32_16x16x32_bf16 v[56:59], v[180:183], v[168:171], v[56:59]
	v_mfma_f32_16x16x32_bf16 v[52:55], v[146:149], v[196:199], v[52:55]
	v_mfma_f32_16x16x32_bf16 v[48:51], v[180:183], v[192:195], v[48:51]
	v_mfma_f32_16x16x32_bf16 v[44:47], v[146:149], v[204:207], v[44:47]
	v_mfma_f32_16x16x32_bf16 v[40:43], v[180:183], v[200:203], v[40:43]
	v_mfma_f32_16x16x32_bf16 v[36:39], v[146:149], v[212:215], v[36:39]
	v_mfma_f32_16x16x32_bf16 v[32:35], v[180:183], v[208:211], v[32:35]
	v_mfma_f32_16x16x32_bf16 v[216:219], v[184:187], v[188:191], v[56:59]
	v_mfma_f32_16x16x32_bf16 v[232:235], v[184:187], v[196:199], v[48:51]
	v_mfma_f32_16x16x32_bf16 v[236:239], v[184:187], v[204:207], v[40:43]
	v_mfma_f32_16x16x32_bf16 v[142:145], v[184:187], v[212:215], v[32:35]
	s_setprio 0
	s_setprio 1
	v_mfma_f32_16x16x32_bf16 v[28:31], v[96:99], v[168:171], v[28:31]
	v_mfma_f32_16x16x32_bf16 v[24:27], v[112:115], v[168:171], v[24:27]
	v_mfma_f32_16x16x32_bf16 v[20:23], v[96:99], v[192:195], v[20:23]
	v_mfma_f32_16x16x32_bf16 v[16:19], v[112:115], v[192:195], v[16:19]
	v_mfma_f32_16x16x32_bf16 v[12:15], v[96:99], v[200:203], v[12:15]
	v_mfma_f32_16x16x32_bf16 v[8:11], v[112:115], v[200:203], v[8:11]
	v_mfma_f32_16x16x32_bf16 v[4:7], v[96:99], v[208:211], v[4:7]
	v_mfma_f32_16x16x32_bf16 v[0:3], v[112:115], v[208:211], v[0:3]
	v_mfma_f32_16x16x32_bf16 v[28:31], v[104:107], v[188:191], v[28:31]
	v_mfma_f32_16x16x32_bf16 v[24:27], v[120:123], v[188:191], v[24:27]
	v_mfma_f32_16x16x32_bf16 v[20:23], v[104:107], v[196:199], v[20:23]
	v_mfma_f32_16x16x32_bf16 v[16:19], v[120:123], v[196:199], v[16:19]
	v_mfma_f32_16x16x32_bf16 v[12:15], v[104:107], v[204:207], v[12:15]
	v_mfma_f32_16x16x32_bf16 v[8:11], v[120:123], v[204:207], v[8:11]
	v_mfma_f32_16x16x32_bf16 v[4:7], v[104:107], v[212:215], v[4:7]
	v_mfma_f32_16x16x32_bf16 v[0:3], v[120:123], v[212:215], v[0:3]
	s_setprio 0
	s_barrier
	ds_read_b128 v[32:35], v163
	ds_read_b128 v[146:149], v163 offset:1024
	ds_read_b128 v[168:171], v163 offset:2048
	ds_read_b128 v[178:181], v163 offset:3072
	ds_read_b128 v[40:43], v161 offset:32768
	ds_read_b128 v[48:51], v161 offset:33792
	ds_read_b128 v[56:59], v160 offset:32768
	ds_read_b128 v[182:185], v160 offset:33792
	ds_read_b128 v[186:189], v159 offset:32768
	ds_read_b128 v[190:193], v159 offset:33792
	ds_read_b128 v[194:197], v158 offset:32768
	ds_read_b128 v[198:201], v158 offset:33792
	s_waitcnt vmcnt(2)
	s_barrier
	s_waitcnt lgkmcnt(0)
	s_setprio 1
	s_waitcnt lgkmcnt(0)
	v_mfma_f32_16x16x32_bf16 v[96:99], v[32:35], v[40:43], v[124:127]
	v_mfma_f32_16x16x32_bf16 v[120:123], v[146:149], v[48:51], v[96:99]
	v_mfma_f32_16x16x32_bf16 v[96:99], v[168:171], v[40:43], v[138:141]
	v_mfma_f32_16x16x32_bf16 v[124:127], v[178:181], v[48:51], v[96:99]
	v_mfma_f32_16x16x32_bf16 v[96:99], v[32:35], v[56:59], v[116:119]
	v_mfma_f32_16x16x32_bf16 v[112:115], v[146:149], v[182:185], v[96:99]
	v_mfma_f32_16x16x32_bf16 v[96:99], v[168:171], v[56:59], v[220:223]
	v_mfma_f32_16x16x32_bf16 v[116:119], v[178:181], v[182:185], v[96:99]
	v_mfma_f32_16x16x32_bf16 v[96:99], v[32:35], v[186:189], v[108:111]
	v_mfma_f32_16x16x32_bf16 v[104:107], v[146:149], v[190:193], v[96:99]
	v_mfma_f32_16x16x32_bf16 v[96:99], v[168:171], v[186:189], v[224:227]
	v_mfma_f32_16x16x32_bf16 v[108:111], v[178:181], v[190:193], v[96:99]
	v_mfma_f32_16x16x32_bf16 v[96:99], v[32:35], v[194:197], v[100:103]
	v_mfma_f32_16x16x32_bf16 v[100:103], v[168:171], v[194:197], v[228:231]
	v_mfma_f32_16x16x32_bf16 v[96:99], v[146:149], v[198:201], v[96:99]
	v_mfma_f32_16x16x32_bf16 v[100:103], v[178:181], v[198:201], v[100:103]
	s_setprio 0
	s_barrier
	ds_read_b128 v[138:141], v162
	ds_read_b128 v[202:205], v162 offset:1024
	ds_read_b128 v[206:209], v162 offset:2048
	ds_read_b128 v[210:213], v162 offset:3072
	s_waitcnt vmcnt(0)
	s_barrier
	s_waitcnt lgkmcnt(0)
	s_setprio 1
	s_waitcnt lgkmcnt(0)
	v_mfma_f32_16x16x32_bf16 v[92:95], v[138:141], v[40:43], v[92:95]
	v_mfma_f32_16x16x32_bf16 v[40:43], v[206:209], v[40:43], v[88:91]
	v_mfma_f32_16x16x32_bf16 v[88:91], v[210:213], v[48:51], v[40:43]
	v_mfma_f32_16x16x32_bf16 v[40:43], v[138:141], v[56:59], v[84:87]
	v_mfma_f32_16x16x32_bf16 v[84:87], v[202:205], v[182:185], v[40:43]
	v_mfma_f32_16x16x32_bf16 v[40:43], v[206:209], v[56:59], v[80:83]
	v_mfma_f32_16x16x32_bf16 v[80:83], v[210:213], v[182:185], v[40:43]
	v_mfma_f32_16x16x32_bf16 v[40:43], v[138:141], v[186:189], v[76:79]
	v_mfma_f32_16x16x32_bf16 v[76:79], v[202:205], v[190:193], v[40:43]
	v_mfma_f32_16x16x32_bf16 v[40:43], v[206:209], v[186:189], v[72:75]
	v_mfma_f32_16x16x32_bf16 v[72:75], v[210:213], v[190:193], v[40:43]
	v_mfma_f32_16x16x32_bf16 v[40:43], v[138:141], v[194:197], v[68:71]
	v_mfma_f32_16x16x32_bf16 v[68:71], v[202:205], v[198:201], v[40:43]
	v_mfma_f32_16x16x32_bf16 v[40:43], v[206:209], v[194:197], v[64:67]
	v_mfma_f32_16x16x32_bf16 v[92:95], v[202:205], v[48:51], v[92:95]
	v_mfma_f32_16x16x32_bf16 v[64:67], v[210:213], v[198:201], v[40:43]
	s_setprio 0
	s_barrier
	ds_read_b128 v[182:185], v161 offset:49152
	ds_read_b128 v[186:189], v161 offset:50176
	ds_read_b128 v[190:193], v160 offset:49152
	ds_read_b128 v[160:163], v160 offset:50176
	ds_read_b128 v[194:197], v159 offset:49152
	ds_read_b128 v[198:201], v159 offset:50176
	ds_read_b128 v[220:223], v158 offset:49152
	ds_read_b128 v[224:227], v158 offset:50176
	s_barrier
	s_waitcnt lgkmcnt(0)
	s_setprio 1
	s_waitcnt lgkmcnt(0)
	v_mfma_f32_16x16x32_bf16 v[40:43], v[32:35], v[182:185], v[60:63]
	v_mfma_f32_16x16x32_bf16 v[56:59], v[146:149], v[186:189], v[40:43]
	v_mfma_f32_16x16x32_bf16 v[40:43], v[168:171], v[182:185], v[216:219]
	v_mfma_f32_16x16x32_bf16 v[60:63], v[178:181], v[186:189], v[40:43]
	v_mfma_f32_16x16x32_bf16 v[40:43], v[32:35], v[190:193], v[52:55]
	v_mfma_f32_16x16x32_bf16 v[48:51], v[146:149], v[160:163], v[40:43]
	v_mfma_f32_16x16x32_bf16 v[40:43], v[168:171], v[190:193], v[232:235]
	v_mfma_f32_16x16x32_bf16 v[52:55], v[178:181], v[160:163], v[40:43]
	v_mfma_f32_16x16x32_bf16 v[40:43], v[32:35], v[194:197], v[44:47]
	v_mfma_f32_16x16x32_bf16 v[44:47], v[168:171], v[194:197], v[236:239]
	v_mfma_f32_16x16x32_bf16 v[32:35], v[32:35], v[220:223], v[36:39]
	v_mfma_f32_16x16x32_bf16 v[36:39], v[168:171], v[220:223], v[142:145]
	v_mfma_f32_16x16x32_bf16 v[40:43], v[146:149], v[198:201], v[40:43]
	v_mfma_f32_16x16x32_bf16 v[44:47], v[178:181], v[198:201], v[44:47]
	v_mfma_f32_16x16x32_bf16 v[32:35], v[146:149], v[224:227], v[32:35]
	v_mfma_f32_16x16x32_bf16 v[36:39], v[178:181], v[224:227], v[36:39]
	s_setprio 0
	s_setprio 1
	v_mfma_f32_16x16x32_bf16 v[28:31], v[138:141], v[182:185], v[28:31]
	v_mfma_f32_16x16x32_bf16 v[24:27], v[206:209], v[182:185], v[24:27]
	v_mfma_f32_16x16x32_bf16 v[20:23], v[138:141], v[190:193], v[20:23]
	v_mfma_f32_16x16x32_bf16 v[16:19], v[206:209], v[190:193], v[16:19]
	v_mfma_f32_16x16x32_bf16 v[12:15], v[138:141], v[194:197], v[12:15]
	v_mfma_f32_16x16x32_bf16 v[8:11], v[206:209], v[194:197], v[8:11]
	v_mfma_f32_16x16x32_bf16 v[4:7], v[138:141], v[220:223], v[4:7]
	v_mfma_f32_16x16x32_bf16 v[0:3], v[206:209], v[220:223], v[0:3]
	v_mfma_f32_16x16x32_bf16 v[28:31], v[202:205], v[186:189], v[28:31]
	v_mfma_f32_16x16x32_bf16 v[24:27], v[210:213], v[186:189], v[24:27]
	v_mfma_f32_16x16x32_bf16 v[20:23], v[202:205], v[160:163], v[20:23]
	v_mfma_f32_16x16x32_bf16 v[16:19], v[210:213], v[160:163], v[16:19]
	v_mfma_f32_16x16x32_bf16 v[12:15], v[202:205], v[198:201], v[12:15]
	v_mfma_f32_16x16x32_bf16 v[8:11], v[210:213], v[198:201], v[8:11]
	v_mfma_f32_16x16x32_bf16 v[4:7], v[202:205], v[224:227], v[4:7]
	v_mfma_f32_16x16x32_bf16 v[0:3], v[210:213], v[224:227], v[0:3]
	s_setprio 0
	s_and_b64 vcc, exec, s[66:67]
	s_barrier
	s_cbranch_vccnz .LBB0_193
	s_mul_hi_i32 s0, s82, 0x66666667
	s_lshr_b32 s1, s0, 31
	s_ashr_i32 s0, s0, 1
	s_add_i32 s0, s0, s1
	v_readlane_b32 s1, v255, 15
	s_add_i32 s1, s0, s1
	s_mul_i32 s0, s0, 5
	s_sub_i32 s0, s82, s0
	v_readlane_b32 s2, v255, 14
	s_add_i32 s2, s0, s2
	s_lshl_b32 s8, s2, 8
	s_ashr_i32 s9, s8, 31
	s_lshl_b32 s0, s1, 8
	s_lshl_b64 s[40:41], s[8:9], 11
	s_add_u32 s40, s20, s40
	s_addc_u32 s41, s21, s41
	v_lshl_add_u64 v[138:139], s[40:41], 0, v[130:131]
	v_readfirstlane_b32 s1, v153
	v_lshl_add_u64 v[138:139], v[138:139], 0, v[132:133]
	s_mov_b32 m0, s1
	v_readfirstlane_b32 s1, v173
	global_load_lds_dwordx4 v[138:139], off
	s_mov_b32 m0, s1
	s_ashr_i32 s1, s0, 31
	v_lshl_add_u64 v[138:139], s[40:41], 0, v[134:135]
	s_lshl_b64 s[40:41], s[0:1], 11
	s_add_u32 s40, s45, s40
	v_lshl_add_u64 v[138:139], v[138:139], 0, v[136:137]
	s_addc_u32 s41, s46, s41
	s_bitset1_b32 s8, 7
	global_load_lds_dwordx4 v[138:139], off
	v_lshl_add_u64 v[138:139], s[40:41], 0, v[130:131]
	v_readfirstlane_b32 s1, v152
	s_ashr_i32 s9, s8, 31
	v_lshl_add_u64 v[138:139], v[138:139], 0, v[132:133]
	s_mov_b32 m0, s1
	s_lshl_b64 s[8:9], s[8:9], 11
	global_load_lds_dwordx4 v[138:139], off
	v_lshl_add_u64 v[138:139], s[40:41], 0, v[134:135]
	v_readfirstlane_b32 s1, v174
	s_add_u32 s8, s20, s8
	v_lshl_add_u64 v[138:139], v[138:139], 0, v[136:137]
	s_mov_b32 m0, s1
	s_addc_u32 s9, s21, s9
	global_load_lds_dwordx4 v[138:139], off
	v_lshl_add_u64 v[138:139], s[8:9], 0, v[130:131]
	v_readfirstlane_b32 s1, v151
	v_lshl_add_u64 v[138:139], v[138:139], 0, v[132:133]
	s_mov_b32 m0, s1
	v_readfirstlane_b32 s1, v175
	s_bitset1_b32 s0, 7
	global_load_lds_dwordx4 v[138:139], off
	s_mov_b32 m0, s1
	s_ashr_i32 s1, s0, 31
	s_lshl_b64 s[0:1], s[0:1], 11
	s_add_u32 s0, s45, s0
	v_lshl_add_u64 v[138:139], s[8:9], 0, v[134:135]
	s_addc_u32 s1, s46, s1
	v_lshl_add_u64 v[138:139], v[138:139], 0, v[136:137]
	v_lshl_add_u64 v[130:131], s[0:1], 0, v[130:131]
	v_readfirstlane_b32 s2, v176
	global_load_lds_dwordx4 v[138:139], off
	v_lshl_add_u64 v[130:131], v[130:131], 0, v[132:133]
	s_mov_b32 m0, s2
	s_nop 0
	global_load_lds_dwordx4 v[130:131], off
	v_lshl_add_u64 v[130:131], s[0:1], 0, v[134:135]
	v_readfirstlane_b32 s0, v177
	v_lshl_add_u64 v[130:131], v[130:131], 0, v[136:137]
	s_mov_b32 m0, s0
	s_nop 0
	global_load_lds_dwordx4 v[130:131], off

.LBB0_1529:
	ds_read_b128 v[182:185], v180
	ds_read_b128 v[186:189], v180 offset:1024
	ds_read_b128 v[190:193], v180 offset:2048
	ds_read_b128 v[194:197], v180 offset:3072
	v_add_u32_e32 v0, 0xc000, v162
	v_lshl_add_u64 v[246:247], v[142:143], 0, s[60:61]
	v_readfirstlane_b32 s1, v0
	v_lshl_add_u64 v[2:3], v[246:247], 0, s[18:19]
	s_mov_b32 m0, s1
	ds_read_b128 v[198:201], v161
	ds_read_b128 v[202:205], v161 offset:1024
	ds_read_b128 v[206:209], v160
	ds_read_b128 v[210:213], v160 offset:1024
	ds_read_b128 v[214:217], v159
	ds_read_b128 v[218:221], v159 offset:1024
	ds_read_b128 v[222:225], v158
	ds_read_b128 v[226:229], v158 offset:1024
	global_load_lds_dwordx4 v[2:3], off
	v_add_u32_e32 v2, 0xe000, v162
	v_lshl_add_u64 v[248:249], v[144:145], 0, s[60:61]
	v_readfirstlane_b32 s1, v2
	v_lshl_add_u64 v[230:231], v[248:249], 0, s[18:19]
	s_mov_b32 m0, s1
	s_nop 0
	global_load_lds_dwordx4 v[230:231], off
	s_waitcnt vmcnt(10)
	s_waitcnt lgkmcnt(8)
	s_barrier
	s_waitcnt lgkmcnt(0)
	s_setprio 1
	s_waitcnt lgkmcnt(0)
	v_mfma_f32_16x16x32_bf16 v[128:131], v[182:185], v[198:201], v[128:131]
	v_mfma_f32_16x16x32_bf16 v[124:127], v[190:193], v[198:201], v[124:127]
	v_mfma_f32_16x16x32_bf16 v[120:123], v[182:185], v[206:209], v[120:123]
	v_mfma_f32_16x16x32_bf16 v[116:119], v[190:193], v[206:209], v[116:119]
	v_mfma_f32_16x16x32_bf16 v[112:115], v[182:185], v[214:217], v[112:115]
	v_mfma_f32_16x16x32_bf16 v[108:111], v[190:193], v[214:217], v[108:111]
	v_mfma_f32_16x16x32_bf16 v[104:107], v[182:185], v[222:225], v[104:107]
	v_mfma_f32_16x16x32_bf16 v[100:103], v[190:193], v[222:225], v[100:103]
	v_mfma_f32_16x16x32_bf16 v[128:131], v[186:189], v[202:205], v[128:131]
	v_mfma_f32_16x16x32_bf16 v[124:127], v[194:197], v[202:205], v[124:127]
	v_mfma_f32_16x16x32_bf16 v[120:123], v[186:189], v[210:213], v[120:123]
	v_mfma_f32_16x16x32_bf16 v[116:119], v[194:197], v[210:213], v[116:119]
	v_mfma_f32_16x16x32_bf16 v[112:115], v[186:189], v[218:221], v[112:115]
	v_mfma_f32_16x16x32_bf16 v[108:111], v[194:197], v[218:221], v[108:111]
	v_mfma_f32_16x16x32_bf16 v[104:107], v[186:189], v[226:229], v[104:107]
	v_mfma_f32_16x16x32_bf16 v[100:103], v[194:197], v[226:229], v[100:103]
	s_setprio 0
	s_barrier
	v_lshl_add_u64 v[250:251], v[138:139], 0, s[60:61]
	v_readfirstlane_b32 s1, v147
	v_lshl_add_u64 v[252:253], v[250:251], 0, s[20:21]
	s_mov_b32 m0, s1
	v_add_u32_e32 v3, 0x2000, v147
	ds_read_b128 v[230:233], v178
	ds_read_b128 v[234:237], v178 offset:1024
	ds_read_b128 v[238:241], v178 offset:2048
	ds_read_b128 v[242:245], v178 offset:3072
	global_load_lds_dwordx4 v[252:253], off
	v_lshl_add_u64 v[252:253], v[140:141], 0, s[60:61]
	v_readfirstlane_b32 s1, v3
	v_lshl_add_u64 v[132:133], v[252:253], 0, s[20:21]
	s_mov_b32 m0, s1
	s_add_i32 s1, s0, 2
	global_load_lds_dwordx4 v[132:133], off
	s_waitcnt vmcnt(10)
	s_barrier
	s_waitcnt lgkmcnt(0)
	s_setprio 1
	s_waitcnt lgkmcnt(0)
	v_mfma_f32_16x16x32_bf16 v[96:99], v[230:233], v[198:201], v[96:99]
	v_mfma_f32_16x16x32_bf16 v[92:95], v[238:241], v[198:201], v[92:95]
	v_mfma_f32_16x16x32_bf16 v[88:91], v[230:233], v[206:209], v[88:91]
	v_mfma_f32_16x16x32_bf16 v[84:87], v[238:241], v[206:209], v[84:87]
	v_mfma_f32_16x16x32_bf16 v[80:83], v[230:233], v[214:217], v[80:83]
	v_mfma_f32_16x16x32_bf16 v[76:79], v[238:241], v[214:217], v[76:79]
	v_mfma_f32_16x16x32_bf16 v[72:75], v[230:233], v[222:225], v[72:75]
	v_mfma_f32_16x16x32_bf16 v[68:71], v[238:241], v[222:225], v[68:71]
	v_mfma_f32_16x16x32_bf16 v[96:99], v[234:237], v[202:205], v[96:99]
	v_mfma_f32_16x16x32_bf16 v[92:95], v[242:245], v[202:205], v[92:95]
	v_mfma_f32_16x16x32_bf16 v[88:91], v[234:237], v[210:213], v[88:91]
	v_mfma_f32_16x16x32_bf16 v[84:87], v[242:245], v[210:213], v[84:87]
	v_mfma_f32_16x16x32_bf16 v[80:83], v[234:237], v[218:221], v[80:83]
	v_mfma_f32_16x16x32_bf16 v[76:79], v[242:245], v[218:221], v[76:79]
	v_mfma_f32_16x16x32_bf16 v[72:75], v[234:237], v[226:229], v[72:75]
	v_mfma_f32_16x16x32_bf16 v[68:71], v[242:245], v[226:229], v[68:71]
	s_setprio 0
	v_readfirstlane_b32 s2, v162
	v_lshl_add_u64 v[132:133], v[246:247], 0, s[24:25]
	s_mov_b32 m0, s2
	v_readfirstlane_b32 s2, v163
	s_barrier
	ds_read_b128 v[198:201], v161 offset:16384
	ds_read_b128 v[202:205], v161 offset:17408
	ds_read_b128 v[206:209], v160 offset:16384
	ds_read_b128 v[210:213], v160 offset:17408
	ds_read_b128 v[214:217], v159 offset:16384
	ds_read_b128 v[218:221], v159 offset:17408
	ds_read_b128 v[222:225], v158 offset:16384
	ds_read_b128 v[226:229], v158 offset:17408
	global_load_lds_dwordx4 v[132:133], off
	v_lshl_add_u64 v[132:133], v[248:249], 0, s[24:25]
	s_mov_b32 m0, s2
	s_nop 0
	global_load_lds_dwordx4 v[132:133], off
	s_barrier
	s_waitcnt lgkmcnt(0)
	s_setprio 1
	s_waitcnt lgkmcnt(0)
	v_mfma_f32_16x16x32_bf16 v[64:67], v[182:185], v[198:201], v[64:67]
	v_mfma_f32_16x16x32_bf16 v[60:63], v[190:193], v[198:201], v[60:63]
	v_mfma_f32_16x16x32_bf16 v[56:59], v[182:185], v[206:209], v[56:59]
	v_mfma_f32_16x16x32_bf16 v[52:55], v[190:193], v[206:209], v[52:55]
	v_mfma_f32_16x16x32_bf16 v[48:51], v[182:185], v[214:217], v[48:51]
	v_mfma_f32_16x16x32_bf16 v[44:47], v[190:193], v[214:217], v[44:47]
	v_mfma_f32_16x16x32_bf16 v[40:43], v[182:185], v[222:225], v[40:43]
	v_mfma_f32_16x16x32_bf16 v[36:39], v[190:193], v[222:225], v[36:39]
	v_mfma_f32_16x16x32_bf16 v[64:67], v[186:189], v[202:205], v[64:67]
	v_mfma_f32_16x16x32_bf16 v[60:63], v[194:197], v[202:205], v[60:63]
	v_mfma_f32_16x16x32_bf16 v[56:59], v[186:189], v[210:213], v[56:59]
	v_mfma_f32_16x16x32_bf16 v[52:55], v[194:197], v[210:213], v[52:55]
	v_mfma_f32_16x16x32_bf16 v[48:51], v[186:189], v[218:221], v[48:51]
	v_mfma_f32_16x16x32_bf16 v[44:47], v[194:197], v[218:221], v[44:47]
	v_mfma_f32_16x16x32_bf16 v[40:43], v[186:189], v[226:229], v[40:43]
	v_mfma_f32_16x16x32_bf16 v[36:39], v[194:197], v[226:229], v[36:39]
	s_setprio 0
	s_barrier
	v_readfirstlane_b32 s2, v168
	v_add_u32_e32 v3, 0x2000, v168
	v_lshl_add_u64 v[132:133], v[250:251], 0, s[26:27]
	s_mov_b32 m0, s2
	v_readfirstlane_b32 s2, v3
	global_load_lds_dwordx4 v[132:133], off
	v_lshl_add_u64 v[132:133], v[252:253], 0, s[26:27]
	s_mov_b32 m0, s2
	s_nop 0
	global_load_lds_dwordx4 v[132:133], off
	s_waitcnt vmcnt(10)
	s_barrier
	s_setprio 1
	v_mfma_f32_16x16x32_bf16 v[32:35], v[230:233], v[198:201], v[32:35]
	v_mfma_f32_16x16x32_bf16 v[28:31], v[238:241], v[198:201], v[28:31]
	v_mfma_f32_16x16x32_bf16 v[24:27], v[230:233], v[206:209], v[24:27]
	v_mfma_f32_16x16x32_bf16 v[20:23], v[238:241], v[206:209], v[20:23]
	v_mfma_f32_16x16x32_bf16 v[16:19], v[230:233], v[214:217], v[16:19]
	v_mfma_f32_16x16x32_bf16 v[12:15], v[238:241], v[214:217], v[12:15]
	v_mfma_f32_16x16x32_bf16 v[8:11], v[230:233], v[222:225], v[8:11]
	v_mfma_f32_16x16x32_bf16 v[4:7], v[238:241], v[222:225], v[4:7]
	v_mfma_f32_16x16x32_bf16 v[32:35], v[234:237], v[202:205], v[32:35]
	v_mfma_f32_16x16x32_bf16 v[28:31], v[242:245], v[202:205], v[28:31]
	v_mfma_f32_16x16x32_bf16 v[24:27], v[234:237], v[210:213], v[24:27]
	v_mfma_f32_16x16x32_bf16 v[20:23], v[242:245], v[210:213], v[20:23]
	v_mfma_f32_16x16x32_bf16 v[16:19], v[234:237], v[218:221], v[16:19]
	v_mfma_f32_16x16x32_bf16 v[12:15], v[242:245], v[218:221], v[12:15]
	v_mfma_f32_16x16x32_bf16 v[8:11], v[234:237], v[226:229], v[8:11]
	v_mfma_f32_16x16x32_bf16 v[4:7], v[242:245], v[226:229], v[4:7]
	s_setprio 0
	s_barrier
	ds_read_b128 v[182:185], v170
	ds_read_b128 v[186:189], v170 offset:1024
	ds_read_b128 v[190:193], v170 offset:2048
	ds_read_b128 v[194:197], v170 offset:3072
	v_readfirstlane_b32 s2, v169
	v_lshl_add_u64 v[132:133], v[246:247], 0, s[28:29]
	s_mov_b32 m0, s2
	v_readfirstlane_b32 s2, v171
	ds_read_b128 v[198:201], v161 offset:32768
	ds_read_b128 v[202:205], v161 offset:33792
	ds_read_b128 v[206:209], v160 offset:32768
	ds_read_b128 v[210:213], v160 offset:33792
	ds_read_b128 v[214:217], v159 offset:32768
	ds_read_b128 v[218:221], v159 offset:33792
	ds_read_b128 v[222:225], v158 offset:32768
	ds_read_b128 v[226:229], v158 offset:33792
	global_load_lds_dwordx4 v[132:133], off
	v_lshl_add_u64 v[132:133], v[248:249], 0, s[28:29]
	s_mov_b32 m0, s2
	s_nop 0
	global_load_lds_dwordx4 v[132:133], off
	s_waitcnt vmcnt(10)
	s_waitcnt lgkmcnt(8)
	s_barrier
	s_waitcnt lgkmcnt(0)
	s_setprio 1
	s_waitcnt lgkmcnt(0)
	v_mfma_f32_16x16x32_bf16 v[128:131], v[182:185], v[198:201], v[128:131]
	v_mfma_f32_16x16x32_bf16 v[124:127], v[190:193], v[198:201], v[124:127]
	v_mfma_f32_16x16x32_bf16 v[120:123], v[182:185], v[206:209], v[120:123]
	v_mfma_f32_16x16x32_bf16 v[116:119], v[190:193], v[206:209], v[116:119]
	v_mfma_f32_16x16x32_bf16 v[112:115], v[182:185], v[214:217], v[112:115]
	v_mfma_f32_16x16x32_bf16 v[108:111], v[190:193], v[214:217], v[108:111]
	v_mfma_f32_16x16x32_bf16 v[104:107], v[182:185], v[222:225], v[104:107]
	v_mfma_f32_16x16x32_bf16 v[100:103], v[190:193], v[222:225], v[100:103]
	v_mfma_f32_16x16x32_bf16 v[128:131], v[186:189], v[202:205], v[128:131]
	v_mfma_f32_16x16x32_bf16 v[124:127], v[194:197], v[202:205], v[124:127]
	v_mfma_f32_16x16x32_bf16 v[120:123], v[186:189], v[210:213], v[120:123]
	v_mfma_f32_16x16x32_bf16 v[116:119], v[194:197], v[210:213], v[116:119]
	v_mfma_f32_16x16x32_bf16 v[112:115], v[186:189], v[218:221], v[112:115]
	v_mfma_f32_16x16x32_bf16 v[108:111], v[194:197], v[218:221], v[108:111]
	v_mfma_f32_16x16x32_bf16 v[104:107], v[186:189], v[226:229], v[104:107]
	v_mfma_f32_16x16x32_bf16 v[100:103], v[194:197], v[226:229], v[100:103]
	s_setprio 0
	s_barrier
	v_readfirstlane_b32 s2, v172
	v_lshl_add_u64 v[132:133], v[250:251], 0, s[30:31]
	s_mov_b32 m0, s2
	v_readfirstlane_b32 s2, v173
	ds_read_b128 v[230:233], v167
	ds_read_b128 v[234:237], v167 offset:1024
	ds_read_b128 v[238:241], v167 offset:2048
	ds_read_b128 v[242:245], v167 offset:3072
	global_load_lds_dwordx4 v[132:133], off
	v_lshl_add_u64 v[132:133], v[252:253], 0, s[30:31]
	s_mov_b32 m0, s2
	s_nop 0
	global_load_lds_dwordx4 v[132:133], off
	s_waitcnt vmcnt(10)
	s_barrier
	s_waitcnt lgkmcnt(0)
	s_setprio 1
	s_waitcnt lgkmcnt(0)
	v_mfma_f32_16x16x32_bf16 v[96:99], v[230:233], v[198:201], v[96:99]
	v_mfma_f32_16x16x32_bf16 v[92:95], v[238:241], v[198:201], v[92:95]
	v_mfma_f32_16x16x32_bf16 v[88:91], v[230:233], v[206:209], v[88:91]
	v_mfma_f32_16x16x32_bf16 v[84:87], v[238:241], v[206:209], v[84:87]
	v_mfma_f32_16x16x32_bf16 v[80:83], v[230:233], v[214:217], v[80:83]
	v_mfma_f32_16x16x32_bf16 v[76:79], v[238:241], v[214:217], v[76:79]
	v_mfma_f32_16x16x32_bf16 v[72:75], v[230:233], v[222:225], v[72:75]
	v_mfma_f32_16x16x32_bf16 v[68:71], v[238:241], v[222:225], v[68:71]
	v_mfma_f32_16x16x32_bf16 v[96:99], v[234:237], v[202:205], v[96:99]
	v_mfma_f32_16x16x32_bf16 v[92:95], v[242:245], v[202:205], v[92:95]
	v_mfma_f32_16x16x32_bf16 v[88:91], v[234:237], v[210:213], v[88:91]
	v_mfma_f32_16x16x32_bf16 v[84:87], v[242:245], v[210:213], v[84:87]
	v_mfma_f32_16x16x32_bf16 v[80:83], v[234:237], v[218:221], v[80:83]
	v_mfma_f32_16x16x32_bf16 v[76:79], v[242:245], v[218:221], v[76:79]
	v_mfma_f32_16x16x32_bf16 v[72:75], v[234:237], v[226:229], v[72:75]
	v_mfma_f32_16x16x32_bf16 v[68:71], v[242:245], v[226:229], v[68:71]
	s_setprio 0
	v_readfirstlane_b32 s2, v174
	v_lshl_add_u64 v[132:133], v[246:247], 0, s[34:35]
	s_mov_b32 m0, s2
	v_readfirstlane_b32 s2, v175
	s_barrier
	ds_read_b128 v[198:201], v161 offset:49152
	ds_read_b128 v[202:205], v161 offset:50176
	ds_read_b128 v[206:209], v160 offset:49152
	ds_read_b128 v[210:213], v160 offset:50176
	ds_read_b128 v[214:217], v159 offset:49152
	ds_read_b128 v[218:221], v159 offset:50176
	ds_read_b128 v[222:225], v158 offset:49152
	ds_read_b128 v[226:229], v158 offset:50176
	global_load_lds_dwordx4 v[132:133], off
	v_lshl_add_u64 v[132:133], v[248:249], 0, s[34:35]
	s_mov_b32 m0, s2
	s_nop 0
	global_load_lds_dwordx4 v[132:133], off
	s_barrier
	s_waitcnt lgkmcnt(0)
	s_setprio 1
	s_waitcnt lgkmcnt(0)
	v_mfma_f32_16x16x32_bf16 v[64:67], v[182:185], v[198:201], v[64:67]
	v_mfma_f32_16x16x32_bf16 v[60:63], v[190:193], v[198:201], v[60:63]
	v_mfma_f32_16x16x32_bf16 v[56:59], v[182:185], v[206:209], v[56:59]
	v_mfma_f32_16x16x32_bf16 v[52:55], v[190:193], v[206:209], v[52:55]
	v_mfma_f32_16x16x32_bf16 v[48:51], v[182:185], v[214:217], v[48:51]
	v_mfma_f32_16x16x32_bf16 v[44:47], v[190:193], v[214:217], v[44:47]
	v_mfma_f32_16x16x32_bf16 v[40:43], v[182:185], v[222:225], v[40:43]
	v_mfma_f32_16x16x32_bf16 v[36:39], v[190:193], v[222:225], v[36:39]
	v_mfma_f32_16x16x32_bf16 v[64:67], v[186:189], v[202:205], v[64:67]
	v_mfma_f32_16x16x32_bf16 v[60:63], v[194:197], v[202:205], v[60:63]
	v_mfma_f32_16x16x32_bf16 v[56:59], v[186:189], v[210:213], v[56:59]
	v_mfma_f32_16x16x32_bf16 v[52:55], v[194:197], v[210:213], v[52:55]
	v_mfma_f32_16x16x32_bf16 v[48:51], v[186:189], v[218:221], v[48:51]
	v_mfma_f32_16x16x32_bf16 v[44:47], v[194:197], v[218:221], v[44:47]
	v_mfma_f32_16x16x32_bf16 v[40:43], v[186:189], v[226:229], v[40:43]
	v_mfma_f32_16x16x32_bf16 v[36:39], v[194:197], v[226:229], v[36:39]
	s_setprio 0
	s_barrier
	v_readfirstlane_b32 s2, v176
	v_lshl_add_u64 v[132:133], v[250:251], 0, s[36:37]
	s_mov_b32 m0, s2
	v_readfirstlane_b32 s2, v177
	global_load_lds_dwordx4 v[132:133], off
	v_lshl_add_u64 v[132:133], v[252:253], 0, s[36:37]
	s_mov_b32 m0, s2
	s_nop 0
	global_load_lds_dwordx4 v[132:133], off
	s_waitcnt vmcnt(10)
	s_barrier
	s_setprio 1
	v_mfma_f32_16x16x32_bf16 v[32:35], v[230:233], v[198:201], v[32:35]
	v_mfma_f32_16x16x32_bf16 v[28:31], v[238:241], v[198:201], v[28:31]
	v_mfma_f32_16x16x32_bf16 v[24:27], v[230:233], v[206:209], v[24:27]
	v_mfma_f32_16x16x32_bf16 v[20:23], v[238:241], v[206:209], v[20:23]
	v_mfma_f32_16x16x32_bf16 v[16:19], v[230:233], v[214:217], v[16:19]
	v_mfma_f32_16x16x32_bf16 v[12:15], v[238:241], v[214:217], v[12:15]
	v_mfma_f32_16x16x32_bf16 v[8:11], v[230:233], v[222:225], v[8:11]
	v_mfma_f32_16x16x32_bf16 v[4:7], v[238:241], v[222:225], v[4:7]
	v_mfma_f32_16x16x32_bf16 v[32:35], v[234:237], v[202:205], v[32:35]
	v_mfma_f32_16x16x32_bf16 v[28:31], v[242:245], v[202:205], v[28:31]
	v_mfma_f32_16x16x32_bf16 v[24:27], v[234:237], v[210:213], v[24:27]
	v_mfma_f32_16x16x32_bf16 v[20:23], v[242:245], v[210:213], v[20:23]
	v_mfma_f32_16x16x32_bf16 v[16:19], v[234:237], v[218:221], v[16:19]
	v_mfma_f32_16x16x32_bf16 v[12:15], v[242:245], v[218:221], v[12:15]
	v_mfma_f32_16x16x32_bf16 v[8:11], v[234:237], v[226:229], v[8:11]
	v_mfma_f32_16x16x32_bf16 v[4:7], v[242:245], v[226:229], v[4:7]
	s_setprio 0
	s_add_u32 s60, s60, 0x100
	s_addc_u32 s61, s61, 0
	s_cmp_gt_u32 s0, 11
	s_barrier
	s_cbranch_scc1 .LBB0_1532
	s_mov_b32 s0, s1
	s_cmp_lt_i32 s0, 12
	s_cbranch_scc1 .LBB0_1493

.LBB0_1532:
	v_readfirstlane_b32 s0, v0
	v_lshl_add_u64 v[134:135], v[134:135], 0, s[56:57]
	s_mov_b32 m0, s0
	v_readfirstlane_b32 s0, v2
	ds_read_b128 v[138:141], v180
	ds_read_b128 v[142:145], v180 offset:1024
	ds_read_b128 v[172:175], v180 offset:2048
	ds_read_b128 v[180:183], v180 offset:3072
	ds_read_b128 v[184:187], v161
	ds_read_b128 v[188:191], v161 offset:1024
	ds_read_b128 v[192:195], v160
	ds_read_b128 v[196:199], v160 offset:1024
	ds_read_b128 v[200:203], v159
	ds_read_b128 v[204:207], v159 offset:1024
	ds_read_b128 v[208:211], v158
	ds_read_b128 v[212:215], v158 offset:1024
	global_load_lds_dwordx4 v[134:135], off
	v_lshl_add_u64 v[134:135], v[136:137], 0, s[56:57]
	s_mov_b32 m0, s0
	s_nop 0
	global_load_lds_dwordx4 v[134:135], off
	s_waitcnt vmcnt(10)
	s_barrier
	s_waitcnt lgkmcnt(0)
	s_setprio 1
	s_waitcnt lgkmcnt(0)
	v_mfma_f32_16x16x32_bf16 v[128:131], v[138:141], v[184:187], v[128:131]
	v_mfma_f32_16x16x32_bf16 v[124:127], v[172:175], v[184:187], v[124:127]
	v_mfma_f32_16x16x32_bf16 v[120:123], v[138:141], v[192:195], v[120:123]
	v_mfma_f32_16x16x32_bf16 v[116:119], v[172:175], v[192:195], v[116:119]
	v_mfma_f32_16x16x32_bf16 v[112:115], v[138:141], v[200:203], v[112:115]
	v_mfma_f32_16x16x32_bf16 v[108:111], v[172:175], v[200:203], v[108:111]
	v_mfma_f32_16x16x32_bf16 v[104:107], v[138:141], v[208:211], v[104:107]
	v_mfma_f32_16x16x32_bf16 v[100:103], v[172:175], v[208:211], v[100:103]
	v_mfma_f32_16x16x32_bf16 v[128:131], v[142:145], v[188:191], v[128:131]
	v_mfma_f32_16x16x32_bf16 v[124:127], v[180:183], v[188:191], v[124:127]
	v_mfma_f32_16x16x32_bf16 v[120:123], v[142:145], v[196:199], v[120:123]
	v_mfma_f32_16x16x32_bf16 v[116:119], v[180:183], v[196:199], v[116:119]
	v_mfma_f32_16x16x32_bf16 v[112:115], v[142:145], v[204:207], v[112:115]
	v_mfma_f32_16x16x32_bf16 v[108:111], v[180:183], v[204:207], v[108:111]
	v_mfma_f32_16x16x32_bf16 v[104:107], v[142:145], v[212:215], v[104:107]
	v_mfma_f32_16x16x32_bf16 v[100:103], v[180:183], v[212:215], v[100:103]
	s_setprio 0
	s_barrier
	ds_read_b128 v[134:137], v178
	ds_read_b128 v[216:219], v178 offset:1024
	ds_read_b128 v[220:223], v178 offset:2048
	ds_read_b128 v[176:179], v178 offset:3072
	s_waitcnt vmcnt(8)
	s_barrier
	s_waitcnt lgkmcnt(0)
	s_setprio 1
	s_waitcnt lgkmcnt(0)
	v_mfma_f32_16x16x32_bf16 v[96:99], v[134:137], v[184:187], v[96:99]
	v_mfma_f32_16x16x32_bf16 v[92:95], v[220:223], v[184:187], v[92:95]
	v_mfma_f32_16x16x32_bf16 v[88:91], v[134:137], v[192:195], v[88:91]
	v_mfma_f32_16x16x32_bf16 v[84:87], v[220:223], v[192:195], v[84:87]
	v_mfma_f32_16x16x32_bf16 v[80:83], v[134:137], v[200:203], v[80:83]
	v_mfma_f32_16x16x32_bf16 v[76:79], v[220:223], v[200:203], v[76:79]
	v_mfma_f32_16x16x32_bf16 v[72:75], v[134:137], v[208:211], v[72:75]
	v_mfma_f32_16x16x32_bf16 v[68:71], v[220:223], v[208:211], v[68:71]
	v_mfma_f32_16x16x32_bf16 v[96:99], v[216:219], v[188:191], v[96:99]
	v_mfma_f32_16x16x32_bf16 v[92:95], v[176:179], v[188:191], v[92:95]
	v_mfma_f32_16x16x32_bf16 v[88:91], v[216:219], v[196:199], v[88:91]
	v_mfma_f32_16x16x32_bf16 v[84:87], v[176:179], v[196:199], v[84:87]
	v_mfma_f32_16x16x32_bf16 v[80:83], v[216:219], v[204:207], v[80:83]
	v_mfma_f32_16x16x32_bf16 v[76:79], v[176:179], v[204:207], v[76:79]
	v_mfma_f32_16x16x32_bf16 v[72:75], v[216:219], v[212:215], v[72:75]
	v_mfma_f32_16x16x32_bf16 v[68:71], v[176:179], v[212:215], v[68:71]
	s_setprio 0
	s_barrier
	ds_read_b128 v[184:187], v161 offset:16384
	ds_read_b128 v[188:191], v161 offset:17408
	ds_read_b128 v[192:195], v160 offset:16384
	ds_read_b128 v[196:199], v160 offset:17408
	ds_read_b128 v[200:203], v159 offset:16384
	ds_read_b128 v[204:207], v159 offset:17408
	ds_read_b128 v[208:211], v158 offset:16384
	ds_read_b128 v[212:215], v158 offset:17408
	s_waitcnt vmcnt(4)
	s_barrier
	s_waitcnt lgkmcnt(0)
	s_setprio 1
	s_waitcnt lgkmcnt(0)
	v_mfma_f32_16x16x32_bf16 v[64:67], v[138:141], v[184:187], v[64:67]
	v_mfma_f32_16x16x32_bf16 v[56:59], v[138:141], v[192:195], v[56:59]
	v_mfma_f32_16x16x32_bf16 v[48:51], v[138:141], v[200:203], v[48:51]
	v_mfma_f32_16x16x32_bf16 v[40:43], v[138:141], v[208:211], v[40:43]
	v_mfma_f32_16x16x32_bf16 v[36:39], v[172:175], v[208:211], v[36:39]
	v_mfma_f32_16x16x32_bf16 v[224:227], v[142:145], v[188:191], v[64:67]
	v_mfma_f32_16x16x32_bf16 v[60:63], v[172:175], v[184:187], v[60:63]
	v_mfma_f32_16x16x32_bf16 v[232:235], v[142:145], v[196:199], v[56:59]
	v_mfma_f32_16x16x32_bf16 v[52:55], v[172:175], v[192:195], v[52:55]
	v_mfma_f32_16x16x32_bf16 v[240:243], v[142:145], v[204:207], v[48:51]
	v_mfma_f32_16x16x32_bf16 v[44:47], v[172:175], v[200:203], v[44:47]
	v_mfma_f32_16x16x32_bf16 v[138:141], v[142:145], v[212:215], v[40:43]
	v_mfma_f32_16x16x32_bf16 v[142:145], v[180:183], v[212:215], v[36:39]
	v_mfma_f32_16x16x32_bf16 v[228:231], v[180:183], v[188:191], v[60:63]
	v_mfma_f32_16x16x32_bf16 v[236:239], v[180:183], v[196:199], v[52:55]
	v_mfma_f32_16x16x32_bf16 v[244:247], v[180:183], v[204:207], v[44:47]
	s_setprio 0
	s_setprio 1
	v_mfma_f32_16x16x32_bf16 v[8:11], v[134:137], v[208:211], v[8:11]
	v_mfma_f32_16x16x32_bf16 v[32:35], v[134:137], v[184:187], v[32:35]
	v_mfma_f32_16x16x32_bf16 v[28:31], v[220:223], v[184:187], v[28:31]
	v_mfma_f32_16x16x32_bf16 v[24:27], v[134:137], v[192:195], v[24:27]
	v_mfma_f32_16x16x32_bf16 v[20:23], v[220:223], v[192:195], v[20:23]
	v_mfma_f32_16x16x32_bf16 v[16:19], v[134:137], v[200:203], v[16:19]
	v_mfma_f32_16x16x32_bf16 v[12:15], v[220:223], v[200:203], v[12:15]
	v_mfma_f32_16x16x32_bf16 v[134:137], v[216:219], v[212:215], v[8:11]
	v_mfma_f32_16x16x32_bf16 v[2:5], v[220:223], v[208:211], v[4:7]
	v_mfma_f32_16x16x32_bf16 v[172:175], v[216:219], v[188:191], v[32:35]
	v_mfma_f32_16x16x32_bf16 v[180:183], v[176:179], v[188:191], v[28:31]
	v_mfma_f32_16x16x32_bf16 v[184:187], v[216:219], v[196:199], v[24:27]
	v_mfma_f32_16x16x32_bf16 v[188:191], v[176:179], v[196:199], v[20:23]
	v_mfma_f32_16x16x32_bf16 v[192:195], v[216:219], v[204:207], v[16:19]
	v_mfma_f32_16x16x32_bf16 v[196:199], v[176:179], v[204:207], v[12:15]
	v_mfma_f32_16x16x32_bf16 v[176:179], v[176:179], v[212:215], v[2:5]
	s_setprio 0
	s_barrier
	ds_read_b128 v[200:203], v170
	ds_read_b128 v[204:207], v170 offset:1024
	ds_read_b128 v[208:211], v170 offset:2048
	ds_read_b128 v[168:171], v170 offset:3072
	ds_read_b128 v[22:25], v161 offset:32768
	ds_read_b128 v[34:37], v161 offset:33792
	ds_read_b128 v[38:41], v160 offset:32768
	ds_read_b128 v[50:53], v160 offset:33792
	ds_read_b128 v[54:57], v159 offset:32768
	ds_read_b128 v[58:61], v159 offset:33792
	ds_read_b128 v[62:65], v158 offset:32768
	ds_read_b128 v[212:215], v158 offset:33792
	s_waitcnt vmcnt(2)
	s_barrier
	s_waitcnt lgkmcnt(0)
	s_setprio 1
	s_waitcnt lgkmcnt(0)
	v_mfma_f32_16x16x32_bf16 v[18:21], v[200:203], v[54:57], v[112:115]
	v_mfma_f32_16x16x32_bf16 v[26:29], v[204:207], v[58:61], v[18:21]
	v_mfma_f32_16x16x32_bf16 v[18:21], v[208:211], v[54:57], v[108:111]
	v_mfma_f32_16x16x32_bf16 v[30:33], v[168:171], v[58:61], v[18:21]
	v_mfma_f32_16x16x32_bf16 v[18:21], v[200:203], v[62:65], v[104:107]
	v_mfma_f32_16x16x32_bf16 v[2:5], v[200:203], v[22:25], v[128:131]
	v_mfma_f32_16x16x32_bf16 v[6:9], v[208:211], v[22:25], v[124:127]
	v_mfma_f32_16x16x32_bf16 v[10:13], v[200:203], v[38:41], v[120:123]
	v_mfma_f32_16x16x32_bf16 v[14:17], v[208:211], v[38:41], v[116:119]
	v_mfma_f32_16x16x32_bf16 v[42:45], v[204:207], v[212:215], v[18:21]
	v_mfma_f32_16x16x32_bf16 v[18:21], v[208:211], v[62:65], v[100:103]
	v_mfma_f32_16x16x32_bf16 v[2:5], v[204:207], v[34:37], v[2:5]
	v_mfma_f32_16x16x32_bf16 v[6:9], v[168:171], v[34:37], v[6:9]
	v_mfma_f32_16x16x32_bf16 v[10:13], v[204:207], v[50:53], v[10:13]
	v_mfma_f32_16x16x32_bf16 v[14:17], v[168:171], v[50:53], v[14:17]
	v_mfma_f32_16x16x32_bf16 v[46:49], v[168:171], v[212:215], v[18:21]
	s_setprio 0
	s_barrier
	ds_read_b128 v[122:125], v167
	ds_read_b128 v[126:129], v167 offset:1024
	ds_read_b128 v[216:219], v167 offset:2048
	ds_read_b128 v[220:223], v167 offset:3072
	s_waitcnt vmcnt(0)
	s_barrier
	s_waitcnt lgkmcnt(0)
	s_setprio 1
	s_waitcnt lgkmcnt(0)
	v_mfma_f32_16x16x32_bf16 v[18:21], v[122:125], v[22:25], v[96:99]
	v_mfma_f32_16x16x32_bf16 v[22:25], v[216:219], v[22:25], v[92:95]
	v_mfma_f32_16x16x32_bf16 v[18:21], v[126:129], v[34:37], v[18:21]
	v_mfma_f32_16x16x32_bf16 v[22:25], v[220:223], v[34:37], v[22:25]
	v_mfma_f32_16x16x32_bf16 v[34:37], v[122:125], v[38:41], v[88:91]
	v_mfma_f32_16x16x32_bf16 v[38:41], v[216:219], v[38:41], v[84:87]
	v_mfma_f32_16x16x32_bf16 v[34:37], v[126:129], v[50:53], v[34:37]
	v_mfma_f32_16x16x32_bf16 v[38:41], v[220:223], v[50:53], v[38:41]
	v_mfma_f32_16x16x32_bf16 v[50:53], v[122:125], v[54:57], v[80:83]
	v_mfma_f32_16x16x32_bf16 v[54:57], v[216:219], v[54:57], v[76:79]
	v_mfma_f32_16x16x32_bf16 v[50:53], v[126:129], v[58:61], v[50:53]
	v_mfma_f32_16x16x32_bf16 v[54:57], v[220:223], v[58:61], v[54:57]
	v_mfma_f32_16x16x32_bf16 v[58:61], v[122:125], v[62:65], v[72:75]
	v_mfma_f32_16x16x32_bf16 v[62:65], v[216:219], v[62:65], v[68:71]
	v_mfma_f32_16x16x32_bf16 v[58:61], v[126:129], v[212:215], v[58:61]
	v_mfma_f32_16x16x32_bf16 v[62:65], v[220:223], v[212:215], v[62:65]
	s_setprio 0
	s_barrier
	ds_read_b128 v[86:89], v161 offset:49152
	ds_read_b128 v[94:97], v161 offset:50176
	ds_read_b128 v[102:105], v160 offset:49152
	ds_read_b128 v[110:113], v160 offset:50176
	ds_read_b128 v[118:121], v159 offset:49152
	ds_read_b128 v[160:163], v159 offset:50176
	ds_read_b128 v[212:215], v158 offset:49152
	ds_read_b128 v[248:251], v158 offset:50176
	s_barrier
	s_waitcnt lgkmcnt(0)
	s_setprio 1
	s_waitcnt lgkmcnt(0)
	v_mfma_f32_16x16x32_bf16 v[78:81], v[208:211], v[102:105], v[236:239]
	v_mfma_f32_16x16x32_bf16 v[82:85], v[168:171], v[110:113], v[78:81]
	v_mfma_f32_16x16x32_bf16 v[78:81], v[200:203], v[118:121], v[240:243]
	v_mfma_f32_16x16x32_bf16 v[90:93], v[204:207], v[160:163], v[78:81]
	v_mfma_f32_16x16x32_bf16 v[78:81], v[208:211], v[118:121], v[244:247]
	v_mfma_f32_16x16x32_bf16 v[98:101], v[168:171], v[160:163], v[78:81]
	v_mfma_f32_16x16x32_bf16 v[78:81], v[200:203], v[212:215], v[138:141]
	v_mfma_f32_16x16x32_bf16 v[66:69], v[200:203], v[86:89], v[224:227]
	v_mfma_f32_16x16x32_bf16 v[70:73], v[208:211], v[86:89], v[228:231]
	v_mfma_f32_16x16x32_bf16 v[74:77], v[200:203], v[102:105], v[232:235]
	v_mfma_f32_16x16x32_bf16 v[106:109], v[204:207], v[248:251], v[78:81]
	v_mfma_f32_16x16x32_bf16 v[78:81], v[208:211], v[212:215], v[142:145]
	v_mfma_f32_16x16x32_bf16 v[66:69], v[204:207], v[94:97], v[66:69]
	v_mfma_f32_16x16x32_bf16 v[70:73], v[168:171], v[94:97], v[70:73]
	v_mfma_f32_16x16x32_bf16 v[74:77], v[204:207], v[110:113], v[74:77]
	v_mfma_f32_16x16x32_bf16 v[114:117], v[168:171], v[248:251], v[78:81]
	s_setprio 0
	s_setprio 1
	v_mfma_f32_16x16x32_bf16 v[78:81], v[122:125], v[86:89], v[172:175]
	v_mfma_f32_16x16x32_bf16 v[86:89], v[216:219], v[86:89], v[180:183]
	v_mfma_f32_16x16x32_bf16 v[78:81], v[126:129], v[94:97], v[78:81]
	v_mfma_f32_16x16x32_bf16 v[86:89], v[220:223], v[94:97], v[86:89]
	v_mfma_f32_16x16x32_bf16 v[94:97], v[122:125], v[102:105], v[184:187]
	v_mfma_f32_16x16x32_bf16 v[102:105], v[216:219], v[102:105], v[188:191]
	v_mfma_f32_16x16x32_bf16 v[94:97], v[126:129], v[110:113], v[94:97]
	v_mfma_f32_16x16x32_bf16 v[102:105], v[220:223], v[110:113], v[102:105]
	v_mfma_f32_16x16x32_bf16 v[110:113], v[122:125], v[118:121], v[192:195]
	v_mfma_f32_16x16x32_bf16 v[122:125], v[122:125], v[212:215], v[134:137]
	v_mfma_f32_16x16x32_bf16 v[110:113], v[126:129], v[160:163], v[110:113]
	v_mfma_f32_16x16x32_bf16 v[118:121], v[216:219], v[118:121], v[196:199]
	v_mfma_f32_16x16x32_bf16 v[122:125], v[126:129], v[248:251], v[122:125]
	v_mfma_f32_16x16x32_bf16 v[126:129], v[216:219], v[212:215], v[176:179]
	v_mfma_f32_16x16x32_bf16 v[118:121], v[220:223], v[160:163], v[118:121]
	v_mfma_f32_16x16x32_bf16 v[126:129], v[220:223], v[248:251], v[126:129]
	s_setprio 0
	v_and_b32_e32 v0, 0xffffff00, v149
	v_lshlrev_b32_e32 v130, 2, v155
	v_add3_u32 v131, s70, v0, v130
	v_add3_u32 v0, s71, v0, v130
	s_barrier
	ds_read2_b32 v[136:137], v131 offset1:16
	ds_read2_b32 v[138:139], v131 offset0:32 offset1:48
	ds_read2_b32 v[142:143], v0 offset1:16
	ds_read2_b32 v[146:147], v0 offset0:32 offset1:48
	v_cmp_gt_u32_e32 vcc, s55, v149
	s_waitcnt lgkmcnt(0)
	v_mov_b32_e32 v0, v137
	v_mov_b32_e32 v140, v139
	v_mov_b32_e32 v144, v143
	v_mov_b32_e32 v134, v147
	s_and_saveexec_b64 s[4:5], vcc
	s_cbranch_execz .LBB0_1487
	s_barrier
	s_branch .LBB0_1487

.LBB0_1661:
	ds_read_b128 v[180:183], v172
	ds_read_b128 v[184:187], v172 offset:1024
	ds_read_b128 v[188:191], v172 offset:2048
	ds_read_b128 v[192:195], v172 offset:3072
	v_add_u32_e32 v178, 0xc000, v152
	v_lshl_add_u64 v[244:245], s[8:9], 0, v[146:147]
	v_readfirstlane_b32 s1, v178
	v_add_u32_e32 v179, 0xe000, v152
	v_lshl_add_u64 v[224:225], v[244:245], 0, s[12:13]
	s_mov_b32 m0, s1
	v_lshl_add_u64 v[246:247], s[8:9], 0, v[148:149]
	v_readfirstlane_b32 s1, v179
	ds_read_b128 v[174:177], v161
	ds_read_b128 v[196:199], v161 offset:1024
	ds_read_b128 v[200:203], v160
	ds_read_b128 v[204:207], v160 offset:1024
	ds_read_b128 v[208:211], v159
	ds_read_b128 v[212:215], v159 offset:1024
	ds_read_b128 v[216:219], v158
	ds_read_b128 v[220:223], v158 offset:1024
	global_load_lds_dwordx4 v[224:225], off
	v_lshl_add_u64 v[224:225], v[246:247], 0, s[12:13]
	s_mov_b32 m0, s1
	s_nop 0
	global_load_lds_dwordx4 v[224:225], off
	s_waitcnt vmcnt(10)
	s_waitcnt lgkmcnt(8)
	s_barrier
	s_waitcnt lgkmcnt(0)
	s_setprio 1
	s_waitcnt lgkmcnt(0)
	v_mfma_f32_16x16x32_bf16 v[124:127], v[180:183], v[174:177], v[124:127]
	v_mfma_f32_16x16x32_bf16 v[120:123], v[188:191], v[174:177], v[120:123]
	v_mfma_f32_16x16x32_bf16 v[116:119], v[180:183], v[200:203], v[116:119]
	v_mfma_f32_16x16x32_bf16 v[112:115], v[188:191], v[200:203], v[112:115]
	v_mfma_f32_16x16x32_bf16 v[108:111], v[180:183], v[208:211], v[108:111]
	v_mfma_f32_16x16x32_bf16 v[104:107], v[188:191], v[208:211], v[104:107]
	v_mfma_f32_16x16x32_bf16 v[100:103], v[180:183], v[216:219], v[100:103]
	v_mfma_f32_16x16x32_bf16 v[96:99], v[188:191], v[216:219], v[96:99]
	v_mfma_f32_16x16x32_bf16 v[124:127], v[184:187], v[196:199], v[124:127]
	v_mfma_f32_16x16x32_bf16 v[120:123], v[192:195], v[196:199], v[120:123]
	v_mfma_f32_16x16x32_bf16 v[116:119], v[184:187], v[204:207], v[116:119]
	v_mfma_f32_16x16x32_bf16 v[112:115], v[192:195], v[204:207], v[112:115]
	v_mfma_f32_16x16x32_bf16 v[108:111], v[184:187], v[212:215], v[108:111]
	v_mfma_f32_16x16x32_bf16 v[104:107], v[192:195], v[212:215], v[104:107]
	v_mfma_f32_16x16x32_bf16 v[100:103], v[184:187], v[220:223], v[100:103]
	v_mfma_f32_16x16x32_bf16 v[96:99], v[192:195], v[220:223], v[96:99]
	s_setprio 0
	s_barrier
	v_lshl_add_u64 v[248:249], s[8:9], 0, v[142:143]
	v_readfirstlane_b32 s1, v153
	v_add_u32_e32 v173, 0x2000, v153
	v_lshl_add_u64 v[240:241], v[248:249], 0, s[14:15]
	s_mov_b32 m0, s1
	v_lshl_add_u64 v[250:251], s[8:9], 0, v[144:145]
	v_readfirstlane_b32 s1, v173
	ds_read_b128 v[224:227], v168
	ds_read_b128 v[228:231], v168 offset:1024
	ds_read_b128 v[232:235], v168 offset:2048
	ds_read_b128 v[236:239], v168 offset:3072
	global_load_lds_dwordx4 v[240:241], off
	v_lshl_add_u64 v[240:241], v[250:251], 0, s[14:15]
	s_mov_b32 m0, s1
	s_nop 0
	global_load_lds_dwordx4 v[240:241], off
	s_waitcnt vmcnt(10)
	s_barrier
	s_waitcnt lgkmcnt(0)
	s_setprio 1
	s_waitcnt lgkmcnt(0)
	v_mfma_f32_16x16x32_bf16 v[92:95], v[224:227], v[174:177], v[92:95]
	v_mfma_f32_16x16x32_bf16 v[88:91], v[232:235], v[174:177], v[88:91]
	v_mfma_f32_16x16x32_bf16 v[84:87], v[224:227], v[200:203], v[84:87]
	v_mfma_f32_16x16x32_bf16 v[80:83], v[232:235], v[200:203], v[80:83]
	v_mfma_f32_16x16x32_bf16 v[76:79], v[224:227], v[208:211], v[76:79]
	v_mfma_f32_16x16x32_bf16 v[72:75], v[232:235], v[208:211], v[72:75]
	v_mfma_f32_16x16x32_bf16 v[68:71], v[224:227], v[216:219], v[68:71]
	v_mfma_f32_16x16x32_bf16 v[64:67], v[232:235], v[216:219], v[64:67]
	v_mfma_f32_16x16x32_bf16 v[92:95], v[228:231], v[196:199], v[92:95]
	v_mfma_f32_16x16x32_bf16 v[88:91], v[236:239], v[196:199], v[88:91]
	v_mfma_f32_16x16x32_bf16 v[84:87], v[228:231], v[204:207], v[84:87]
	v_mfma_f32_16x16x32_bf16 v[80:83], v[236:239], v[204:207], v[80:83]
	v_mfma_f32_16x16x32_bf16 v[76:79], v[228:231], v[212:215], v[76:79]
	v_mfma_f32_16x16x32_bf16 v[72:75], v[236:239], v[212:215], v[72:75]
	v_mfma_f32_16x16x32_bf16 v[68:71], v[228:231], v[220:223], v[68:71]
	v_mfma_f32_16x16x32_bf16 v[64:67], v[236:239], v[220:223], v[64:67]
	s_setprio 0
	v_readfirstlane_b32 s1, v152
	v_lshl_add_u64 v[174:175], v[244:245], 0, s[16:17]
	s_mov_b32 m0, s1
	s_barrier
	ds_read_b128 v[196:199], v161 offset:16384
	ds_read_b128 v[200:203], v161 offset:17408
	ds_read_b128 v[204:207], v160 offset:16384
	ds_read_b128 v[208:211], v160 offset:17408
	ds_read_b128 v[212:215], v159 offset:16384
	ds_read_b128 v[216:219], v159 offset:17408
	ds_read_b128 v[220:223], v158 offset:16384
	ds_read_b128 v[240:243], v158 offset:17408
	global_load_lds_dwordx4 v[174:175], off
	v_add_u32_e32 v174, 0x2000, v152
	v_lshl_add_u64 v[176:177], v[246:247], 0, s[16:17]
	v_readfirstlane_b32 s1, v174
	s_mov_b32 m0, s1
	s_nop 0
	global_load_lds_dwordx4 v[176:177], off
	s_barrier
	s_waitcnt lgkmcnt(0)
	s_setprio 1
	s_waitcnt lgkmcnt(0)
	v_mfma_f32_16x16x32_bf16 v[60:63], v[180:183], v[196:199], v[60:63]
	v_mfma_f32_16x16x32_bf16 v[56:59], v[188:191], v[196:199], v[56:59]
	v_mfma_f32_16x16x32_bf16 v[52:55], v[180:183], v[204:207], v[52:55]
	v_mfma_f32_16x16x32_bf16 v[48:51], v[188:191], v[204:207], v[48:51]
	v_mfma_f32_16x16x32_bf16 v[44:47], v[180:183], v[212:215], v[44:47]
	v_mfma_f32_16x16x32_bf16 v[40:43], v[188:191], v[212:215], v[40:43]
	v_mfma_f32_16x16x32_bf16 v[36:39], v[180:183], v[220:223], v[36:39]
	v_mfma_f32_16x16x32_bf16 v[32:35], v[188:191], v[220:223], v[32:35]
	v_mfma_f32_16x16x32_bf16 v[60:63], v[184:187], v[200:203], v[60:63]
	v_mfma_f32_16x16x32_bf16 v[56:59], v[192:195], v[200:203], v[56:59]
	v_mfma_f32_16x16x32_bf16 v[52:55], v[184:187], v[208:211], v[52:55]
	v_mfma_f32_16x16x32_bf16 v[48:51], v[192:195], v[208:211], v[48:51]
	v_mfma_f32_16x16x32_bf16 v[44:47], v[184:187], v[216:219], v[44:47]
	v_mfma_f32_16x16x32_bf16 v[40:43], v[192:195], v[216:219], v[40:43]
	v_mfma_f32_16x16x32_bf16 v[36:39], v[184:187], v[240:243], v[36:39]
	v_mfma_f32_16x16x32_bf16 v[32:35], v[192:195], v[240:243], v[32:35]
	s_setprio 0
	s_barrier
	v_readfirstlane_b32 s1, v151
	v_add_u32_e32 v175, 0x2000, v151
	v_lshl_add_u64 v[176:177], v[248:249], 0, s[18:19]
	s_mov_b32 m0, s1
	v_readfirstlane_b32 s1, v175
	global_load_lds_dwordx4 v[176:177], off
	v_lshl_add_u64 v[176:177], v[250:251], 0, s[18:19]
	s_mov_b32 m0, s1
	s_nop 0
	global_load_lds_dwordx4 v[176:177], off
	s_waitcnt vmcnt(10)
	s_barrier
	s_setprio 1
	v_mfma_f32_16x16x32_bf16 v[28:31], v[224:227], v[196:199], v[28:31]
	v_mfma_f32_16x16x32_bf16 v[24:27], v[232:235], v[196:199], v[24:27]
	v_mfma_f32_16x16x32_bf16 v[20:23], v[224:227], v[204:207], v[20:23]
	v_mfma_f32_16x16x32_bf16 v[16:19], v[232:235], v[204:207], v[16:19]
	v_mfma_f32_16x16x32_bf16 v[12:15], v[224:227], v[212:215], v[12:15]
	v_mfma_f32_16x16x32_bf16 v[8:11], v[232:235], v[212:215], v[8:11]
	v_mfma_f32_16x16x32_bf16 v[4:7], v[224:227], v[220:223], v[4:7]
	v_mfma_f32_16x16x32_bf16 v[0:3], v[232:235], v[220:223], v[0:3]
	v_mfma_f32_16x16x32_bf16 v[28:31], v[228:231], v[200:203], v[28:31]
	v_mfma_f32_16x16x32_bf16 v[24:27], v[236:239], v[200:203], v[24:27]
	v_mfma_f32_16x16x32_bf16 v[20:23], v[228:231], v[208:211], v[20:23]
	v_mfma_f32_16x16x32_bf16 v[16:19], v[236:239], v[208:211], v[16:19]
	v_mfma_f32_16x16x32_bf16 v[12:15], v[228:231], v[216:219], v[12:15]
	v_mfma_f32_16x16x32_bf16 v[8:11], v[236:239], v[216:219], v[8:11]
	v_mfma_f32_16x16x32_bf16 v[4:7], v[228:231], v[240:243], v[4:7]
	v_mfma_f32_16x16x32_bf16 v[0:3], v[236:239], v[240:243], v[0:3]
	s_setprio 0
	s_barrier
	ds_read_b128 v[180:183], v163
	ds_read_b128 v[184:187], v163 offset:1024
	ds_read_b128 v[188:191], v163 offset:2048
	ds_read_b128 v[192:195], v163 offset:3072
	v_add_u32_e32 v176, 0x4000, v152
	v_add_u32_e32 v177, 0x6000, v152
	v_readfirstlane_b32 s1, v176
	v_lshl_add_u64 v[228:229], v[244:245], 0, s[20:21]
	s_mov_b32 m0, s1
	v_readfirstlane_b32 s1, v177
	ds_read_b128 v[196:199], v161 offset:32768
	ds_read_b128 v[200:203], v161 offset:33792
	ds_read_b128 v[204:207], v160 offset:32768
	ds_read_b128 v[208:211], v160 offset:33792
	ds_read_b128 v[212:215], v159 offset:32768
	ds_read_b128 v[216:219], v159 offset:33792
	ds_read_b128 v[220:223], v158 offset:32768
	ds_read_b128 v[224:227], v158 offset:33792
	global_load_lds_dwordx4 v[228:229], off
	v_lshl_add_u64 v[228:229], v[246:247], 0, s[20:21]
	s_mov_b32 m0, s1
	s_nop 0
	global_load_lds_dwordx4 v[228:229], off
	s_waitcnt vmcnt(10)
	s_waitcnt lgkmcnt(8)
	s_barrier
	s_waitcnt lgkmcnt(0)
	s_setprio 1
	s_waitcnt lgkmcnt(0)
	v_mfma_f32_16x16x32_bf16 v[124:127], v[180:183], v[196:199], v[124:127]
	v_mfma_f32_16x16x32_bf16 v[120:123], v[188:191], v[196:199], v[120:123]
	v_mfma_f32_16x16x32_bf16 v[116:119], v[180:183], v[204:207], v[116:119]
	v_mfma_f32_16x16x32_bf16 v[112:115], v[188:191], v[204:207], v[112:115]
	v_mfma_f32_16x16x32_bf16 v[108:111], v[180:183], v[212:215], v[108:111]
	v_mfma_f32_16x16x32_bf16 v[104:107], v[188:191], v[212:215], v[104:107]
	v_mfma_f32_16x16x32_bf16 v[100:103], v[180:183], v[220:223], v[100:103]
	v_mfma_f32_16x16x32_bf16 v[96:99], v[188:191], v[220:223], v[96:99]
	v_mfma_f32_16x16x32_bf16 v[124:127], v[184:187], v[200:203], v[124:127]
	v_mfma_f32_16x16x32_bf16 v[120:123], v[192:195], v[200:203], v[120:123]
	v_mfma_f32_16x16x32_bf16 v[116:119], v[184:187], v[208:211], v[116:119]
	v_mfma_f32_16x16x32_bf16 v[112:115], v[192:195], v[208:211], v[112:115]
	v_mfma_f32_16x16x32_bf16 v[108:111], v[184:187], v[216:219], v[108:111]
	v_mfma_f32_16x16x32_bf16 v[104:107], v[192:195], v[216:219], v[104:107]
	v_mfma_f32_16x16x32_bf16 v[100:103], v[184:187], v[224:227], v[100:103]
	v_mfma_f32_16x16x32_bf16 v[96:99], v[192:195], v[224:227], v[96:99]
	s_setprio 0
	s_barrier
	v_readfirstlane_b32 s1, v167
	v_add_u32_e32 v254, 0x2000, v167
	v_lshl_add_u64 v[252:253], v[248:249], 0, s[24:25]
	s_mov_b32 m0, s1
	v_readfirstlane_b32 s1, v254
	ds_read_b128 v[228:231], v162
	ds_read_b128 v[232:235], v162 offset:1024
	ds_read_b128 v[236:239], v162 offset:2048
	ds_read_b128 v[240:243], v162 offset:3072
	global_load_lds_dwordx4 v[252:253], off
	v_lshl_add_u64 v[252:253], v[250:251], 0, s[24:25]
	s_mov_b32 m0, s1
	s_nop 0
	global_load_lds_dwordx4 v[252:253], off
	s_waitcnt vmcnt(10)
	s_barrier
	s_waitcnt lgkmcnt(0)
	s_setprio 1
	s_waitcnt lgkmcnt(0)
	v_mfma_f32_16x16x32_bf16 v[92:95], v[228:231], v[196:199], v[92:95]
	v_mfma_f32_16x16x32_bf16 v[88:91], v[236:239], v[196:199], v[88:91]
	v_mfma_f32_16x16x32_bf16 v[84:87], v[228:231], v[204:207], v[84:87]
	v_mfma_f32_16x16x32_bf16 v[80:83], v[236:239], v[204:207], v[80:83]
	v_mfma_f32_16x16x32_bf16 v[76:79], v[228:231], v[212:215], v[76:79]
	v_mfma_f32_16x16x32_bf16 v[72:75], v[236:239], v[212:215], v[72:75]
	v_mfma_f32_16x16x32_bf16 v[68:71], v[228:231], v[220:223], v[68:71]
	v_mfma_f32_16x16x32_bf16 v[64:67], v[236:239], v[220:223], v[64:67]
	v_mfma_f32_16x16x32_bf16 v[92:95], v[232:235], v[200:203], v[92:95]
	v_mfma_f32_16x16x32_bf16 v[88:91], v[240:243], v[200:203], v[88:91]
	v_mfma_f32_16x16x32_bf16 v[84:87], v[232:235], v[208:211], v[84:87]
	v_mfma_f32_16x16x32_bf16 v[80:83], v[240:243], v[208:211], v[80:83]
	v_mfma_f32_16x16x32_bf16 v[76:79], v[232:235], v[216:219], v[76:79]
	v_mfma_f32_16x16x32_bf16 v[72:75], v[240:243], v[216:219], v[72:75]
	v_mfma_f32_16x16x32_bf16 v[68:71], v[232:235], v[224:227], v[68:71]
	v_mfma_f32_16x16x32_bf16 v[64:67], v[240:243], v[224:227], v[64:67]
	s_setprio 0
	v_readfirstlane_b32 s1, v169
	v_lshl_add_u64 v[244:245], v[244:245], 0, s[26:27]
	s_mov_b32 m0, s1
	v_readfirstlane_b32 s1, v170
	s_barrier
	ds_read_b128 v[196:199], v161 offset:49152
	ds_read_b128 v[200:203], v161 offset:50176
	ds_read_b128 v[204:207], v160 offset:49152
	ds_read_b128 v[208:211], v160 offset:50176
	ds_read_b128 v[212:215], v159 offset:49152
	ds_read_b128 v[216:219], v159 offset:50176
	ds_read_b128 v[220:223], v158 offset:49152
	ds_read_b128 v[224:227], v158 offset:50176
	global_load_lds_dwordx4 v[244:245], off
	v_lshl_add_u64 v[244:245], v[246:247], 0, s[26:27]
	s_mov_b32 m0, s1
	s_nop 0
	global_load_lds_dwordx4 v[244:245], off
	s_barrier
	s_waitcnt lgkmcnt(0)
	s_setprio 1
	s_waitcnt lgkmcnt(0)
	v_mfma_f32_16x16x32_bf16 v[60:63], v[180:183], v[196:199], v[60:63]
	v_mfma_f32_16x16x32_bf16 v[56:59], v[188:191], v[196:199], v[56:59]
	v_mfma_f32_16x16x32_bf16 v[52:55], v[180:183], v[204:207], v[52:55]
	v_mfma_f32_16x16x32_bf16 v[48:51], v[188:191], v[204:207], v[48:51]
	v_mfma_f32_16x16x32_bf16 v[44:47], v[180:183], v[212:215], v[44:47]
	v_mfma_f32_16x16x32_bf16 v[40:43], v[188:191], v[212:215], v[40:43]
	v_mfma_f32_16x16x32_bf16 v[36:39], v[180:183], v[220:223], v[36:39]
	v_mfma_f32_16x16x32_bf16 v[32:35], v[188:191], v[220:223], v[32:35]
	v_mfma_f32_16x16x32_bf16 v[60:63], v[184:187], v[200:203], v[60:63]
	v_mfma_f32_16x16x32_bf16 v[56:59], v[192:195], v[200:203], v[56:59]
	v_mfma_f32_16x16x32_bf16 v[52:55], v[184:187], v[208:211], v[52:55]
	v_mfma_f32_16x16x32_bf16 v[48:51], v[192:195], v[208:211], v[48:51]
	v_mfma_f32_16x16x32_bf16 v[44:47], v[184:187], v[216:219], v[44:47]
	v_mfma_f32_16x16x32_bf16 v[40:43], v[192:195], v[216:219], v[40:43]
	v_mfma_f32_16x16x32_bf16 v[36:39], v[184:187], v[224:227], v[36:39]
	v_mfma_f32_16x16x32_bf16 v[32:35], v[192:195], v[224:227], v[32:35]
	s_setprio 0
	s_barrier
	v_readfirstlane_b32 s1, v171
	v_add_u32_e32 v182, 0x2000, v171
	v_lshl_add_u64 v[180:181], v[248:249], 0, s[28:29]
	s_mov_b32 m0, s1
	v_readfirstlane_b32 s1, v182
	global_load_lds_dwordx4 v[180:181], off
	v_lshl_add_u64 v[180:181], v[250:251], 0, s[28:29]
	s_mov_b32 m0, s1
	s_nop 0
	global_load_lds_dwordx4 v[180:181], off
	s_waitcnt vmcnt(10)
	s_barrier
	s_setprio 1
	v_mfma_f32_16x16x32_bf16 v[28:31], v[228:231], v[196:199], v[28:31]
	v_mfma_f32_16x16x32_bf16 v[24:27], v[236:239], v[196:199], v[24:27]
	v_mfma_f32_16x16x32_bf16 v[20:23], v[228:231], v[204:207], v[20:23]
	v_mfma_f32_16x16x32_bf16 v[16:19], v[236:239], v[204:207], v[16:19]
	v_mfma_f32_16x16x32_bf16 v[12:15], v[228:231], v[212:215], v[12:15]
	v_mfma_f32_16x16x32_bf16 v[8:11], v[236:239], v[212:215], v[8:11]
	v_mfma_f32_16x16x32_bf16 v[4:7], v[228:231], v[220:223], v[4:7]
	v_mfma_f32_16x16x32_bf16 v[0:3], v[236:239], v[220:223], v[0:3]
	v_mfma_f32_16x16x32_bf16 v[28:31], v[232:235], v[200:203], v[28:31]
	v_mfma_f32_16x16x32_bf16 v[24:27], v[240:243], v[200:203], v[24:27]
	v_mfma_f32_16x16x32_bf16 v[20:23], v[232:235], v[208:211], v[20:23]
	v_mfma_f32_16x16x32_bf16 v[16:19], v[240:243], v[208:211], v[16:19]
	v_mfma_f32_16x16x32_bf16 v[12:15], v[232:235], v[216:219], v[12:15]
	v_mfma_f32_16x16x32_bf16 v[8:11], v[240:243], v[216:219], v[8:11]
	v_mfma_f32_16x16x32_bf16 v[4:7], v[232:235], v[224:227], v[4:7]
	v_mfma_f32_16x16x32_bf16 v[0:3], v[240:243], v[224:227], v[0:3]
	s_setprio 0
	s_add_i32 s0, s0, 2
	v_lshl_add_u64 v[142:143], v[142:143], 0, s[30:31]
	v_lshl_add_u64 v[144:145], v[144:145], 0, s[30:31]
	v_lshl_add_u64 v[146:147], v[146:147], 0, s[30:31]
	s_cmp_lt_u32 s0, 12
	v_lshl_add_u64 v[148:149], v[148:149], 0, s[30:31]
	s_barrier
	s_cbranch_scc1 .LBB0_1661
	s_or_b32 s0, s36, 0x80
	s_ashr_i32 s1, s0, 31
	s_lshl_b64 s[0:1], s[0:1], 11
	s_add_u32 s0, s39, s0
	s_addc_u32 s1, s46, s1
	v_lshl_add_u64 v[170:171], s[0:1], 0, v[130:131]
	v_lshl_add_u64 v[138:139], v[138:139], 1, v[170:171]
	v_readfirstlane_b32 s2, v178
	v_lshl_add_u64 v[138:139], v[138:139], 0, s[34:35]
	s_mov_b32 m0, s2
	ds_read_b128 v[142:145], v172
	ds_read_b128 v[146:149], v172 offset:1024
	ds_read_b128 v[180:183], v172 offset:2048
	ds_read_b128 v[184:187], v172 offset:3072
	ds_read_b128 v[188:191], v161
	ds_read_b128 v[192:195], v161 offset:1024
	ds_read_b128 v[196:199], v160
	ds_read_b128 v[200:203], v160 offset:1024
	ds_read_b128 v[204:207], v159
	ds_read_b128 v[208:211], v159 offset:1024
	ds_read_b128 v[212:215], v158
	ds_read_b128 v[216:219], v158 offset:1024
	global_load_lds_dwordx4 v[138:139], off
	v_lshl_add_u64 v[138:139], s[0:1], 0, v[134:135]
	v_lshl_add_u64 v[138:139], v[140:141], 1, v[138:139]
	v_readfirstlane_b32 s0, v179
	v_lshl_add_u64 v[138:139], v[138:139], 0, s[34:35]
	s_mov_b32 m0, s0
	v_readlane_b32 s0, v255, 11
	global_load_lds_dwordx4 v[138:139], off
	s_waitcnt vmcnt(10)
	s_add_i32 s70, s70, s0
	s_barrier
	s_waitcnt lgkmcnt(0)
	s_cmpk_gt_i32 s70, 0x7f
	s_cselect_b64 s[58:59], -1, 0
	s_setprio 1
	s_waitcnt lgkmcnt(0)
	v_mfma_f32_16x16x32_bf16 v[124:127], v[142:145], v[188:191], v[124:127]
	v_mfma_f32_16x16x32_bf16 v[120:123], v[180:183], v[188:191], v[120:123]
	v_mfma_f32_16x16x32_bf16 v[116:119], v[142:145], v[196:199], v[116:119]
	v_mfma_f32_16x16x32_bf16 v[112:115], v[180:183], v[196:199], v[112:115]
	v_mfma_f32_16x16x32_bf16 v[108:111], v[142:145], v[204:207], v[108:111]
	v_mfma_f32_16x16x32_bf16 v[104:107], v[180:183], v[204:207], v[104:107]
	v_mfma_f32_16x16x32_bf16 v[100:103], v[142:145], v[212:215], v[100:103]
	v_mfma_f32_16x16x32_bf16 v[96:99], v[180:183], v[212:215], v[96:99]
	v_mfma_f32_16x16x32_bf16 v[124:127], v[146:149], v[192:195], v[124:127]
	v_mfma_f32_16x16x32_bf16 v[120:123], v[184:187], v[192:195], v[120:123]
	v_mfma_f32_16x16x32_bf16 v[116:119], v[146:149], v[200:203], v[116:119]
	v_mfma_f32_16x16x32_bf16 v[112:115], v[184:187], v[200:203], v[112:115]
	v_mfma_f32_16x16x32_bf16 v[108:111], v[146:149], v[208:211], v[108:111]
	v_mfma_f32_16x16x32_bf16 v[104:107], v[184:187], v[208:211], v[104:107]
	v_mfma_f32_16x16x32_bf16 v[100:103], v[146:149], v[216:219], v[100:103]
	v_mfma_f32_16x16x32_bf16 v[96:99], v[184:187], v[216:219], v[96:99]
	s_setprio 0
	s_barrier
	ds_read_b128 v[138:141], v168
	ds_read_b128 v[220:223], v168 offset:1024
	ds_read_b128 v[224:227], v168 offset:2048
	ds_read_b128 v[168:171], v168 offset:3072
	s_waitcnt vmcnt(8)
	s_barrier
	s_waitcnt lgkmcnt(0)
	s_setprio 1
	s_waitcnt lgkmcnt(0)
	v_mfma_f32_16x16x32_bf16 v[92:95], v[138:141], v[188:191], v[92:95]
	v_mfma_f32_16x16x32_bf16 v[88:91], v[224:227], v[188:191], v[88:91]
	v_mfma_f32_16x16x32_bf16 v[84:87], v[138:141], v[196:199], v[84:87]
	v_mfma_f32_16x16x32_bf16 v[80:83], v[224:227], v[196:199], v[80:83]
	v_mfma_f32_16x16x32_bf16 v[76:79], v[138:141], v[204:207], v[76:79]
	v_mfma_f32_16x16x32_bf16 v[72:75], v[224:227], v[204:207], v[72:75]
	v_mfma_f32_16x16x32_bf16 v[68:71], v[138:141], v[212:215], v[68:71]
	v_mfma_f32_16x16x32_bf16 v[64:67], v[224:227], v[212:215], v[64:67]
	v_mfma_f32_16x16x32_bf16 v[92:95], v[220:223], v[192:195], v[92:95]
	v_mfma_f32_16x16x32_bf16 v[88:91], v[168:171], v[192:195], v[88:91]
	v_mfma_f32_16x16x32_bf16 v[84:87], v[220:223], v[200:203], v[84:87]
	v_mfma_f32_16x16x32_bf16 v[80:83], v[168:171], v[200:203], v[80:83]
	v_mfma_f32_16x16x32_bf16 v[76:79], v[220:223], v[208:211], v[76:79]
	v_mfma_f32_16x16x32_bf16 v[72:75], v[168:171], v[208:211], v[72:75]
	v_mfma_f32_16x16x32_bf16 v[68:71], v[220:223], v[216:219], v[68:71]
	v_mfma_f32_16x16x32_bf16 v[64:67], v[168:171], v[216:219], v[64:67]
	s_setprio 0
	s_barrier
	ds_read_b128 v[188:191], v161 offset:16384
	ds_read_b128 v[192:195], v161 offset:17408
	ds_read_b128 v[196:199], v160 offset:16384
	ds_read_b128 v[200:203], v160 offset:17408
	ds_read_b128 v[204:207], v159 offset:16384
	ds_read_b128 v[208:211], v159 offset:17408
	ds_read_b128 v[212:215], v158 offset:16384
	ds_read_b128 v[216:219], v158 offset:17408
	s_waitcnt vmcnt(4)
	s_barrier
	s_waitcnt lgkmcnt(0)
	s_setprio 1
	s_waitcnt lgkmcnt(0)
	v_mfma_f32_16x16x32_bf16 v[60:63], v[142:145], v[188:191], v[60:63]
	v_mfma_f32_16x16x32_bf16 v[56:59], v[180:183], v[188:191], v[56:59]
	v_mfma_f32_16x16x32_bf16 v[52:55], v[142:145], v[196:199], v[52:55]
	v_mfma_f32_16x16x32_bf16 v[48:51], v[180:183], v[196:199], v[48:51]
	v_mfma_f32_16x16x32_bf16 v[44:47], v[142:145], v[204:207], v[44:47]
	v_mfma_f32_16x16x32_bf16 v[40:43], v[180:183], v[204:207], v[40:43]
	v_mfma_f32_16x16x32_bf16 v[36:39], v[142:145], v[212:215], v[36:39]
	v_mfma_f32_16x16x32_bf16 v[32:35], v[180:183], v[212:215], v[32:35]
	v_mfma_f32_16x16x32_bf16 v[60:63], v[146:149], v[192:195], v[60:63]
	v_mfma_f32_16x16x32_bf16 v[56:59], v[184:187], v[192:195], v[56:59]
	v_mfma_f32_16x16x32_bf16 v[52:55], v[146:149], v[200:203], v[52:55]
	v_mfma_f32_16x16x32_bf16 v[48:51], v[184:187], v[200:203], v[48:51]
	v_mfma_f32_16x16x32_bf16 v[44:47], v[146:149], v[208:211], v[44:47]
	v_mfma_f32_16x16x32_bf16 v[40:43], v[184:187], v[208:211], v[40:43]
	v_mfma_f32_16x16x32_bf16 v[36:39], v[146:149], v[216:219], v[36:39]
	v_mfma_f32_16x16x32_bf16 v[32:35], v[184:187], v[216:219], v[32:35]
	s_setprio 0
	s_setprio 1
	v_mfma_f32_16x16x32_bf16 v[28:31], v[138:141], v[188:191], v[28:31]
	v_mfma_f32_16x16x32_bf16 v[24:27], v[224:227], v[188:191], v[24:27]
	v_mfma_f32_16x16x32_bf16 v[20:23], v[138:141], v[196:199], v[20:23]
	v_mfma_f32_16x16x32_bf16 v[16:19], v[224:227], v[196:199], v[16:19]
	v_mfma_f32_16x16x32_bf16 v[12:15], v[138:141], v[204:207], v[12:15]
	v_mfma_f32_16x16x32_bf16 v[8:11], v[224:227], v[204:207], v[8:11]
	v_mfma_f32_16x16x32_bf16 v[4:7], v[138:141], v[212:215], v[4:7]
	v_mfma_f32_16x16x32_bf16 v[0:3], v[224:227], v[212:215], v[0:3]
	v_mfma_f32_16x16x32_bf16 v[28:31], v[220:223], v[192:195], v[28:31]
	v_mfma_f32_16x16x32_bf16 v[24:27], v[168:171], v[192:195], v[24:27]
	v_mfma_f32_16x16x32_bf16 v[20:23], v[220:223], v[200:203], v[20:23]
	v_mfma_f32_16x16x32_bf16 v[16:19], v[168:171], v[200:203], v[16:19]
	v_mfma_f32_16x16x32_bf16 v[12:15], v[220:223], v[208:211], v[12:15]
	v_mfma_f32_16x16x32_bf16 v[8:11], v[168:171], v[208:211], v[8:11]
	v_mfma_f32_16x16x32_bf16 v[4:7], v[220:223], v[216:219], v[4:7]
	v_mfma_f32_16x16x32_bf16 v[0:3], v[168:171], v[216:219], v[0:3]
	s_setprio 0
	s_barrier
	ds_read_b128 v[138:141], v163
	ds_read_b128 v[142:145], v163 offset:1024
	ds_read_b128 v[146:149], v163 offset:2048
	ds_read_b128 v[168:171], v163 offset:3072
	ds_read_b128 v[178:181], v161 offset:32768
	ds_read_b128 v[182:185], v161 offset:33792
	ds_read_b128 v[186:189], v160 offset:32768
	ds_read_b128 v[190:193], v160 offset:33792
	ds_read_b128 v[194:197], v159 offset:32768
	ds_read_b128 v[198:201], v159 offset:33792
	ds_read_b128 v[202:205], v158 offset:32768
	ds_read_b128 v[206:209], v158 offset:33792
	s_waitcnt vmcnt(2)
	s_barrier
	s_waitcnt lgkmcnt(0)
	s_setprio 1
	s_waitcnt lgkmcnt(0)
	v_mfma_f32_16x16x32_bf16 v[124:127], v[138:141], v[178:181], v[124:127]
	v_mfma_f32_16x16x32_bf16 v[120:123], v[146:149], v[178:181], v[120:123]
	v_mfma_f32_16x16x32_bf16 v[116:119], v[138:141], v[186:189], v[116:119]
	v_mfma_f32_16x16x32_bf16 v[112:115], v[146:149], v[186:189], v[112:115]
	v_mfma_f32_16x16x32_bf16 v[108:111], v[138:141], v[194:197], v[108:111]
	v_mfma_f32_16x16x32_bf16 v[104:107], v[146:149], v[194:197], v[104:107]
	v_mfma_f32_16x16x32_bf16 v[100:103], v[138:141], v[202:205], v[100:103]
	v_mfma_f32_16x16x32_bf16 v[96:99], v[146:149], v[202:205], v[96:99]
	v_mfma_f32_16x16x32_bf16 v[124:127], v[142:145], v[182:185], v[124:127]
	v_mfma_f32_16x16x32_bf16 v[120:123], v[168:171], v[182:185], v[120:123]
	v_mfma_f32_16x16x32_bf16 v[116:119], v[142:145], v[190:193], v[116:119]
	v_mfma_f32_16x16x32_bf16 v[112:115], v[168:171], v[190:193], v[112:115]
	v_mfma_f32_16x16x32_bf16 v[108:111], v[142:145], v[198:201], v[108:111]
	v_mfma_f32_16x16x32_bf16 v[104:107], v[168:171], v[198:201], v[104:107]
	v_mfma_f32_16x16x32_bf16 v[100:103], v[142:145], v[206:209], v[100:103]
	v_mfma_f32_16x16x32_bf16 v[96:99], v[168:171], v[206:209], v[96:99]
	s_setprio 0
	s_barrier
	ds_read_b128 v[210:213], v162
	ds_read_b128 v[214:217], v162 offset:1024
	ds_read_b128 v[218:221], v162 offset:2048
	ds_read_b128 v[222:225], v162 offset:3072
	s_waitcnt vmcnt(0)
	s_barrier
	s_waitcnt lgkmcnt(0)
	s_setprio 1
	s_waitcnt lgkmcnt(0)
	v_mfma_f32_16x16x32_bf16 v[92:95], v[210:213], v[178:181], v[92:95]
	v_mfma_f32_16x16x32_bf16 v[88:91], v[218:221], v[178:181], v[88:91]
	v_mfma_f32_16x16x32_bf16 v[84:87], v[210:213], v[186:189], v[84:87]
	v_mfma_f32_16x16x32_bf16 v[80:83], v[218:221], v[186:189], v[80:83]
	v_mfma_f32_16x16x32_bf16 v[76:79], v[210:213], v[194:197], v[76:79]
	v_mfma_f32_16x16x32_bf16 v[72:75], v[218:221], v[194:197], v[72:75]
	v_mfma_f32_16x16x32_bf16 v[68:71], v[210:213], v[202:205], v[68:71]
	v_mfma_f32_16x16x32_bf16 v[64:67], v[218:221], v[202:205], v[64:67]
	v_mfma_f32_16x16x32_bf16 v[92:95], v[214:217], v[182:185], v[92:95]
	v_mfma_f32_16x16x32_bf16 v[88:91], v[222:225], v[182:185], v[88:91]
	v_mfma_f32_16x16x32_bf16 v[84:87], v[214:217], v[190:193], v[84:87]
	v_mfma_f32_16x16x32_bf16 v[80:83], v[222:225], v[190:193], v[80:83]
	v_mfma_f32_16x16x32_bf16 v[76:79], v[214:217], v[198:201], v[76:79]
	v_mfma_f32_16x16x32_bf16 v[72:75], v[222:225], v[198:201], v[72:75]
	v_mfma_f32_16x16x32_bf16 v[68:71], v[214:217], v[206:209], v[68:71]
	v_mfma_f32_16x16x32_bf16 v[64:67], v[222:225], v[206:209], v[64:67]
	s_setprio 0
	s_barrier
	ds_read_b128 v[178:181], v161 offset:49152
	ds_read_b128 v[182:185], v161 offset:50176
	ds_read_b128 v[186:189], v160 offset:49152
	ds_read_b128 v[160:163], v160 offset:50176
	ds_read_b128 v[190:193], v159 offset:49152
	ds_read_b128 v[194:197], v159 offset:50176
	ds_read_b128 v[198:201], v158 offset:49152
	ds_read_b128 v[202:205], v158 offset:50176
	s_barrier
	s_waitcnt lgkmcnt(0)
	s_setprio 1
	s_waitcnt lgkmcnt(0)
	v_mfma_f32_16x16x32_bf16 v[60:63], v[138:141], v[178:181], v[60:63]
	v_mfma_f32_16x16x32_bf16 v[56:59], v[146:149], v[178:181], v[56:59]
	v_mfma_f32_16x16x32_bf16 v[52:55], v[138:141], v[186:189], v[52:55]
	v_mfma_f32_16x16x32_bf16 v[48:51], v[146:149], v[186:189], v[48:51]
	v_mfma_f32_16x16x32_bf16 v[44:47], v[138:141], v[190:193], v[44:47]
	v_mfma_f32_16x16x32_bf16 v[40:43], v[146:149], v[190:193], v[40:43]
	v_mfma_f32_16x16x32_bf16 v[36:39], v[138:141], v[198:201], v[36:39]
	v_mfma_f32_16x16x32_bf16 v[32:35], v[146:149], v[198:201], v[32:35]
	v_mfma_f32_16x16x32_bf16 v[60:63], v[142:145], v[182:185], v[60:63]
	v_mfma_f32_16x16x32_bf16 v[56:59], v[168:171], v[182:185], v[56:59]
	v_mfma_f32_16x16x32_bf16 v[52:55], v[142:145], v[160:163], v[52:55]
	v_mfma_f32_16x16x32_bf16 v[48:51], v[168:171], v[160:163], v[48:51]
	v_mfma_f32_16x16x32_bf16 v[44:47], v[142:145], v[194:197], v[44:47]
	v_mfma_f32_16x16x32_bf16 v[40:43], v[168:171], v[194:197], v[40:43]
	v_mfma_f32_16x16x32_bf16 v[36:39], v[142:145], v[202:205], v[36:39]
	v_mfma_f32_16x16x32_bf16 v[32:35], v[168:171], v[202:205], v[32:35]
	s_setprio 0
	s_setprio 1
	v_mfma_f32_16x16x32_bf16 v[28:31], v[210:213], v[178:181], v[28:31]
	v_mfma_f32_16x16x32_bf16 v[24:27], v[218:221], v[178:181], v[24:27]
	v_mfma_f32_16x16x32_bf16 v[20:23], v[210:213], v[186:189], v[20:23]
	v_mfma_f32_16x16x32_bf16 v[16:19], v[218:221], v[186:189], v[16:19]
	v_mfma_f32_16x16x32_bf16 v[12:15], v[210:213], v[190:193], v[12:15]
	v_mfma_f32_16x16x32_bf16 v[8:11], v[218:221], v[190:193], v[8:11]
	v_mfma_f32_16x16x32_bf16 v[4:7], v[210:213], v[198:201], v[4:7]
	v_mfma_f32_16x16x32_bf16 v[0:3], v[218:221], v[198:201], v[0:3]
	v_mfma_f32_16x16x32_bf16 v[28:31], v[214:217], v[182:185], v[28:31]
	v_mfma_f32_16x16x32_bf16 v[24:27], v[222:225], v[182:185], v[24:27]
	v_mfma_f32_16x16x32_bf16 v[20:23], v[214:217], v[160:163], v[20:23]
	v_mfma_f32_16x16x32_bf16 v[16:19], v[222:225], v[160:163], v[16:19]
	v_mfma_f32_16x16x32_bf16 v[12:15], v[214:217], v[194:197], v[12:15]
	v_mfma_f32_16x16x32_bf16 v[8:11], v[222:225], v[194:197], v[8:11]
	v_mfma_f32_16x16x32_bf16 v[4:7], v[214:217], v[202:205], v[4:7]
	v_mfma_f32_16x16x32_bf16 v[0:3], v[222:225], v[202:205], v[0:3]
	s_setprio 0
	s_and_b64 vcc, exec, s[58:59]
	s_barrier
	s_cbranch_vccnz .LBB0_1664
	s_lshr_b32 s0, s70, 2
	s_and_b32 s1, s70, 3
	s_add_i32 s0, s0, s56
	s_or_b32 s1, s1, s53
	s_lshl_b32 s0, s0, 8
	s_lshl_b32 s1, s1, 19
	s_add_u32 s40, s57, s1
	s_addc_u32 s41, s62, 0
	v_lshl_add_u64 v[138:139], s[40:41], 0, v[130:131]
	v_readfirstlane_b32 s1, v153
	v_lshl_add_u64 v[138:139], v[138:139], 0, v[132:133]
	s_mov_b32 m0, s1
	v_readfirstlane_b32 s1, v173
	global_load_lds_dwordx4 v[138:139], off
	s_mov_b32 m0, s1
	s_ashr_i32 s1, s0, 31
	s_lshl_b64 s[42:43], s[0:1], 11
	v_lshl_add_u64 v[138:139], s[40:41], 0, v[134:135]
	s_add_u32 s42, s39, s42
	v_lshl_add_u64 v[138:139], v[138:139], 0, v[136:137]
	s_addc_u32 s43, s46, s43
	global_load_lds_dwordx4 v[138:139], off
	v_lshl_add_u64 v[138:139], s[42:43], 0, v[130:131]
	v_readfirstlane_b32 s1, v152
	v_lshl_add_u64 v[138:139], v[138:139], 0, v[132:133]
	s_mov_b32 m0, s1
	v_readfirstlane_b32 s1, v174
	global_load_lds_dwordx4 v[138:139], off
	v_lshl_add_u64 v[138:139], s[42:43], 0, v[134:135]
	s_add_u32 s40, s40, 0x40000
	v_lshl_add_u64 v[138:139], v[138:139], 0, v[136:137]
	s_mov_b32 m0, s1
	s_addc_u32 s41, s41, 0
	global_load_lds_dwordx4 v[138:139], off
	v_lshl_add_u64 v[138:139], s[40:41], 0, v[130:131]
	v_readfirstlane_b32 s1, v151
	v_lshl_add_u64 v[138:139], v[138:139], 0, v[132:133]
	s_mov_b32 m0, s1
	v_readfirstlane_b32 s1, v175
	s_bitset1_b32 s0, 7
	global_load_lds_dwordx4 v[138:139], off
	s_mov_b32 m0, s1
	s_ashr_i32 s1, s0, 31
	s_lshl_b64 s[0:1], s[0:1], 11
	s_add_u32 s0, s39, s0
	v_lshl_add_u64 v[138:139], s[40:41], 0, v[134:135]
	s_addc_u32 s1, s46, s1
	v_lshl_add_u64 v[138:139], v[138:139], 0, v[136:137]
	v_lshl_add_u64 v[130:131], s[0:1], 0, v[130:131]
	v_readfirstlane_b32 s2, v176
	global_load_lds_dwordx4 v[138:139], off
	v_lshl_add_u64 v[130:131], v[130:131], 0, v[132:133]
	s_mov_b32 m0, s2
	s_nop 0
	global_load_lds_dwordx4 v[130:131], off
	v_lshl_add_u64 v[130:131], s[0:1], 0, v[134:135]
	v_readfirstlane_b32 s0, v177
	v_lshl_add_u64 v[130:131], v[130:131], 0, v[136:137]
	s_mov_b32 m0, s0
	s_nop 0
	global_load_lds_dwordx4 v[130:131], off

.LBB0_1720:
	ds_read_b128 v[176:179], v173
	ds_read_b128 v[180:183], v173 offset:1024
	ds_read_b128 v[184:187], v173 offset:2048
	ds_read_b128 v[188:191], v173 offset:3072
	v_add_u32_e32 v174, 0xc000, v157
	v_lshl_add_u64 v[240:241], s[6:7], 0, v[142:143]
	v_readfirstlane_b32 s2, v174
	v_add_u32_e32 v175, 0xe000, v157
	v_lshl_add_u64 v[224:225], v[240:241], 0, s[14:15]
	s_mov_b32 m0, s2
	v_lshl_add_u64 v[242:243], s[6:7], 0, v[144:145]
	v_readfirstlane_b32 s2, v175
	ds_read_b128 v[192:195], v155
	ds_read_b128 v[196:199], v155 offset:1024
	ds_read_b128 v[200:203], v154
	ds_read_b128 v[204:207], v154 offset:1024
	ds_read_b128 v[208:211], v153
	ds_read_b128 v[212:215], v153 offset:1024
	ds_read_b128 v[216:219], v152
	ds_read_b128 v[220:223], v152 offset:1024
	global_load_lds_dwordx4 v[224:225], off
	v_lshl_add_u64 v[224:225], v[242:243], 0, s[14:15]
	s_mov_b32 m0, s2
	s_nop 0
	global_load_lds_dwordx4 v[224:225], off
	s_waitcnt vmcnt(10)
	s_waitcnt lgkmcnt(8)
	s_barrier
	s_waitcnt lgkmcnt(0)
	s_setprio 1
	s_waitcnt lgkmcnt(0)
	v_mfma_f32_16x16x32_bf16 v[124:127], v[176:179], v[192:195], v[124:127]
	v_mfma_f32_16x16x32_bf16 v[120:123], v[184:187], v[192:195], v[120:123]
	v_mfma_f32_16x16x32_bf16 v[116:119], v[176:179], v[200:203], v[116:119]
	v_mfma_f32_16x16x32_bf16 v[112:115], v[184:187], v[200:203], v[112:115]
	v_mfma_f32_16x16x32_bf16 v[108:111], v[176:179], v[208:211], v[108:111]
	v_mfma_f32_16x16x32_bf16 v[104:107], v[184:187], v[208:211], v[104:107]
	v_mfma_f32_16x16x32_bf16 v[100:103], v[176:179], v[216:219], v[100:103]
	v_mfma_f32_16x16x32_bf16 v[96:99], v[184:187], v[216:219], v[96:99]
	v_mfma_f32_16x16x32_bf16 v[124:127], v[180:183], v[196:199], v[124:127]
	v_mfma_f32_16x16x32_bf16 v[120:123], v[188:191], v[196:199], v[120:123]
	v_mfma_f32_16x16x32_bf16 v[116:119], v[180:183], v[204:207], v[116:119]
	v_mfma_f32_16x16x32_bf16 v[112:115], v[188:191], v[204:207], v[112:115]
	v_mfma_f32_16x16x32_bf16 v[108:111], v[180:183], v[212:215], v[108:111]
	v_mfma_f32_16x16x32_bf16 v[104:107], v[188:191], v[212:215], v[104:107]
	v_mfma_f32_16x16x32_bf16 v[100:103], v[180:183], v[220:223], v[100:103]
	v_mfma_f32_16x16x32_bf16 v[96:99], v[188:191], v[220:223], v[96:99]
	s_setprio 0
	s_barrier
	v_lshl_add_u64 v[244:245], s[6:7], 0, v[138:139]
	v_readfirstlane_b32 s2, v151
	v_lshl_add_u64 v[246:247], v[244:245], 0, s[16:17]
	s_mov_b32 m0, s2
	v_add_u32_e32 v250, 0x2000, v151
	ds_read_b128 v[224:227], v170
	ds_read_b128 v[228:231], v170 offset:1024
	ds_read_b128 v[232:235], v170 offset:2048
	ds_read_b128 v[236:239], v170 offset:3072
	global_load_lds_dwordx4 v[246:247], off
	v_lshl_add_u64 v[246:247], s[6:7], 0, v[140:141]
	v_readfirstlane_b32 s2, v250
	v_lshl_add_u64 v[248:249], v[246:247], 0, s[16:17]
	s_mov_b32 m0, s2
	s_nop 0
	global_load_lds_dwordx4 v[248:249], off
	s_waitcnt vmcnt(10)
	s_barrier
	s_waitcnt lgkmcnt(0)
	s_setprio 1
	s_waitcnt lgkmcnt(0)
	v_mfma_f32_16x16x32_bf16 v[92:95], v[224:227], v[192:195], v[92:95]
	v_mfma_f32_16x16x32_bf16 v[88:91], v[232:235], v[192:195], v[88:91]
	v_mfma_f32_16x16x32_bf16 v[84:87], v[224:227], v[200:203], v[84:87]
	v_mfma_f32_16x16x32_bf16 v[80:83], v[232:235], v[200:203], v[80:83]
	v_mfma_f32_16x16x32_bf16 v[76:79], v[224:227], v[208:211], v[76:79]
	v_mfma_f32_16x16x32_bf16 v[72:75], v[232:235], v[208:211], v[72:75]
	v_mfma_f32_16x16x32_bf16 v[68:71], v[224:227], v[216:219], v[68:71]
	v_mfma_f32_16x16x32_bf16 v[64:67], v[232:235], v[216:219], v[64:67]
	v_mfma_f32_16x16x32_bf16 v[92:95], v[228:231], v[196:199], v[92:95]
	v_mfma_f32_16x16x32_bf16 v[88:91], v[236:239], v[196:199], v[88:91]
	v_mfma_f32_16x16x32_bf16 v[84:87], v[228:231], v[204:207], v[84:87]
	v_mfma_f32_16x16x32_bf16 v[80:83], v[236:239], v[204:207], v[80:83]
	v_mfma_f32_16x16x32_bf16 v[76:79], v[228:231], v[212:215], v[76:79]
	v_mfma_f32_16x16x32_bf16 v[72:75], v[236:239], v[212:215], v[72:75]
	v_mfma_f32_16x16x32_bf16 v[68:71], v[228:231], v[220:223], v[68:71]
	v_mfma_f32_16x16x32_bf16 v[64:67], v[236:239], v[220:223], v[64:67]
	s_setprio 0
	v_readfirstlane_b32 s2, v157
	v_lshl_add_u64 v[248:249], v[240:241], 0, s[18:19]
	s_mov_b32 m0, s2
	v_readfirstlane_b32 s2, v158
	s_barrier
	ds_read_b128 v[192:195], v155 offset:16384
	ds_read_b128 v[196:199], v155 offset:17408
	ds_read_b128 v[200:203], v154 offset:16384
	ds_read_b128 v[204:207], v154 offset:17408
	ds_read_b128 v[208:211], v153 offset:16384
	ds_read_b128 v[212:215], v153 offset:17408
	ds_read_b128 v[216:219], v152 offset:16384
	ds_read_b128 v[220:223], v152 offset:17408
	global_load_lds_dwordx4 v[248:249], off
	v_lshl_add_u64 v[248:249], v[242:243], 0, s[18:19]
	s_mov_b32 m0, s2
	s_nop 0
	global_load_lds_dwordx4 v[248:249], off
	s_barrier
	s_waitcnt lgkmcnt(0)
	s_setprio 1
	s_waitcnt lgkmcnt(0)
	v_mfma_f32_16x16x32_bf16 v[60:63], v[176:179], v[192:195], v[60:63]
	v_mfma_f32_16x16x32_bf16 v[56:59], v[184:187], v[192:195], v[56:59]
	v_mfma_f32_16x16x32_bf16 v[52:55], v[176:179], v[200:203], v[52:55]
	v_mfma_f32_16x16x32_bf16 v[48:51], v[184:187], v[200:203], v[48:51]
	v_mfma_f32_16x16x32_bf16 v[44:47], v[176:179], v[208:211], v[44:47]
	v_mfma_f32_16x16x32_bf16 v[40:43], v[184:187], v[208:211], v[40:43]
	v_mfma_f32_16x16x32_bf16 v[36:39], v[176:179], v[216:219], v[36:39]
	v_mfma_f32_16x16x32_bf16 v[32:35], v[184:187], v[216:219], v[32:35]
	v_mfma_f32_16x16x32_bf16 v[60:63], v[180:183], v[196:199], v[60:63]
	v_mfma_f32_16x16x32_bf16 v[56:59], v[188:191], v[196:199], v[56:59]
	v_mfma_f32_16x16x32_bf16 v[52:55], v[180:183], v[204:207], v[52:55]
	v_mfma_f32_16x16x32_bf16 v[48:51], v[188:191], v[204:207], v[48:51]
	v_mfma_f32_16x16x32_bf16 v[44:47], v[180:183], v[212:215], v[44:47]
	v_mfma_f32_16x16x32_bf16 v[40:43], v[188:191], v[212:215], v[40:43]
	v_mfma_f32_16x16x32_bf16 v[36:39], v[180:183], v[220:223], v[36:39]
	v_mfma_f32_16x16x32_bf16 v[32:35], v[188:191], v[220:223], v[32:35]
	s_setprio 0
	s_barrier
	v_readfirstlane_b32 s2, v159
	v_add_u32_e32 v178, 0x2000, v159
	v_lshl_add_u64 v[176:177], v[244:245], 0, s[20:21]
	s_mov_b32 m0, s2
	v_readfirstlane_b32 s2, v178
	global_load_lds_dwordx4 v[176:177], off
	v_lshl_add_u64 v[176:177], v[246:247], 0, s[20:21]
	s_mov_b32 m0, s2
	s_nop 0
	global_load_lds_dwordx4 v[176:177], off
	s_waitcnt vmcnt(10)
	s_barrier
	s_setprio 1
	v_mfma_f32_16x16x32_bf16 v[28:31], v[224:227], v[192:195], v[28:31]
	v_mfma_f32_16x16x32_bf16 v[24:27], v[232:235], v[192:195], v[24:27]
	v_mfma_f32_16x16x32_bf16 v[20:23], v[224:227], v[200:203], v[20:23]
	v_mfma_f32_16x16x32_bf16 v[16:19], v[232:235], v[200:203], v[16:19]
	v_mfma_f32_16x16x32_bf16 v[12:15], v[224:227], v[208:211], v[12:15]
	v_mfma_f32_16x16x32_bf16 v[8:11], v[232:235], v[208:211], v[8:11]
	v_mfma_f32_16x16x32_bf16 v[4:7], v[224:227], v[216:219], v[4:7]
	v_mfma_f32_16x16x32_bf16 v[0:3], v[232:235], v[216:219], v[0:3]
	v_mfma_f32_16x16x32_bf16 v[28:31], v[228:231], v[196:199], v[28:31]
	v_mfma_f32_16x16x32_bf16 v[24:27], v[236:239], v[196:199], v[24:27]
	v_mfma_f32_16x16x32_bf16 v[20:23], v[228:231], v[204:207], v[20:23]
	v_mfma_f32_16x16x32_bf16 v[16:19], v[236:239], v[204:207], v[16:19]
	v_mfma_f32_16x16x32_bf16 v[12:15], v[228:231], v[212:215], v[12:15]
	v_mfma_f32_16x16x32_bf16 v[8:11], v[236:239], v[212:215], v[8:11]
	v_mfma_f32_16x16x32_bf16 v[4:7], v[228:231], v[220:223], v[4:7]
	v_mfma_f32_16x16x32_bf16 v[0:3], v[236:239], v[220:223], v[0:3]
	s_setprio 0
	s_barrier
	ds_read_b128 v[176:179], v160
	ds_read_b128 v[180:183], v160 offset:1024
	ds_read_b128 v[184:187], v160 offset:2048
	ds_read_b128 v[188:191], v160 offset:3072
	v_readfirstlane_b32 s2, v161
	v_lshl_add_u64 v[224:225], v[240:241], 0, s[24:25]
	s_mov_b32 m0, s2
	v_readfirstlane_b32 s2, v162
	ds_read_b128 v[192:195], v155 offset:32768
	ds_read_b128 v[196:199], v155 offset:33792
	ds_read_b128 v[200:203], v154 offset:32768
	ds_read_b128 v[204:207], v154 offset:33792
	ds_read_b128 v[208:211], v153 offset:32768
	ds_read_b128 v[212:215], v153 offset:33792
	ds_read_b128 v[216:219], v152 offset:32768
	ds_read_b128 v[220:223], v152 offset:33792
	global_load_lds_dwordx4 v[224:225], off
	v_lshl_add_u64 v[224:225], v[242:243], 0, s[24:25]
	s_mov_b32 m0, s2
	s_nop 0
	global_load_lds_dwordx4 v[224:225], off
	s_waitcnt vmcnt(10)
	s_waitcnt lgkmcnt(8)
	s_barrier
	s_waitcnt lgkmcnt(0)
	s_setprio 1
	s_waitcnt lgkmcnt(0)
	v_mfma_f32_16x16x32_bf16 v[124:127], v[176:179], v[192:195], v[124:127]
	v_mfma_f32_16x16x32_bf16 v[120:123], v[184:187], v[192:195], v[120:123]
	v_mfma_f32_16x16x32_bf16 v[116:119], v[176:179], v[200:203], v[116:119]
	v_mfma_f32_16x16x32_bf16 v[112:115], v[184:187], v[200:203], v[112:115]
	v_mfma_f32_16x16x32_bf16 v[108:111], v[176:179], v[208:211], v[108:111]
	v_mfma_f32_16x16x32_bf16 v[104:107], v[184:187], v[208:211], v[104:107]
	v_mfma_f32_16x16x32_bf16 v[100:103], v[176:179], v[216:219], v[100:103]
	v_mfma_f32_16x16x32_bf16 v[96:99], v[184:187], v[216:219], v[96:99]
	v_mfma_f32_16x16x32_bf16 v[124:127], v[180:183], v[196:199], v[124:127]
	v_mfma_f32_16x16x32_bf16 v[120:123], v[188:191], v[196:199], v[120:123]
	v_mfma_f32_16x16x32_bf16 v[116:119], v[180:183], v[204:207], v[116:119]
	v_mfma_f32_16x16x32_bf16 v[112:115], v[188:191], v[204:207], v[112:115]
	v_mfma_f32_16x16x32_bf16 v[108:111], v[180:183], v[212:215], v[108:111]
	v_mfma_f32_16x16x32_bf16 v[104:107], v[188:191], v[212:215], v[104:107]
	v_mfma_f32_16x16x32_bf16 v[100:103], v[180:183], v[220:223], v[100:103]
	v_mfma_f32_16x16x32_bf16 v[96:99], v[188:191], v[220:223], v[96:99]
	s_setprio 0
	s_barrier
	v_readfirstlane_b32 s2, v163
	v_lshl_add_u64 v[248:249], v[244:245], 0, s[26:27]
	s_mov_b32 m0, s2
	v_readfirstlane_b32 s2, v167
	ds_read_b128 v[224:227], v156
	ds_read_b128 v[228:231], v156 offset:1024
	ds_read_b128 v[232:235], v156 offset:2048
	ds_read_b128 v[236:239], v156 offset:3072
	global_load_lds_dwordx4 v[248:249], off
	v_lshl_add_u64 v[248:249], v[246:247], 0, s[26:27]
	s_mov_b32 m0, s2
	s_nop 0
	global_load_lds_dwordx4 v[248:249], off
	s_waitcnt vmcnt(10)
	s_barrier
	s_waitcnt lgkmcnt(0)
	s_setprio 1
	s_waitcnt lgkmcnt(0)
	v_mfma_f32_16x16x32_bf16 v[92:95], v[224:227], v[192:195], v[92:95]
	v_mfma_f32_16x16x32_bf16 v[88:91], v[232:235], v[192:195], v[88:91]
	v_mfma_f32_16x16x32_bf16 v[84:87], v[224:227], v[200:203], v[84:87]
	v_mfma_f32_16x16x32_bf16 v[80:83], v[232:235], v[200:203], v[80:83]
	v_mfma_f32_16x16x32_bf16 v[76:79], v[224:227], v[208:211], v[76:79]
	v_mfma_f32_16x16x32_bf16 v[72:75], v[232:235], v[208:211], v[72:75]
	v_mfma_f32_16x16x32_bf16 v[68:71], v[224:227], v[216:219], v[68:71]
	v_mfma_f32_16x16x32_bf16 v[64:67], v[232:235], v[216:219], v[64:67]
	v_mfma_f32_16x16x32_bf16 v[92:95], v[228:231], v[196:199], v[92:95]
	v_mfma_f32_16x16x32_bf16 v[88:91], v[236:239], v[196:199], v[88:91]
	v_mfma_f32_16x16x32_bf16 v[84:87], v[228:231], v[204:207], v[84:87]
	v_mfma_f32_16x16x32_bf16 v[80:83], v[236:239], v[204:207], v[80:83]
	v_mfma_f32_16x16x32_bf16 v[76:79], v[228:231], v[212:215], v[76:79]
	v_mfma_f32_16x16x32_bf16 v[72:75], v[236:239], v[212:215], v[72:75]
	v_mfma_f32_16x16x32_bf16 v[68:71], v[228:231], v[220:223], v[68:71]
	v_mfma_f32_16x16x32_bf16 v[64:67], v[236:239], v[220:223], v[64:67]
	s_setprio 0
	v_readfirstlane_b32 s2, v168
	v_lshl_add_u64 v[240:241], v[240:241], 0, s[28:29]
	s_mov_b32 m0, s2
	v_readfirstlane_b32 s2, v169
	s_barrier
	ds_read_b128 v[192:195], v155 offset:49152
	ds_read_b128 v[196:199], v155 offset:50176
	ds_read_b128 v[200:203], v154 offset:49152
	ds_read_b128 v[204:207], v154 offset:50176
	ds_read_b128 v[208:211], v153 offset:49152
	ds_read_b128 v[212:215], v153 offset:50176
	ds_read_b128 v[216:219], v152 offset:49152
	ds_read_b128 v[220:223], v152 offset:50176
	global_load_lds_dwordx4 v[240:241], off
	v_lshl_add_u64 v[240:241], v[242:243], 0, s[28:29]
	s_mov_b32 m0, s2
	s_nop 0
	global_load_lds_dwordx4 v[240:241], off
	s_barrier
	s_waitcnt lgkmcnt(0)
	s_setprio 1
	s_waitcnt lgkmcnt(0)
	v_mfma_f32_16x16x32_bf16 v[60:63], v[176:179], v[192:195], v[60:63]
	v_mfma_f32_16x16x32_bf16 v[56:59], v[184:187], v[192:195], v[56:59]
	v_mfma_f32_16x16x32_bf16 v[52:55], v[176:179], v[200:203], v[52:55]
	v_mfma_f32_16x16x32_bf16 v[48:51], v[184:187], v[200:203], v[48:51]
	v_mfma_f32_16x16x32_bf16 v[44:47], v[176:179], v[208:211], v[44:47]
	v_mfma_f32_16x16x32_bf16 v[40:43], v[184:187], v[208:211], v[40:43]
	v_mfma_f32_16x16x32_bf16 v[36:39], v[176:179], v[216:219], v[36:39]
	v_mfma_f32_16x16x32_bf16 v[32:35], v[184:187], v[216:219], v[32:35]
	v_mfma_f32_16x16x32_bf16 v[60:63], v[180:183], v[196:199], v[60:63]
	v_mfma_f32_16x16x32_bf16 v[56:59], v[188:191], v[196:199], v[56:59]
	v_mfma_f32_16x16x32_bf16 v[52:55], v[180:183], v[204:207], v[52:55]
	v_mfma_f32_16x16x32_bf16 v[48:51], v[188:191], v[204:207], v[48:51]
	v_mfma_f32_16x16x32_bf16 v[44:47], v[180:183], v[212:215], v[44:47]
	v_mfma_f32_16x16x32_bf16 v[40:43], v[188:191], v[212:215], v[40:43]
	v_mfma_f32_16x16x32_bf16 v[36:39], v[180:183], v[220:223], v[36:39]
	v_mfma_f32_16x16x32_bf16 v[32:35], v[188:191], v[220:223], v[32:35]
	s_setprio 0
	s_barrier
	v_readfirstlane_b32 s2, v171
	v_lshl_add_u64 v[176:177], v[244:245], 0, s[30:31]
	s_mov_b32 m0, s2
	v_readfirstlane_b32 s2, v172
	global_load_lds_dwordx4 v[176:177], off
	v_lshl_add_u64 v[176:177], v[246:247], 0, s[30:31]
	s_mov_b32 m0, s2
	s_nop 0
	global_load_lds_dwordx4 v[176:177], off
	s_waitcnt vmcnt(10)
	s_barrier
	s_setprio 1
	v_mfma_f32_16x16x32_bf16 v[28:31], v[224:227], v[192:195], v[28:31]
	v_mfma_f32_16x16x32_bf16 v[24:27], v[232:235], v[192:195], v[24:27]
	v_mfma_f32_16x16x32_bf16 v[20:23], v[224:227], v[200:203], v[20:23]
	v_mfma_f32_16x16x32_bf16 v[16:19], v[232:235], v[200:203], v[16:19]
	v_mfma_f32_16x16x32_bf16 v[12:15], v[224:227], v[208:211], v[12:15]
	v_mfma_f32_16x16x32_bf16 v[8:11], v[232:235], v[208:211], v[8:11]
	v_mfma_f32_16x16x32_bf16 v[4:7], v[224:227], v[216:219], v[4:7]
	v_mfma_f32_16x16x32_bf16 v[0:3], v[232:235], v[216:219], v[0:3]
	v_mfma_f32_16x16x32_bf16 v[28:31], v[228:231], v[196:199], v[28:31]
	v_mfma_f32_16x16x32_bf16 v[24:27], v[236:239], v[196:199], v[24:27]
	v_mfma_f32_16x16x32_bf16 v[20:23], v[228:231], v[204:207], v[20:23]
	v_mfma_f32_16x16x32_bf16 v[16:19], v[236:239], v[204:207], v[16:19]
	v_mfma_f32_16x16x32_bf16 v[12:15], v[228:231], v[212:215], v[12:15]
	v_mfma_f32_16x16x32_bf16 v[8:11], v[236:239], v[212:215], v[8:11]
	v_mfma_f32_16x16x32_bf16 v[4:7], v[228:231], v[220:223], v[4:7]
	v_mfma_f32_16x16x32_bf16 v[0:3], v[236:239], v[220:223], v[0:3]
	s_setprio 0
	s_add_i32 s1, s1, 2
	v_lshl_add_u64 v[138:139], v[138:139], 0, s[34:35]
	v_lshl_add_u64 v[140:141], v[140:141], 0, s[34:35]
	v_lshl_add_u64 v[142:143], v[142:143], 0, s[34:35]
	s_cmp_lt_u32 s1, 60
	v_lshl_add_u64 v[144:145], v[144:145], 0, s[34:35]
	s_barrier
	s_cbranch_scc1 .LBB0_1720
	s_add_u32 s4, s38, 0x1f80
	s_addc_u32 s5, s39, 0
	v_lshl_add_u64 v[132:133], s[4:5], 0, v[132:133]
	v_readfirstlane_b32 s1, v174
	v_lshl_add_u64 v[130:131], v[130:131], 1, v[132:133]
	s_mov_b32 m0, s1
	ds_read_b128 v[138:141], v173
	ds_read_b128 v[142:145], v173 offset:1024
	ds_read_b128 v[176:179], v173 offset:2048
	ds_read_b128 v[180:183], v173 offset:3072
	ds_read_b128 v[184:187], v155
	ds_read_b128 v[188:191], v155 offset:1024
	ds_read_b128 v[192:195], v154
	ds_read_b128 v[196:199], v154 offset:1024
	ds_read_b128 v[200:203], v153
	ds_read_b128 v[204:207], v153 offset:1024
	ds_read_b128 v[208:211], v152
	ds_read_b128 v[212:215], v152 offset:1024
	global_load_lds_dwordx4 v[130:131], off
	v_lshl_add_u64 v[130:131], s[4:5], 0, v[136:137]
	v_readfirstlane_b32 s1, v175
	v_lshl_add_u64 v[130:131], v[134:135], 1, v[130:131]
	s_mov_b32 m0, s1
	s_nop 0
	global_load_lds_dwordx4 v[130:131], off
	s_waitcnt vmcnt(10)
	s_barrier
	s_waitcnt lgkmcnt(0)
	s_setprio 1
	s_waitcnt lgkmcnt(0)
	v_mfma_f32_16x16x32_bf16 v[124:127], v[138:141], v[184:187], v[124:127]
	v_mfma_f32_16x16x32_bf16 v[116:119], v[138:141], v[192:195], v[116:119]
	v_mfma_f32_16x16x32_bf16 v[108:111], v[138:141], v[200:203], v[108:111]
	v_mfma_f32_16x16x32_bf16 v[100:103], v[138:141], v[208:211], v[100:103]
	v_mfma_f32_16x16x32_bf16 v[124:127], v[142:145], v[188:191], v[124:127]
	v_mfma_f32_16x16x32_bf16 v[120:123], v[176:179], v[184:187], v[120:123]
	v_mfma_f32_16x16x32_bf16 v[116:119], v[142:145], v[196:199], v[116:119]
	v_mfma_f32_16x16x32_bf16 v[112:115], v[176:179], v[192:195], v[112:115]
	v_mfma_f32_16x16x32_bf16 v[108:111], v[142:145], v[204:207], v[108:111]
	v_mfma_f32_16x16x32_bf16 v[104:107], v[176:179], v[200:203], v[104:107]
	v_mfma_f32_16x16x32_bf16 v[100:103], v[142:145], v[212:215], v[100:103]
	v_mfma_f32_16x16x32_bf16 v[96:99], v[176:179], v[208:211], v[96:99]
	v_mfma_f32_16x16x32_bf16 v[130:133], v[180:183], v[188:191], v[120:123]
	v_mfma_f32_16x16x32_bf16 v[134:137], v[180:183], v[196:199], v[112:115]
	v_mfma_f32_16x16x32_bf16 v[172:175], v[180:183], v[204:207], v[104:107]
	v_mfma_f32_16x16x32_bf16 v[216:219], v[180:183], v[212:215], v[96:99]
	s_setprio 0
	s_barrier
	s_nop 1
	ds_read_b128 v[96:99], v170
	ds_read_b128 v[104:107], v170 offset:1024
	ds_read_b128 v[112:115], v170 offset:2048
	ds_read_b128 v[120:123], v170 offset:3072
	s_waitcnt vmcnt(8)
	s_barrier
	s_waitcnt lgkmcnt(0)
	s_setprio 1
	s_waitcnt lgkmcnt(0)
	v_mfma_f32_16x16x32_bf16 v[92:95], v[96:99], v[184:187], v[92:95]
	v_mfma_f32_16x16x32_bf16 v[84:87], v[96:99], v[192:195], v[84:87]
	v_mfma_f32_16x16x32_bf16 v[76:79], v[96:99], v[200:203], v[76:79]
	v_mfma_f32_16x16x32_bf16 v[68:71], v[96:99], v[208:211], v[68:71]
	v_mfma_f32_16x16x32_bf16 v[92:95], v[104:107], v[188:191], v[92:95]
	v_mfma_f32_16x16x32_bf16 v[88:91], v[112:115], v[184:187], v[88:91]
	v_mfma_f32_16x16x32_bf16 v[84:87], v[104:107], v[196:199], v[84:87]
	v_mfma_f32_16x16x32_bf16 v[80:83], v[112:115], v[192:195], v[80:83]
	v_mfma_f32_16x16x32_bf16 v[76:79], v[104:107], v[204:207], v[76:79]
	v_mfma_f32_16x16x32_bf16 v[72:75], v[112:115], v[200:203], v[72:75]
	v_mfma_f32_16x16x32_bf16 v[68:71], v[104:107], v[212:215], v[68:71]
	v_mfma_f32_16x16x32_bf16 v[64:67], v[112:115], v[208:211], v[64:67]
	v_mfma_f32_16x16x32_bf16 v[168:171], v[120:123], v[188:191], v[88:91]
	v_mfma_f32_16x16x32_bf16 v[184:187], v[120:123], v[196:199], v[80:83]
	v_mfma_f32_16x16x32_bf16 v[188:191], v[120:123], v[204:207], v[72:75]
	v_mfma_f32_16x16x32_bf16 v[192:195], v[120:123], v[212:215], v[64:67]
	s_setprio 0
	s_barrier
	s_nop 1
	ds_read_b128 v[64:67], v155 offset:16384
	ds_read_b128 v[72:75], v155 offset:17408
	ds_read_b128 v[80:83], v154 offset:16384
	ds_read_b128 v[88:91], v154 offset:17408
	ds_read_b128 v[196:199], v153 offset:16384
	ds_read_b128 v[200:203], v153 offset:17408
	ds_read_b128 v[204:207], v152 offset:16384
	ds_read_b128 v[208:211], v152 offset:17408
	s_waitcnt vmcnt(4)
	s_barrier
	s_waitcnt lgkmcnt(0)
	s_setprio 1
	s_waitcnt lgkmcnt(0)
	v_mfma_f32_16x16x32_bf16 v[60:63], v[138:141], v[64:67], v[60:63]
	v_mfma_f32_16x16x32_bf16 v[52:55], v[138:141], v[80:83], v[52:55]
	v_mfma_f32_16x16x32_bf16 v[44:47], v[138:141], v[196:199], v[44:47]
	v_mfma_f32_16x16x32_bf16 v[36:39], v[138:141], v[204:207], v[36:39]
	v_mfma_f32_16x16x32_bf16 v[60:63], v[142:145], v[72:75], v[60:63]
	v_mfma_f32_16x16x32_bf16 v[56:59], v[176:179], v[64:67], v[56:59]
	v_mfma_f32_16x16x32_bf16 v[52:55], v[142:145], v[88:91], v[52:55]
	v_mfma_f32_16x16x32_bf16 v[48:51], v[176:179], v[80:83], v[48:51]
	v_mfma_f32_16x16x32_bf16 v[44:47], v[142:145], v[200:203], v[44:47]
	v_mfma_f32_16x16x32_bf16 v[40:43], v[176:179], v[196:199], v[40:43]
	v_mfma_f32_16x16x32_bf16 v[36:39], v[142:145], v[208:211], v[36:39]
	v_mfma_f32_16x16x32_bf16 v[32:35], v[176:179], v[204:207], v[32:35]
	v_mfma_f32_16x16x32_bf16 v[212:215], v[180:183], v[72:75], v[56:59]
	v_mfma_f32_16x16x32_bf16 v[220:223], v[180:183], v[88:91], v[48:51]
	v_mfma_f32_16x16x32_bf16 v[224:227], v[180:183], v[200:203], v[40:43]
	v_mfma_f32_16x16x32_bf16 v[138:141], v[180:183], v[208:211], v[32:35]
	s_setprio 0
	s_setprio 1
	v_mfma_f32_16x16x32_bf16 v[28:31], v[96:99], v[64:67], v[28:31]
	v_mfma_f32_16x16x32_bf16 v[20:23], v[96:99], v[80:83], v[20:23]
	v_mfma_f32_16x16x32_bf16 v[12:15], v[96:99], v[196:199], v[12:15]
	v_mfma_f32_16x16x32_bf16 v[4:7], v[96:99], v[204:207], v[4:7]
	v_mfma_f32_16x16x32_bf16 v[28:31], v[104:107], v[72:75], v[28:31]
	v_mfma_f32_16x16x32_bf16 v[24:27], v[112:115], v[64:67], v[24:27]
	v_mfma_f32_16x16x32_bf16 v[20:23], v[104:107], v[88:91], v[20:23]
	v_mfma_f32_16x16x32_bf16 v[16:19], v[112:115], v[80:83], v[16:19]
	v_mfma_f32_16x16x32_bf16 v[12:15], v[104:107], v[200:203], v[12:15]
	v_mfma_f32_16x16x32_bf16 v[8:11], v[112:115], v[196:199], v[8:11]
	v_mfma_f32_16x16x32_bf16 v[4:7], v[104:107], v[208:211], v[4:7]
	v_mfma_f32_16x16x32_bf16 v[0:3], v[112:115], v[204:207], v[0:3]
	v_mfma_f32_16x16x32_bf16 v[142:145], v[120:123], v[72:75], v[24:27]
	v_mfma_f32_16x16x32_bf16 v[176:179], v[120:123], v[88:91], v[16:19]
	v_mfma_f32_16x16x32_bf16 v[180:183], v[120:123], v[200:203], v[8:11]
	v_mfma_f32_16x16x32_bf16 v[196:199], v[120:123], v[208:211], v[0:3]
	s_setprio 0
	s_barrier
	s_nop 1
	ds_read_b128 v[0:3], v160
	ds_read_b128 v[8:11], v160 offset:1024
	ds_read_b128 v[16:19], v160 offset:2048
	ds_read_b128 v[24:27], v160 offset:3072
	ds_read_b128 v[32:35], v155 offset:32768
	ds_read_b128 v[40:43], v155 offset:33792
	ds_read_b128 v[48:51], v154 offset:32768
	ds_read_b128 v[56:59], v154 offset:33792
	ds_read_b128 v[64:67], v153 offset:32768
	ds_read_b128 v[158:161], v153 offset:33792
	ds_read_b128 v[200:203], v152 offset:32768
	ds_read_b128 v[204:207], v152 offset:33792
	s_waitcnt vmcnt(2)
	s_barrier
	s_waitcnt lgkmcnt(0)
	s_setprio 1
	s_waitcnt lgkmcnt(0)
	v_mfma_f32_16x16x32_bf16 v[72:75], v[0:3], v[32:35], v[124:127]
	v_mfma_f32_16x16x32_bf16 v[120:123], v[8:11], v[40:43], v[72:75]
	v_mfma_f32_16x16x32_bf16 v[72:75], v[16:19], v[32:35], v[130:133]
	v_mfma_f32_16x16x32_bf16 v[124:127], v[24:27], v[40:43], v[72:75]
	v_mfma_f32_16x16x32_bf16 v[72:75], v[0:3], v[48:51], v[116:119]
	v_mfma_f32_16x16x32_bf16 v[112:115], v[8:11], v[56:59], v[72:75]
	v_mfma_f32_16x16x32_bf16 v[72:75], v[16:19], v[48:51], v[134:137]
	v_mfma_f32_16x16x32_bf16 v[116:119], v[24:27], v[56:59], v[72:75]
	v_mfma_f32_16x16x32_bf16 v[72:75], v[0:3], v[64:67], v[108:111]
	v_mfma_f32_16x16x32_bf16 v[104:107], v[8:11], v[158:161], v[72:75]
	v_mfma_f32_16x16x32_bf16 v[72:75], v[16:19], v[64:67], v[172:175]
	v_mfma_f32_16x16x32_bf16 v[108:111], v[24:27], v[158:161], v[72:75]
	v_mfma_f32_16x16x32_bf16 v[72:75], v[0:3], v[200:203], v[100:103]
	v_mfma_f32_16x16x32_bf16 v[96:99], v[8:11], v[204:207], v[72:75]
	v_mfma_f32_16x16x32_bf16 v[72:75], v[16:19], v[200:203], v[216:219]
	v_mfma_f32_16x16x32_bf16 v[100:103], v[24:27], v[204:207], v[72:75]
	s_setprio 0
	s_barrier
	ds_read_b128 v[130:133], v156
	ds_read_b128 v[134:137], v156 offset:1024
	ds_read_b128 v[172:175], v156 offset:2048
	ds_read_b128 v[208:211], v156 offset:3072
	s_waitcnt vmcnt(0)
	s_barrier
	s_waitcnt lgkmcnt(0)
	s_setprio 1
	s_waitcnt lgkmcnt(0)
	v_mfma_f32_16x16x32_bf16 v[72:75], v[130:133], v[32:35], v[92:95]
	v_mfma_f32_16x16x32_bf16 v[32:35], v[172:175], v[32:35], v[168:171]
	v_mfma_f32_16x16x32_bf16 v[92:95], v[208:211], v[40:43], v[32:35]
	v_mfma_f32_16x16x32_bf16 v[32:35], v[130:133], v[48:51], v[84:87]
	v_mfma_f32_16x16x32_bf16 v[80:83], v[134:137], v[56:59], v[32:35]
	v_mfma_f32_16x16x32_bf16 v[32:35], v[172:175], v[48:51], v[184:187]
	v_mfma_f32_16x16x32_bf16 v[84:87], v[208:211], v[56:59], v[32:35]
	v_mfma_f32_16x16x32_bf16 v[32:35], v[130:133], v[64:67], v[76:79]
	v_mfma_f32_16x16x32_bf16 v[88:91], v[134:137], v[40:43], v[72:75]
	v_mfma_f32_16x16x32_bf16 v[72:75], v[134:137], v[158:161], v[32:35]
	v_mfma_f32_16x16x32_bf16 v[32:35], v[172:175], v[64:67], v[188:191]
	v_mfma_f32_16x16x32_bf16 v[76:79], v[208:211], v[158:161], v[32:35]
	v_mfma_f32_16x16x32_bf16 v[32:35], v[130:133], v[200:203], v[68:71]
	v_mfma_f32_16x16x32_bf16 v[64:67], v[134:137], v[204:207], v[32:35]
	v_mfma_f32_16x16x32_bf16 v[32:35], v[172:175], v[200:203], v[192:195]
	v_mfma_f32_16x16x32_bf16 v[68:71], v[208:211], v[204:207], v[32:35]
	s_setprio 0
	s_barrier
	ds_read_b128 v[156:159], v155 offset:49152
	ds_read_b128 v[160:163], v155 offset:50176
	ds_read_b128 v[168:171], v154 offset:49152
	ds_read_b128 v[184:187], v154 offset:50176
	ds_read_b128 v[188:191], v153 offset:49152
	ds_read_b128 v[192:195], v153 offset:50176
	ds_read_b128 v[200:203], v152 offset:49152
	ds_read_b128 v[152:155], v152 offset:50176
	s_barrier
	s_waitcnt lgkmcnt(0)
	s_setprio 1
	s_waitcnt lgkmcnt(0)
	v_mfma_f32_16x16x32_bf16 v[32:35], v[0:3], v[156:159], v[60:63]
	v_mfma_f32_16x16x32_bf16 v[56:59], v[8:11], v[160:163], v[32:35]
	v_mfma_f32_16x16x32_bf16 v[32:35], v[16:19], v[156:159], v[212:215]
	v_mfma_f32_16x16x32_bf16 v[60:63], v[24:27], v[160:163], v[32:35]
	v_mfma_f32_16x16x32_bf16 v[32:35], v[0:3], v[168:171], v[52:55]
	v_mfma_f32_16x16x32_bf16 v[48:51], v[8:11], v[184:187], v[32:35]
	v_mfma_f32_16x16x32_bf16 v[32:35], v[16:19], v[168:171], v[220:223]
	v_mfma_f32_16x16x32_bf16 v[52:55], v[24:27], v[184:187], v[32:35]
	v_mfma_f32_16x16x32_bf16 v[32:35], v[0:3], v[188:191], v[44:47]
	v_mfma_f32_16x16x32_bf16 v[40:43], v[8:11], v[192:195], v[32:35]
	v_mfma_f32_16x16x32_bf16 v[32:35], v[16:19], v[188:191], v[224:227]
	v_mfma_f32_16x16x32_bf16 v[0:3], v[0:3], v[200:203], v[36:39]
	v_mfma_f32_16x16x32_bf16 v[44:47], v[24:27], v[192:195], v[32:35]
	v_mfma_f32_16x16x32_bf16 v[32:35], v[8:11], v[152:155], v[0:3]
	v_mfma_f32_16x16x32_bf16 v[0:3], v[16:19], v[200:203], v[138:141]
	v_mfma_f32_16x16x32_bf16 v[36:39], v[24:27], v[152:155], v[0:3]
	s_setprio 0
	s_setprio 1
	v_mfma_f32_16x16x32_bf16 v[0:3], v[130:133], v[156:159], v[28:31]
	v_mfma_f32_16x16x32_bf16 v[24:27], v[134:137], v[160:163], v[0:3]
	v_mfma_f32_16x16x32_bf16 v[0:3], v[172:175], v[156:159], v[142:145]
	v_mfma_f32_16x16x32_bf16 v[28:31], v[208:211], v[160:163], v[0:3]
	v_mfma_f32_16x16x32_bf16 v[0:3], v[130:133], v[168:171], v[20:23]
	v_mfma_f32_16x16x32_bf16 v[16:19], v[134:137], v[184:187], v[0:3]
	v_mfma_f32_16x16x32_bf16 v[0:3], v[172:175], v[168:171], v[176:179]
	v_mfma_f32_16x16x32_bf16 v[20:23], v[208:211], v[184:187], v[0:3]
	v_mfma_f32_16x16x32_bf16 v[0:3], v[130:133], v[188:191], v[12:15]
	v_mfma_f32_16x16x32_bf16 v[8:11], v[134:137], v[192:195], v[0:3]
	v_mfma_f32_16x16x32_bf16 v[0:3], v[172:175], v[188:191], v[180:183]
	v_mfma_f32_16x16x32_bf16 v[12:15], v[208:211], v[192:195], v[0:3]
	v_mfma_f32_16x16x32_bf16 v[0:3], v[130:133], v[200:203], v[4:7]
	v_mfma_f32_16x16x32_bf16 v[4:7], v[172:175], v[200:203], v[196:199]
	v_mfma_f32_16x16x32_bf16 v[0:3], v[134:137], v[152:155], v[0:3]
	v_mfma_f32_16x16x32_bf16 v[4:7], v[208:211], v[152:155], v[4:7]
	s_setprio 0
	v_cmp_gt_u32_e32 vcc, s75, v128
	s_barrier
	s_and_saveexec_b64 s[38:39], vcc
	s_cbranch_execz .LBB0_1716
	s_barrier
	s_branch .LBB0_1716

.LBB0_1842:
	ds_read_b128 v[180:183], v172
	ds_read_b128 v[184:187], v172 offset:1024
	ds_read_b128 v[188:191], v172 offset:2048
	ds_read_b128 v[192:195], v172 offset:3072
	v_add_u32_e32 v178, 0xc000, v152
	v_lshl_add_u64 v[244:245], s[12:13], 0, v[146:147]
	v_readfirstlane_b32 s1, v178
	v_add_u32_e32 v179, 0xe000, v152
	v_lshl_add_u64 v[224:225], v[244:245], 0, s[20:21]
	s_mov_b32 m0, s1
	v_lshl_add_u64 v[246:247], s[12:13], 0, v[148:149]
	v_readfirstlane_b32 s1, v179
	ds_read_b128 v[174:177], v161
	ds_read_b128 v[196:199], v161 offset:1024
	ds_read_b128 v[200:203], v160
	ds_read_b128 v[204:207], v160 offset:1024
	ds_read_b128 v[208:211], v159
	ds_read_b128 v[212:215], v159 offset:1024
	ds_read_b128 v[216:219], v158
	ds_read_b128 v[220:223], v158 offset:1024
	global_load_lds_dwordx4 v[224:225], off
	v_lshl_add_u64 v[224:225], v[246:247], 0, s[20:21]
	s_mov_b32 m0, s1
	s_nop 0
	global_load_lds_dwordx4 v[224:225], off
	s_waitcnt vmcnt(10)
	s_waitcnt lgkmcnt(8)
	s_barrier
	s_waitcnt lgkmcnt(0)
	s_setprio 1
	s_waitcnt lgkmcnt(0)
	v_mfma_f32_16x16x32_bf16 v[124:127], v[180:183], v[174:177], v[124:127]
	v_mfma_f32_16x16x32_bf16 v[120:123], v[188:191], v[174:177], v[120:123]
	v_mfma_f32_16x16x32_bf16 v[116:119], v[180:183], v[200:203], v[116:119]
	v_mfma_f32_16x16x32_bf16 v[112:115], v[188:191], v[200:203], v[112:115]
	v_mfma_f32_16x16x32_bf16 v[108:111], v[180:183], v[208:211], v[108:111]
	v_mfma_f32_16x16x32_bf16 v[104:107], v[188:191], v[208:211], v[104:107]
	v_mfma_f32_16x16x32_bf16 v[100:103], v[180:183], v[216:219], v[100:103]
	v_mfma_f32_16x16x32_bf16 v[96:99], v[188:191], v[216:219], v[96:99]
	v_mfma_f32_16x16x32_bf16 v[124:127], v[184:187], v[196:199], v[124:127]
	v_mfma_f32_16x16x32_bf16 v[120:123], v[192:195], v[196:199], v[120:123]
	v_mfma_f32_16x16x32_bf16 v[116:119], v[184:187], v[204:207], v[116:119]
	v_mfma_f32_16x16x32_bf16 v[112:115], v[192:195], v[204:207], v[112:115]
	v_mfma_f32_16x16x32_bf16 v[108:111], v[184:187], v[212:215], v[108:111]
	v_mfma_f32_16x16x32_bf16 v[104:107], v[192:195], v[212:215], v[104:107]
	v_mfma_f32_16x16x32_bf16 v[100:103], v[184:187], v[220:223], v[100:103]
	v_mfma_f32_16x16x32_bf16 v[96:99], v[192:195], v[220:223], v[96:99]
	s_setprio 0
	s_barrier
	v_lshl_add_u64 v[248:249], s[12:13], 0, v[142:143]
	v_readfirstlane_b32 s1, v153
	v_add_u32_e32 v173, 0x2000, v153
	v_lshl_add_u64 v[240:241], v[248:249], 0, s[24:25]
	s_mov_b32 m0, s1
	v_lshl_add_u64 v[250:251], s[12:13], 0, v[144:145]
	v_readfirstlane_b32 s1, v173
	ds_read_b128 v[224:227], v169
	ds_read_b128 v[228:231], v169 offset:1024
	ds_read_b128 v[232:235], v169 offset:2048
	ds_read_b128 v[236:239], v169 offset:3072
	global_load_lds_dwordx4 v[240:241], off
	v_lshl_add_u64 v[240:241], v[250:251], 0, s[24:25]
	s_mov_b32 m0, s1
	s_nop 0
	global_load_lds_dwordx4 v[240:241], off
	s_waitcnt vmcnt(10)
	s_barrier
	s_waitcnt lgkmcnt(0)
	s_setprio 1
	s_waitcnt lgkmcnt(0)
	v_mfma_f32_16x16x32_bf16 v[92:95], v[224:227], v[174:177], v[92:95]
	v_mfma_f32_16x16x32_bf16 v[88:91], v[232:235], v[174:177], v[88:91]
	v_mfma_f32_16x16x32_bf16 v[84:87], v[224:227], v[200:203], v[84:87]
	v_mfma_f32_16x16x32_bf16 v[80:83], v[232:235], v[200:203], v[80:83]
	v_mfma_f32_16x16x32_bf16 v[76:79], v[224:227], v[208:211], v[76:79]
	v_mfma_f32_16x16x32_bf16 v[72:75], v[232:235], v[208:211], v[72:75]
	v_mfma_f32_16x16x32_bf16 v[68:71], v[224:227], v[216:219], v[68:71]
	v_mfma_f32_16x16x32_bf16 v[64:67], v[232:235], v[216:219], v[64:67]
	v_mfma_f32_16x16x32_bf16 v[92:95], v[228:231], v[196:199], v[92:95]
	v_mfma_f32_16x16x32_bf16 v[88:91], v[236:239], v[196:199], v[88:91]
	v_mfma_f32_16x16x32_bf16 v[84:87], v[228:231], v[204:207], v[84:87]
	v_mfma_f32_16x16x32_bf16 v[80:83], v[236:239], v[204:207], v[80:83]
	v_mfma_f32_16x16x32_bf16 v[76:79], v[228:231], v[212:215], v[76:79]
	v_mfma_f32_16x16x32_bf16 v[72:75], v[236:239], v[212:215], v[72:75]
	v_mfma_f32_16x16x32_bf16 v[68:71], v[228:231], v[220:223], v[68:71]
	v_mfma_f32_16x16x32_bf16 v[64:67], v[236:239], v[220:223], v[64:67]
	s_setprio 0
	v_readfirstlane_b32 s1, v152
	v_lshl_add_u64 v[174:175], v[244:245], 0, s[26:27]
	s_mov_b32 m0, s1
	s_barrier
	ds_read_b128 v[196:199], v161 offset:16384
	ds_read_b128 v[200:203], v161 offset:17408
	ds_read_b128 v[204:207], v160 offset:16384
	ds_read_b128 v[208:211], v160 offset:17408
	ds_read_b128 v[212:215], v159 offset:16384
	ds_read_b128 v[216:219], v159 offset:17408
	ds_read_b128 v[220:223], v158 offset:16384
	ds_read_b128 v[240:243], v158 offset:17408
	global_load_lds_dwordx4 v[174:175], off
	v_add_u32_e32 v174, 0x2000, v152
	v_lshl_add_u64 v[176:177], v[246:247], 0, s[26:27]
	v_readfirstlane_b32 s1, v174
	s_mov_b32 m0, s1
	s_nop 0
	global_load_lds_dwordx4 v[176:177], off
	s_barrier
	s_waitcnt lgkmcnt(0)
	s_setprio 1
	s_waitcnt lgkmcnt(0)
	v_mfma_f32_16x16x32_bf16 v[60:63], v[180:183], v[196:199], v[60:63]
	v_mfma_f32_16x16x32_bf16 v[56:59], v[188:191], v[196:199], v[56:59]
	v_mfma_f32_16x16x32_bf16 v[52:55], v[180:183], v[204:207], v[52:55]
	v_mfma_f32_16x16x32_bf16 v[48:51], v[188:191], v[204:207], v[48:51]
	v_mfma_f32_16x16x32_bf16 v[44:47], v[180:183], v[212:215], v[44:47]
	v_mfma_f32_16x16x32_bf16 v[40:43], v[188:191], v[212:215], v[40:43]
	v_mfma_f32_16x16x32_bf16 v[36:39], v[180:183], v[220:223], v[36:39]
	v_mfma_f32_16x16x32_bf16 v[32:35], v[188:191], v[220:223], v[32:35]
	v_mfma_f32_16x16x32_bf16 v[60:63], v[184:187], v[200:203], v[60:63]
	v_mfma_f32_16x16x32_bf16 v[56:59], v[192:195], v[200:203], v[56:59]
	v_mfma_f32_16x16x32_bf16 v[52:55], v[184:187], v[208:211], v[52:55]
	v_mfma_f32_16x16x32_bf16 v[48:51], v[192:195], v[208:211], v[48:51]
	v_mfma_f32_16x16x32_bf16 v[44:47], v[184:187], v[216:219], v[44:47]
	v_mfma_f32_16x16x32_bf16 v[40:43], v[192:195], v[216:219], v[40:43]
	v_mfma_f32_16x16x32_bf16 v[36:39], v[184:187], v[240:243], v[36:39]
	v_mfma_f32_16x16x32_bf16 v[32:35], v[192:195], v[240:243], v[32:35]
	s_setprio 0
	s_barrier
	v_readfirstlane_b32 s1, v151
	v_add_u32_e32 v175, 0x2000, v151
	v_lshl_add_u64 v[176:177], v[248:249], 0, s[28:29]
	s_mov_b32 m0, s1
	v_readfirstlane_b32 s1, v175
	global_load_lds_dwordx4 v[176:177], off
	v_lshl_add_u64 v[176:177], v[250:251], 0, s[28:29]
	s_mov_b32 m0, s1
	s_nop 0
	global_load_lds_dwordx4 v[176:177], off
	s_waitcnt vmcnt(10)
	s_barrier
	s_setprio 1
	v_mfma_f32_16x16x32_bf16 v[28:31], v[224:227], v[196:199], v[28:31]
	v_mfma_f32_16x16x32_bf16 v[24:27], v[232:235], v[196:199], v[24:27]
	v_mfma_f32_16x16x32_bf16 v[20:23], v[224:227], v[204:207], v[20:23]
	v_mfma_f32_16x16x32_bf16 v[16:19], v[232:235], v[204:207], v[16:19]
	v_mfma_f32_16x16x32_bf16 v[12:15], v[224:227], v[212:215], v[12:15]
	v_mfma_f32_16x16x32_bf16 v[8:11], v[232:235], v[212:215], v[8:11]
	v_mfma_f32_16x16x32_bf16 v[4:7], v[224:227], v[220:223], v[4:7]
	v_mfma_f32_16x16x32_bf16 v[0:3], v[232:235], v[220:223], v[0:3]
	v_mfma_f32_16x16x32_bf16 v[28:31], v[228:231], v[200:203], v[28:31]
	v_mfma_f32_16x16x32_bf16 v[24:27], v[236:239], v[200:203], v[24:27]
	v_mfma_f32_16x16x32_bf16 v[20:23], v[228:231], v[208:211], v[20:23]
	v_mfma_f32_16x16x32_bf16 v[16:19], v[236:239], v[208:211], v[16:19]
	v_mfma_f32_16x16x32_bf16 v[12:15], v[228:231], v[216:219], v[12:15]
	v_mfma_f32_16x16x32_bf16 v[8:11], v[236:239], v[216:219], v[8:11]
	v_mfma_f32_16x16x32_bf16 v[4:7], v[228:231], v[240:243], v[4:7]
	v_mfma_f32_16x16x32_bf16 v[0:3], v[236:239], v[240:243], v[0:3]
	s_setprio 0
	s_barrier
	ds_read_b128 v[180:183], v163
	ds_read_b128 v[184:187], v163 offset:1024
	ds_read_b128 v[188:191], v163 offset:2048
	ds_read_b128 v[192:195], v163 offset:3072
	v_add_u32_e32 v176, 0x4000, v152
	v_add_u32_e32 v177, 0x6000, v152
	v_readfirstlane_b32 s1, v176
	v_lshl_add_u64 v[228:229], v[244:245], 0, s[30:31]
	s_mov_b32 m0, s1
	v_readfirstlane_b32 s1, v177
	ds_read_b128 v[196:199], v161 offset:32768
	ds_read_b128 v[200:203], v161 offset:33792
	ds_read_b128 v[204:207], v160 offset:32768
	ds_read_b128 v[208:211], v160 offset:33792
	ds_read_b128 v[212:215], v159 offset:32768
	ds_read_b128 v[216:219], v159 offset:33792
	ds_read_b128 v[220:223], v158 offset:32768
	ds_read_b128 v[224:227], v158 offset:33792
	global_load_lds_dwordx4 v[228:229], off
	v_lshl_add_u64 v[228:229], v[246:247], 0, s[30:31]
	s_mov_b32 m0, s1
	s_nop 0
	global_load_lds_dwordx4 v[228:229], off
	s_waitcnt vmcnt(10)
	s_waitcnt lgkmcnt(8)
	s_barrier
	s_waitcnt lgkmcnt(0)
	s_setprio 1
	s_waitcnt lgkmcnt(0)
	v_mfma_f32_16x16x32_bf16 v[124:127], v[180:183], v[196:199], v[124:127]
	v_mfma_f32_16x16x32_bf16 v[120:123], v[188:191], v[196:199], v[120:123]
	v_mfma_f32_16x16x32_bf16 v[116:119], v[180:183], v[204:207], v[116:119]
	v_mfma_f32_16x16x32_bf16 v[112:115], v[188:191], v[204:207], v[112:115]
	v_mfma_f32_16x16x32_bf16 v[108:111], v[180:183], v[212:215], v[108:111]
	v_mfma_f32_16x16x32_bf16 v[104:107], v[188:191], v[212:215], v[104:107]
	v_mfma_f32_16x16x32_bf16 v[100:103], v[180:183], v[220:223], v[100:103]
	v_mfma_f32_16x16x32_bf16 v[96:99], v[188:191], v[220:223], v[96:99]
	v_mfma_f32_16x16x32_bf16 v[124:127], v[184:187], v[200:203], v[124:127]
	v_mfma_f32_16x16x32_bf16 v[120:123], v[192:195], v[200:203], v[120:123]
	v_mfma_f32_16x16x32_bf16 v[116:119], v[184:187], v[208:211], v[116:119]
	v_mfma_f32_16x16x32_bf16 v[112:115], v[192:195], v[208:211], v[112:115]
	v_mfma_f32_16x16x32_bf16 v[108:111], v[184:187], v[216:219], v[108:111]
	v_mfma_f32_16x16x32_bf16 v[104:107], v[192:195], v[216:219], v[104:107]
	v_mfma_f32_16x16x32_bf16 v[100:103], v[184:187], v[224:227], v[100:103]
	v_mfma_f32_16x16x32_bf16 v[96:99], v[192:195], v[224:227], v[96:99]
	s_setprio 0
	s_barrier
	v_readfirstlane_b32 s1, v167
	v_add_u32_e32 v254, 0x2000, v167
	v_lshl_add_u64 v[252:253], v[248:249], 0, s[34:35]
	s_mov_b32 m0, s1
	v_readfirstlane_b32 s1, v254
	ds_read_b128 v[228:231], v162
	ds_read_b128 v[232:235], v162 offset:1024
	ds_read_b128 v[236:239], v162 offset:2048
	ds_read_b128 v[240:243], v162 offset:3072
	global_load_lds_dwordx4 v[252:253], off
	v_lshl_add_u64 v[252:253], v[250:251], 0, s[34:35]
	s_mov_b32 m0, s1
	s_nop 0
	global_load_lds_dwordx4 v[252:253], off
	s_waitcnt vmcnt(10)
	s_barrier
	s_waitcnt lgkmcnt(0)
	s_setprio 1
	s_waitcnt lgkmcnt(0)
	v_mfma_f32_16x16x32_bf16 v[92:95], v[228:231], v[196:199], v[92:95]
	v_mfma_f32_16x16x32_bf16 v[88:91], v[236:239], v[196:199], v[88:91]
	v_mfma_f32_16x16x32_bf16 v[84:87], v[228:231], v[204:207], v[84:87]
	v_mfma_f32_16x16x32_bf16 v[80:83], v[236:239], v[204:207], v[80:83]
	v_mfma_f32_16x16x32_bf16 v[76:79], v[228:231], v[212:215], v[76:79]
	v_mfma_f32_16x16x32_bf16 v[72:75], v[236:239], v[212:215], v[72:75]
	v_mfma_f32_16x16x32_bf16 v[68:71], v[228:231], v[220:223], v[68:71]
	v_mfma_f32_16x16x32_bf16 v[64:67], v[236:239], v[220:223], v[64:67]
	v_mfma_f32_16x16x32_bf16 v[92:95], v[232:235], v[200:203], v[92:95]
	v_mfma_f32_16x16x32_bf16 v[88:91], v[240:243], v[200:203], v[88:91]
	v_mfma_f32_16x16x32_bf16 v[84:87], v[232:235], v[208:211], v[84:87]
	v_mfma_f32_16x16x32_bf16 v[80:83], v[240:243], v[208:211], v[80:83]
	v_mfma_f32_16x16x32_bf16 v[76:79], v[232:235], v[216:219], v[76:79]
	v_mfma_f32_16x16x32_bf16 v[72:75], v[240:243], v[216:219], v[72:75]
	v_mfma_f32_16x16x32_bf16 v[68:71], v[232:235], v[224:227], v[68:71]
	v_mfma_f32_16x16x32_bf16 v[64:67], v[240:243], v[224:227], v[64:67]
	s_setprio 0
	v_readfirstlane_b32 s1, v168
	v_lshl_add_u64 v[244:245], v[244:245], 0, s[36:37]
	s_mov_b32 m0, s1
	v_readfirstlane_b32 s1, v170
	s_barrier
	ds_read_b128 v[196:199], v161 offset:49152
	ds_read_b128 v[200:203], v161 offset:50176
	ds_read_b128 v[204:207], v160 offset:49152
	ds_read_b128 v[208:211], v160 offset:50176
	ds_read_b128 v[212:215], v159 offset:49152
	ds_read_b128 v[216:219], v159 offset:50176
	ds_read_b128 v[220:223], v158 offset:49152
	ds_read_b128 v[224:227], v158 offset:50176
	global_load_lds_dwordx4 v[244:245], off
	v_lshl_add_u64 v[244:245], v[246:247], 0, s[36:37]
	s_mov_b32 m0, s1
	s_nop 0
	global_load_lds_dwordx4 v[244:245], off
	s_barrier
	s_waitcnt lgkmcnt(0)
	s_setprio 1
	s_waitcnt lgkmcnt(0)
	v_mfma_f32_16x16x32_bf16 v[60:63], v[180:183], v[196:199], v[60:63]
	v_mfma_f32_16x16x32_bf16 v[56:59], v[188:191], v[196:199], v[56:59]
	v_mfma_f32_16x16x32_bf16 v[52:55], v[180:183], v[204:207], v[52:55]
	v_mfma_f32_16x16x32_bf16 v[48:51], v[188:191], v[204:207], v[48:51]
	v_mfma_f32_16x16x32_bf16 v[44:47], v[180:183], v[212:215], v[44:47]
	v_mfma_f32_16x16x32_bf16 v[40:43], v[188:191], v[212:215], v[40:43]
	v_mfma_f32_16x16x32_bf16 v[36:39], v[180:183], v[220:223], v[36:39]
	v_mfma_f32_16x16x32_bf16 v[32:35], v[188:191], v[220:223], v[32:35]
	v_mfma_f32_16x16x32_bf16 v[60:63], v[184:187], v[200:203], v[60:63]
	v_mfma_f32_16x16x32_bf16 v[56:59], v[192:195], v[200:203], v[56:59]
	v_mfma_f32_16x16x32_bf16 v[52:55], v[184:187], v[208:211], v[52:55]
	v_mfma_f32_16x16x32_bf16 v[48:51], v[192:195], v[208:211], v[48:51]
	v_mfma_f32_16x16x32_bf16 v[44:47], v[184:187], v[216:219], v[44:47]
	v_mfma_f32_16x16x32_bf16 v[40:43], v[192:195], v[216:219], v[40:43]
	v_mfma_f32_16x16x32_bf16 v[36:39], v[184:187], v[224:227], v[36:39]
	v_mfma_f32_16x16x32_bf16 v[32:35], v[192:195], v[224:227], v[32:35]
	s_setprio 0
	s_barrier
	v_readfirstlane_b32 s1, v171
	v_add_u32_e32 v182, 0x2000, v171
	v_lshl_add_u64 v[180:181], v[248:249], 0, s[38:39]
	s_mov_b32 m0, s1
	v_readfirstlane_b32 s1, v182
	global_load_lds_dwordx4 v[180:181], off
	v_lshl_add_u64 v[180:181], v[250:251], 0, s[38:39]
	s_mov_b32 m0, s1
	s_nop 0
	global_load_lds_dwordx4 v[180:181], off
	s_waitcnt vmcnt(10)
	s_barrier
	s_setprio 1
	v_mfma_f32_16x16x32_bf16 v[28:31], v[228:231], v[196:199], v[28:31]
	v_mfma_f32_16x16x32_bf16 v[24:27], v[236:239], v[196:199], v[24:27]
	v_mfma_f32_16x16x32_bf16 v[20:23], v[228:231], v[204:207], v[20:23]
	v_mfma_f32_16x16x32_bf16 v[16:19], v[236:239], v[204:207], v[16:19]
	v_mfma_f32_16x16x32_bf16 v[12:15], v[228:231], v[212:215], v[12:15]
	v_mfma_f32_16x16x32_bf16 v[8:11], v[236:239], v[212:215], v[8:11]
	v_mfma_f32_16x16x32_bf16 v[4:7], v[228:231], v[220:223], v[4:7]
	v_mfma_f32_16x16x32_bf16 v[0:3], v[236:239], v[220:223], v[0:3]
	v_mfma_f32_16x16x32_bf16 v[28:31], v[232:235], v[200:203], v[28:31]
	v_mfma_f32_16x16x32_bf16 v[24:27], v[240:243], v[200:203], v[24:27]
	v_mfma_f32_16x16x32_bf16 v[20:23], v[232:235], v[208:211], v[20:23]
	v_mfma_f32_16x16x32_bf16 v[16:19], v[240:243], v[208:211], v[16:19]
	v_mfma_f32_16x16x32_bf16 v[12:15], v[232:235], v[216:219], v[12:15]
	v_mfma_f32_16x16x32_bf16 v[8:11], v[240:243], v[216:219], v[8:11]
	v_mfma_f32_16x16x32_bf16 v[4:7], v[232:235], v[224:227], v[4:7]
	v_mfma_f32_16x16x32_bf16 v[0:3], v[240:243], v[224:227], v[0:3]
	s_setprio 0
	s_add_i32 s0, s0, 2
	v_lshl_add_u64 v[142:143], v[142:143], 0, s[46:47]
	v_lshl_add_u64 v[144:145], v[144:145], 0, s[46:47]
	v_lshl_add_u64 v[146:147], v[146:147], 0, s[46:47]
	s_cmp_lt_u32 s0, 12
	v_lshl_add_u64 v[148:149], v[148:149], 0, s[46:47]
	s_barrier
	s_cbranch_scc1 .LBB0_1842
	s_or_b32 s0, s8, 0x80
	s_ashr_i32 s1, s0, 31
	s_lshl_b64 s[0:1], s[0:1], 11
	s_add_u32 s0, s45, s0
	s_addc_u32 s1, s64, s1
	v_lshl_add_u64 v[170:171], s[0:1], 0, v[130:131]
	v_lshl_add_u64 v[138:139], v[138:139], 1, v[170:171]
	v_readfirstlane_b32 s2, v178
	v_lshl_add_u64 v[138:139], v[138:139], 0, s[58:59]
	s_mov_b32 m0, s2
	ds_read_b128 v[142:145], v172
	ds_read_b128 v[146:149], v172 offset:1024
	ds_read_b128 v[180:183], v172 offset:2048
	ds_read_b128 v[184:187], v172 offset:3072
	ds_read_b128 v[188:191], v161
	ds_read_b128 v[192:195], v161 offset:1024
	ds_read_b128 v[196:199], v160
	ds_read_b128 v[200:203], v160 offset:1024
	ds_read_b128 v[204:207], v159
	ds_read_b128 v[208:211], v159 offset:1024
	ds_read_b128 v[212:215], v158
	ds_read_b128 v[216:219], v158 offset:1024
	global_load_lds_dwordx4 v[138:139], off
	v_lshl_add_u64 v[138:139], s[0:1], 0, v[134:135]
	v_lshl_add_u64 v[138:139], v[140:141], 1, v[138:139]
	v_readfirstlane_b32 s0, v179
	v_lshl_add_u64 v[138:139], v[138:139], 0, s[58:59]
	s_mov_b32 m0, s0
	v_readlane_b32 s0, v255, 11
	global_load_lds_dwordx4 v[138:139], off
	s_waitcnt vmcnt(10)
	s_add_i32 s79, s79, s0
	s_barrier
	s_waitcnt lgkmcnt(0)
	s_cmpk_gt_i32 s79, 0x54
	s_cselect_b64 s[60:61], -1, 0
	s_setprio 1
	s_waitcnt lgkmcnt(0)
	v_mfma_f32_16x16x32_bf16 v[124:127], v[142:145], v[188:191], v[124:127]
	v_mfma_f32_16x16x32_bf16 v[116:119], v[142:145], v[196:199], v[116:119]
	v_mfma_f32_16x16x32_bf16 v[108:111], v[142:145], v[204:207], v[108:111]
	v_mfma_f32_16x16x32_bf16 v[100:103], v[142:145], v[212:215], v[100:103]
	v_mfma_f32_16x16x32_bf16 v[124:127], v[146:149], v[192:195], v[124:127]
	v_mfma_f32_16x16x32_bf16 v[120:123], v[180:183], v[188:191], v[120:123]
	v_mfma_f32_16x16x32_bf16 v[116:119], v[146:149], v[200:203], v[116:119]
	v_mfma_f32_16x16x32_bf16 v[112:115], v[180:183], v[196:199], v[112:115]
	v_mfma_f32_16x16x32_bf16 v[108:111], v[146:149], v[208:211], v[108:111]
	v_mfma_f32_16x16x32_bf16 v[104:107], v[180:183], v[204:207], v[104:107]
	v_mfma_f32_16x16x32_bf16 v[100:103], v[146:149], v[216:219], v[100:103]
	v_mfma_f32_16x16x32_bf16 v[96:99], v[180:183], v[212:215], v[96:99]
	v_mfma_f32_16x16x32_bf16 v[138:141], v[184:187], v[192:195], v[120:123]
	v_mfma_f32_16x16x32_bf16 v[220:223], v[184:187], v[200:203], v[112:115]
	v_mfma_f32_16x16x32_bf16 v[224:227], v[184:187], v[208:211], v[104:107]
	v_mfma_f32_16x16x32_bf16 v[228:231], v[184:187], v[216:219], v[96:99]
	s_setprio 0
	s_barrier
	s_nop 1
	ds_read_b128 v[96:99], v169
	ds_read_b128 v[104:107], v169 offset:1024
	ds_read_b128 v[112:115], v169 offset:2048
	ds_read_b128 v[120:123], v169 offset:3072
	s_waitcnt vmcnt(8)
	s_barrier
	s_waitcnt lgkmcnt(0)
	s_setprio 1
	s_waitcnt lgkmcnt(0)
	v_mfma_f32_16x16x32_bf16 v[92:95], v[96:99], v[188:191], v[92:95]
	v_mfma_f32_16x16x32_bf16 v[88:91], v[112:115], v[188:191], v[88:91]
	v_mfma_f32_16x16x32_bf16 v[84:87], v[96:99], v[196:199], v[84:87]
	v_mfma_f32_16x16x32_bf16 v[80:83], v[112:115], v[196:199], v[80:83]
	v_mfma_f32_16x16x32_bf16 v[76:79], v[96:99], v[204:207], v[76:79]
	v_mfma_f32_16x16x32_bf16 v[72:75], v[112:115], v[204:207], v[72:75]
	v_mfma_f32_16x16x32_bf16 v[68:71], v[96:99], v[212:215], v[68:71]
	v_mfma_f32_16x16x32_bf16 v[64:67], v[112:115], v[212:215], v[64:67]
	v_mfma_f32_16x16x32_bf16 v[92:95], v[104:107], v[192:195], v[92:95]
	v_mfma_f32_16x16x32_bf16 v[88:91], v[120:123], v[192:195], v[88:91]
	v_mfma_f32_16x16x32_bf16 v[84:87], v[104:107], v[200:203], v[84:87]
	v_mfma_f32_16x16x32_bf16 v[80:83], v[120:123], v[200:203], v[80:83]
	v_mfma_f32_16x16x32_bf16 v[76:79], v[104:107], v[208:211], v[76:79]
	v_mfma_f32_16x16x32_bf16 v[72:75], v[120:123], v[208:211], v[72:75]
	v_mfma_f32_16x16x32_bf16 v[68:71], v[104:107], v[216:219], v[68:71]
	v_mfma_f32_16x16x32_bf16 v[64:67], v[120:123], v[216:219], v[64:67]
	s_setprio 0
	s_barrier
	ds_read_b128 v[168:171], v161 offset:16384
	ds_read_b128 v[188:191], v161 offset:17408
	ds_read_b128 v[192:195], v160 offset:16384
	ds_read_b128 v[196:199], v160 offset:17408
	ds_read_b128 v[200:203], v159 offset:16384
	ds_read_b128 v[204:207], v159 offset:17408
	ds_read_b128 v[208:211], v158 offset:16384
	ds_read_b128 v[212:215], v158 offset:17408
	s_waitcnt vmcnt(4)
	s_barrier
	s_waitcnt lgkmcnt(0)
	s_setprio 1
	s_waitcnt lgkmcnt(0)
	v_mfma_f32_16x16x32_bf16 v[60:63], v[142:145], v[168:171], v[60:63]
	v_mfma_f32_16x16x32_bf16 v[52:55], v[142:145], v[192:195], v[52:55]
	v_mfma_f32_16x16x32_bf16 v[44:47], v[142:145], v[200:203], v[44:47]
	v_mfma_f32_16x16x32_bf16 v[36:39], v[142:145], v[208:211], v[36:39]
	v_mfma_f32_16x16x32_bf16 v[60:63], v[146:149], v[188:191], v[60:63]
	v_mfma_f32_16x16x32_bf16 v[56:59], v[180:183], v[168:171], v[56:59]
	v_mfma_f32_16x16x32_bf16 v[52:55], v[146:149], v[196:199], v[52:55]
	v_mfma_f32_16x16x32_bf16 v[48:51], v[180:183], v[192:195], v[48:51]
	v_mfma_f32_16x16x32_bf16 v[44:47], v[146:149], v[204:207], v[44:47]
	v_mfma_f32_16x16x32_bf16 v[40:43], v[180:183], v[200:203], v[40:43]
	v_mfma_f32_16x16x32_bf16 v[36:39], v[146:149], v[212:215], v[36:39]
	v_mfma_f32_16x16x32_bf16 v[32:35], v[180:183], v[208:211], v[32:35]
	v_mfma_f32_16x16x32_bf16 v[216:219], v[184:187], v[188:191], v[56:59]
	v_mfma_f32_16x16x32_bf16 v[232:235], v[184:187], v[196:199], v[48:51]
	v_mfma_f32_16x16x32_bf16 v[236:239], v[184:187], v[204:207], v[40:43]
	v_mfma_f32_16x16x32_bf16 v[142:145], v[184:187], v[212:215], v[32:35]
	s_setprio 0
	s_setprio 1
	v_mfma_f32_16x16x32_bf16 v[28:31], v[96:99], v[168:171], v[28:31]
	v_mfma_f32_16x16x32_bf16 v[24:27], v[112:115], v[168:171], v[24:27]
	v_mfma_f32_16x16x32_bf16 v[20:23], v[96:99], v[192:195], v[20:23]
	v_mfma_f32_16x16x32_bf16 v[16:19], v[112:115], v[192:195], v[16:19]
	v_mfma_f32_16x16x32_bf16 v[12:15], v[96:99], v[200:203], v[12:15]
	v_mfma_f32_16x16x32_bf16 v[8:11], v[112:115], v[200:203], v[8:11]
	v_mfma_f32_16x16x32_bf16 v[4:7], v[96:99], v[208:211], v[4:7]
	v_mfma_f32_16x16x32_bf16 v[0:3], v[112:115], v[208:211], v[0:3]
	v_mfma_f32_16x16x32_bf16 v[28:31], v[104:107], v[188:191], v[28:31]
	v_mfma_f32_16x16x32_bf16 v[24:27], v[120:123], v[188:191], v[24:27]
	v_mfma_f32_16x16x32_bf16 v[20:23], v[104:107], v[196:199], v[20:23]
	v_mfma_f32_16x16x32_bf16 v[16:19], v[120:123], v[196:199], v[16:19]
	v_mfma_f32_16x16x32_bf16 v[12:15], v[104:107], v[204:207], v[12:15]
	v_mfma_f32_16x16x32_bf16 v[8:11], v[120:123], v[204:207], v[8:11]
	v_mfma_f32_16x16x32_bf16 v[4:7], v[104:107], v[212:215], v[4:7]
	v_mfma_f32_16x16x32_bf16 v[0:3], v[120:123], v[212:215], v[0:3]
	s_setprio 0
	s_barrier
	ds_read_b128 v[32:35], v163
	ds_read_b128 v[146:149], v163 offset:1024
	ds_read_b128 v[168:171], v163 offset:2048
	ds_read_b128 v[178:181], v163 offset:3072
	ds_read_b128 v[40:43], v161 offset:32768
	ds_read_b128 v[48:51], v161 offset:33792
	ds_read_b128 v[56:59], v160 offset:32768
	ds_read_b128 v[182:185], v160 offset:33792
	ds_read_b128 v[186:189], v159 offset:32768
	ds_read_b128 v[190:193], v159 offset:33792
	ds_read_b128 v[194:197], v158 offset:32768
	ds_read_b128 v[198:201], v158 offset:33792
	s_waitcnt vmcnt(2)
	s_barrier
	s_waitcnt lgkmcnt(0)
	s_setprio 1
	s_waitcnt lgkmcnt(0)
	v_mfma_f32_16x16x32_bf16 v[96:99], v[32:35], v[40:43], v[124:127]
	v_mfma_f32_16x16x32_bf16 v[120:123], v[146:149], v[48:51], v[96:99]
	v_mfma_f32_16x16x32_bf16 v[96:99], v[168:171], v[40:43], v[138:141]
	v_mfma_f32_16x16x32_bf16 v[124:127], v[178:181], v[48:51], v[96:99]
	v_mfma_f32_16x16x32_bf16 v[96:99], v[32:35], v[56:59], v[116:119]
	v_mfma_f32_16x16x32_bf16 v[112:115], v[146:149], v[182:185], v[96:99]
	v_mfma_f32_16x16x32_bf16 v[96:99], v[168:171], v[56:59], v[220:223]
	v_mfma_f32_16x16x32_bf16 v[116:119], v[178:181], v[182:185], v[96:99]
	v_mfma_f32_16x16x32_bf16 v[96:99], v[32:35], v[186:189], v[108:111]
	v_mfma_f32_16x16x32_bf16 v[104:107], v[146:149], v[190:193], v[96:99]
	v_mfma_f32_16x16x32_bf16 v[96:99], v[168:171], v[186:189], v[224:227]
	v_mfma_f32_16x16x32_bf16 v[108:111], v[178:181], v[190:193], v[96:99]
	v_mfma_f32_16x16x32_bf16 v[96:99], v[32:35], v[194:197], v[100:103]
	v_mfma_f32_16x16x32_bf16 v[100:103], v[168:171], v[194:197], v[228:231]
	v_mfma_f32_16x16x32_bf16 v[96:99], v[146:149], v[198:201], v[96:99]
	v_mfma_f32_16x16x32_bf16 v[100:103], v[178:181], v[198:201], v[100:103]
	s_setprio 0
	s_barrier
	ds_read_b128 v[138:141], v162
	ds_read_b128 v[202:205], v162 offset:1024
	ds_read_b128 v[206:209], v162 offset:2048
	ds_read_b128 v[210:213], v162 offset:3072
	s_waitcnt vmcnt(0)
	s_barrier
	s_waitcnt lgkmcnt(0)
	s_setprio 1
	s_waitcnt lgkmcnt(0)
	v_mfma_f32_16x16x32_bf16 v[92:95], v[138:141], v[40:43], v[92:95]
	v_mfma_f32_16x16x32_bf16 v[40:43], v[206:209], v[40:43], v[88:91]
	v_mfma_f32_16x16x32_bf16 v[88:91], v[210:213], v[48:51], v[40:43]
	v_mfma_f32_16x16x32_bf16 v[40:43], v[138:141], v[56:59], v[84:87]
	v_mfma_f32_16x16x32_bf16 v[84:87], v[202:205], v[182:185], v[40:43]
	v_mfma_f32_16x16x32_bf16 v[40:43], v[206:209], v[56:59], v[80:83]
	v_mfma_f32_16x16x32_bf16 v[80:83], v[210:213], v[182:185], v[40:43]
	v_mfma_f32_16x16x32_bf16 v[40:43], v[138:141], v[186:189], v[76:79]
	v_mfma_f32_16x16x32_bf16 v[76:79], v[202:205], v[190:193], v[40:43]
	v_mfma_f32_16x16x32_bf16 v[40:43], v[206:209], v[186:189], v[72:75]
	v_mfma_f32_16x16x32_bf16 v[72:75], v[210:213], v[190:193], v[40:43]
	v_mfma_f32_16x16x32_bf16 v[40:43], v[138:141], v[194:197], v[68:71]
	v_mfma_f32_16x16x32_bf16 v[68:71], v[202:205], v[198:201], v[40:43]
	v_mfma_f32_16x16x32_bf16 v[40:43], v[206:209], v[194:197], v[64:67]
	v_mfma_f32_16x16x32_bf16 v[92:95], v[202:205], v[48:51], v[92:95]
	v_mfma_f32_16x16x32_bf16 v[64:67], v[210:213], v[198:201], v[40:43]
	s_setprio 0
	s_barrier
	ds_read_b128 v[182:185], v161 offset:49152
	ds_read_b128 v[186:189], v161 offset:50176
	ds_read_b128 v[190:193], v160 offset:49152
	ds_read_b128 v[160:163], v160 offset:50176
	ds_read_b128 v[194:197], v159 offset:49152
	ds_read_b128 v[198:201], v159 offset:50176
	ds_read_b128 v[220:223], v158 offset:49152
	ds_read_b128 v[224:227], v158 offset:50176
	s_barrier
	s_waitcnt lgkmcnt(0)
	s_setprio 1
	s_waitcnt lgkmcnt(0)
	v_mfma_f32_16x16x32_bf16 v[40:43], v[32:35], v[182:185], v[60:63]
	v_mfma_f32_16x16x32_bf16 v[56:59], v[146:149], v[186:189], v[40:43]
	v_mfma_f32_16x16x32_bf16 v[40:43], v[168:171], v[182:185], v[216:219]
	v_mfma_f32_16x16x32_bf16 v[60:63], v[178:181], v[186:189], v[40:43]
	v_mfma_f32_16x16x32_bf16 v[40:43], v[32:35], v[190:193], v[52:55]
	v_mfma_f32_16x16x32_bf16 v[48:51], v[146:149], v[160:163], v[40:43]
	v_mfma_f32_16x16x32_bf16 v[40:43], v[168:171], v[190:193], v[232:235]
	v_mfma_f32_16x16x32_bf16 v[52:55], v[178:181], v[160:163], v[40:43]
	v_mfma_f32_16x16x32_bf16 v[40:43], v[32:35], v[194:197], v[44:47]
	v_mfma_f32_16x16x32_bf16 v[44:47], v[168:171], v[194:197], v[236:239]
	v_mfma_f32_16x16x32_bf16 v[32:35], v[32:35], v[220:223], v[36:39]
	v_mfma_f32_16x16x32_bf16 v[36:39], v[168:171], v[220:223], v[142:145]
	v_mfma_f32_16x16x32_bf16 v[40:43], v[146:149], v[198:201], v[40:43]
	v_mfma_f32_16x16x32_bf16 v[44:47], v[178:181], v[198:201], v[44:47]
	v_mfma_f32_16x16x32_bf16 v[32:35], v[146:149], v[224:227], v[32:35]
	v_mfma_f32_16x16x32_bf16 v[36:39], v[178:181], v[224:227], v[36:39]
	s_setprio 0
	s_setprio 1
	v_mfma_f32_16x16x32_bf16 v[28:31], v[138:141], v[182:185], v[28:31]
	v_mfma_f32_16x16x32_bf16 v[24:27], v[206:209], v[182:185], v[24:27]
	v_mfma_f32_16x16x32_bf16 v[20:23], v[138:141], v[190:193], v[20:23]
	v_mfma_f32_16x16x32_bf16 v[16:19], v[206:209], v[190:193], v[16:19]
	v_mfma_f32_16x16x32_bf16 v[12:15], v[138:141], v[194:197], v[12:15]
	v_mfma_f32_16x16x32_bf16 v[8:11], v[206:209], v[194:197], v[8:11]
	v_mfma_f32_16x16x32_bf16 v[4:7], v[138:141], v[220:223], v[4:7]
	v_mfma_f32_16x16x32_bf16 v[0:3], v[206:209], v[220:223], v[0:3]
	v_mfma_f32_16x16x32_bf16 v[28:31], v[202:205], v[186:189], v[28:31]
	v_mfma_f32_16x16x32_bf16 v[24:27], v[210:213], v[186:189], v[24:27]
	v_mfma_f32_16x16x32_bf16 v[20:23], v[202:205], v[160:163], v[20:23]
	v_mfma_f32_16x16x32_bf16 v[16:19], v[210:213], v[160:163], v[16:19]
	v_mfma_f32_16x16x32_bf16 v[12:15], v[202:205], v[198:201], v[12:15]
	v_mfma_f32_16x16x32_bf16 v[8:11], v[210:213], v[198:201], v[8:11]
	v_mfma_f32_16x16x32_bf16 v[4:7], v[202:205], v[224:227], v[4:7]
	v_mfma_f32_16x16x32_bf16 v[0:3], v[210:213], v[224:227], v[0:3]
	s_setprio 0
	s_and_b64 vcc, exec, s[60:61]
	s_barrier
	s_cbranch_vccnz .LBB0_1845
	s_mul_hi_i32 s0, s79, 0x66666667
	s_lshr_b32 s1, s0, 31
	s_ashr_i32 s0, s0, 1
	s_add_i32 s0, s0, s1
	v_readlane_b32 s1, v255, 15
	s_add_i32 s1, s0, s1
	s_mul_i32 s0, s0, 5
	s_sub_i32 s0, s79, s0
	v_readlane_b32 s2, v255, 14
	s_add_i32 s2, s0, s2
	s_lshl_b32 s4, s2, 8
	s_ashr_i32 s5, s4, 31
	s_lshl_b32 s0, s1, 8
	s_lshl_b64 s[10:11], s[4:5], 11
	s_add_u32 s10, s65, s10
	s_addc_u32 s11, s66, s11
	v_lshl_add_u64 v[138:139], s[10:11], 0, v[130:131]
	v_readfirstlane_b32 s1, v153
	v_lshl_add_u64 v[138:139], v[138:139], 0, v[132:133]
	s_mov_b32 m0, s1
	v_readfirstlane_b32 s1, v173
	global_load_lds_dwordx4 v[138:139], off
	s_mov_b32 m0, s1
	s_ashr_i32 s1, s0, 31
	v_lshl_add_u64 v[138:139], s[10:11], 0, v[134:135]
	s_lshl_b64 s[10:11], s[0:1], 11
	s_add_u32 s10, s45, s10
	v_lshl_add_u64 v[138:139], v[138:139], 0, v[136:137]
	s_addc_u32 s11, s64, s11
	s_bitset1_b32 s4, 7
	global_load_lds_dwordx4 v[138:139], off
	v_lshl_add_u64 v[138:139], s[10:11], 0, v[130:131]
	v_readfirstlane_b32 s1, v152
	s_ashr_i32 s5, s4, 31
	v_lshl_add_u64 v[138:139], v[138:139], 0, v[132:133]
	s_mov_b32 m0, s1
	s_lshl_b64 s[4:5], s[4:5], 11
	global_load_lds_dwordx4 v[138:139], off
	v_lshl_add_u64 v[138:139], s[10:11], 0, v[134:135]
	v_readfirstlane_b32 s1, v174
	s_add_u32 s4, s65, s4
	v_lshl_add_u64 v[138:139], v[138:139], 0, v[136:137]
	s_mov_b32 m0, s1
	s_addc_u32 s5, s66, s5
	global_load_lds_dwordx4 v[138:139], off
	v_lshl_add_u64 v[138:139], s[4:5], 0, v[130:131]
	v_readfirstlane_b32 s1, v151
	v_lshl_add_u64 v[138:139], v[138:139], 0, v[132:133]
	s_mov_b32 m0, s1
	v_readfirstlane_b32 s1, v175
	s_bitset1_b32 s0, 7
	global_load_lds_dwordx4 v[138:139], off
	s_mov_b32 m0, s1
	s_ashr_i32 s1, s0, 31
	s_lshl_b64 s[0:1], s[0:1], 11
	s_add_u32 s0, s45, s0
	v_lshl_add_u64 v[138:139], s[4:5], 0, v[134:135]
	s_addc_u32 s1, s64, s1
	v_lshl_add_u64 v[138:139], v[138:139], 0, v[136:137]
	v_lshl_add_u64 v[130:131], s[0:1], 0, v[130:131]
	v_readfirstlane_b32 s2, v176
	global_load_lds_dwordx4 v[138:139], off
	v_lshl_add_u64 v[130:131], v[130:131], 0, v[132:133]
	s_mov_b32 m0, s2
	s_nop 0
	global_load_lds_dwordx4 v[130:131], off
	v_lshl_add_u64 v[130:131], s[0:1], 0, v[134:135]
	v_readfirstlane_b32 s0, v177
	v_lshl_add_u64 v[130:131], v[130:131], 0, v[136:137]
	s_mov_b32 m0, s0
	s_nop 0
	global_load_lds_dwordx4 v[130:131], off

.LBB0_2799:
	ds_read_b128 v[182:185], v180
	ds_read_b128 v[186:189], v180 offset:1024
	ds_read_b128 v[190:193], v180 offset:2048
	ds_read_b128 v[194:197], v180 offset:3072
	v_add_u32_e32 v0, 0xc000, v162
	v_lshl_add_u64 v[246:247], v[142:143], 0, s[48:49]
	v_readfirstlane_b32 s4, v0
	v_lshl_add_u64 v[2:3], v[246:247], 0, s[20:21]
	s_mov_b32 m0, s4
	ds_read_b128 v[198:201], v161
	ds_read_b128 v[202:205], v161 offset:1024
	ds_read_b128 v[206:209], v160
	ds_read_b128 v[210:213], v160 offset:1024
	ds_read_b128 v[214:217], v159
	ds_read_b128 v[218:221], v159 offset:1024
	ds_read_b128 v[222:225], v158
	ds_read_b128 v[226:229], v158 offset:1024
	global_load_lds_dwordx4 v[2:3], off
	v_add_u32_e32 v2, 0xe000, v162
	v_lshl_add_u64 v[248:249], v[144:145], 0, s[48:49]
	v_readfirstlane_b32 s4, v2
	v_lshl_add_u64 v[230:231], v[248:249], 0, s[20:21]
	s_mov_b32 m0, s4
	s_nop 0
	global_load_lds_dwordx4 v[230:231], off
	s_waitcnt vmcnt(10)
	s_waitcnt lgkmcnt(8)
	s_barrier
	s_waitcnt lgkmcnt(0)
	s_setprio 1
	s_waitcnt lgkmcnt(0)
	v_mfma_f32_16x16x32_bf16 v[128:131], v[182:185], v[198:201], v[128:131]
	v_mfma_f32_16x16x32_bf16 v[124:127], v[190:193], v[198:201], v[124:127]
	v_mfma_f32_16x16x32_bf16 v[120:123], v[182:185], v[206:209], v[120:123]
	v_mfma_f32_16x16x32_bf16 v[116:119], v[190:193], v[206:209], v[116:119]
	v_mfma_f32_16x16x32_bf16 v[112:115], v[182:185], v[214:217], v[112:115]
	v_mfma_f32_16x16x32_bf16 v[108:111], v[190:193], v[214:217], v[108:111]
	v_mfma_f32_16x16x32_bf16 v[104:107], v[182:185], v[222:225], v[104:107]
	v_mfma_f32_16x16x32_bf16 v[100:103], v[190:193], v[222:225], v[100:103]
	v_mfma_f32_16x16x32_bf16 v[128:131], v[186:189], v[202:205], v[128:131]
	v_mfma_f32_16x16x32_bf16 v[124:127], v[194:197], v[202:205], v[124:127]
	v_mfma_f32_16x16x32_bf16 v[120:123], v[186:189], v[210:213], v[120:123]
	v_mfma_f32_16x16x32_bf16 v[116:119], v[194:197], v[210:213], v[116:119]
	v_mfma_f32_16x16x32_bf16 v[112:115], v[186:189], v[218:221], v[112:115]
	v_mfma_f32_16x16x32_bf16 v[108:111], v[194:197], v[218:221], v[108:111]
	v_mfma_f32_16x16x32_bf16 v[104:107], v[186:189], v[226:229], v[104:107]
	v_mfma_f32_16x16x32_bf16 v[100:103], v[194:197], v[226:229], v[100:103]
	s_setprio 0
	s_barrier
	v_lshl_add_u64 v[250:251], v[138:139], 0, s[48:49]
	v_readfirstlane_b32 s4, v147
	v_lshl_add_u64 v[252:253], v[250:251], 0, s[24:25]
	s_mov_b32 m0, s4
	v_add_u32_e32 v3, 0x2000, v147
	ds_read_b128 v[230:233], v178
	ds_read_b128 v[234:237], v178 offset:1024
	ds_read_b128 v[238:241], v178 offset:2048
	ds_read_b128 v[242:245], v178 offset:3072
	global_load_lds_dwordx4 v[252:253], off
	v_lshl_add_u64 v[252:253], v[140:141], 0, s[48:49]
	v_readfirstlane_b32 s4, v3
	v_lshl_add_u64 v[132:133], v[252:253], 0, s[24:25]
	s_mov_b32 m0, s4
	s_add_i32 s4, s2, 2
	global_load_lds_dwordx4 v[132:133], off
	s_waitcnt vmcnt(10)
	s_barrier
	s_waitcnt lgkmcnt(0)
	s_setprio 1
	s_waitcnt lgkmcnt(0)
	v_mfma_f32_16x16x32_bf16 v[96:99], v[230:233], v[198:201], v[96:99]
	v_mfma_f32_16x16x32_bf16 v[92:95], v[238:241], v[198:201], v[92:95]
	v_mfma_f32_16x16x32_bf16 v[88:91], v[230:233], v[206:209], v[88:91]
	v_mfma_f32_16x16x32_bf16 v[84:87], v[238:241], v[206:209], v[84:87]
	v_mfma_f32_16x16x32_bf16 v[80:83], v[230:233], v[214:217], v[80:83]
	v_mfma_f32_16x16x32_bf16 v[76:79], v[238:241], v[214:217], v[76:79]
	v_mfma_f32_16x16x32_bf16 v[72:75], v[230:233], v[222:225], v[72:75]
	v_mfma_f32_16x16x32_bf16 v[68:71], v[238:241], v[222:225], v[68:71]
	v_mfma_f32_16x16x32_bf16 v[96:99], v[234:237], v[202:205], v[96:99]
	v_mfma_f32_16x16x32_bf16 v[92:95], v[242:245], v[202:205], v[92:95]
	v_mfma_f32_16x16x32_bf16 v[88:91], v[234:237], v[210:213], v[88:91]
	v_mfma_f32_16x16x32_bf16 v[84:87], v[242:245], v[210:213], v[84:87]
	v_mfma_f32_16x16x32_bf16 v[80:83], v[234:237], v[218:221], v[80:83]
	v_mfma_f32_16x16x32_bf16 v[76:79], v[242:245], v[218:221], v[76:79]
	v_mfma_f32_16x16x32_bf16 v[72:75], v[234:237], v[226:229], v[72:75]
	v_mfma_f32_16x16x32_bf16 v[68:71], v[242:245], v[226:229], v[68:71]
	s_setprio 0
	v_readfirstlane_b32 s5, v162
	v_lshl_add_u64 v[132:133], v[246:247], 0, s[26:27]
	s_mov_b32 m0, s5
	v_readfirstlane_b32 s5, v163
	s_barrier
	ds_read_b128 v[198:201], v161 offset:16384
	ds_read_b128 v[202:205], v161 offset:17408
	ds_read_b128 v[206:209], v160 offset:16384
	ds_read_b128 v[210:213], v160 offset:17408
	ds_read_b128 v[214:217], v159 offset:16384
	ds_read_b128 v[218:221], v159 offset:17408
	ds_read_b128 v[222:225], v158 offset:16384
	ds_read_b128 v[226:229], v158 offset:17408
	global_load_lds_dwordx4 v[132:133], off
	v_lshl_add_u64 v[132:133], v[248:249], 0, s[26:27]
	s_mov_b32 m0, s5
	s_nop 0
	global_load_lds_dwordx4 v[132:133], off
	s_barrier
	s_waitcnt lgkmcnt(0)
	s_setprio 1
	s_waitcnt lgkmcnt(0)
	v_mfma_f32_16x16x32_bf16 v[64:67], v[182:185], v[198:201], v[64:67]
	v_mfma_f32_16x16x32_bf16 v[60:63], v[190:193], v[198:201], v[60:63]
	v_mfma_f32_16x16x32_bf16 v[56:59], v[182:185], v[206:209], v[56:59]
	v_mfma_f32_16x16x32_bf16 v[52:55], v[190:193], v[206:209], v[52:55]
	v_mfma_f32_16x16x32_bf16 v[48:51], v[182:185], v[214:217], v[48:51]
	v_mfma_f32_16x16x32_bf16 v[44:47], v[190:193], v[214:217], v[44:47]
	v_mfma_f32_16x16x32_bf16 v[40:43], v[182:185], v[222:225], v[40:43]
	v_mfma_f32_16x16x32_bf16 v[36:39], v[190:193], v[222:225], v[36:39]
	v_mfma_f32_16x16x32_bf16 v[64:67], v[186:189], v[202:205], v[64:67]
	v_mfma_f32_16x16x32_bf16 v[60:63], v[194:197], v[202:205], v[60:63]
	v_mfma_f32_16x16x32_bf16 v[56:59], v[186:189], v[210:213], v[56:59]
	v_mfma_f32_16x16x32_bf16 v[52:55], v[194:197], v[210:213], v[52:55]
	v_mfma_f32_16x16x32_bf16 v[48:51], v[186:189], v[218:221], v[48:51]
	v_mfma_f32_16x16x32_bf16 v[44:47], v[194:197], v[218:221], v[44:47]
	v_mfma_f32_16x16x32_bf16 v[40:43], v[186:189], v[226:229], v[40:43]
	v_mfma_f32_16x16x32_bf16 v[36:39], v[194:197], v[226:229], v[36:39]
	s_setprio 0
	s_barrier
	v_readfirstlane_b32 s5, v168
	v_add_u32_e32 v3, 0x2000, v168
	v_lshl_add_u64 v[132:133], v[250:251], 0, s[28:29]
	s_mov_b32 m0, s5
	v_readfirstlane_b32 s5, v3
	global_load_lds_dwordx4 v[132:133], off
	v_lshl_add_u64 v[132:133], v[252:253], 0, s[28:29]
	s_mov_b32 m0, s5
	s_nop 0
	global_load_lds_dwordx4 v[132:133], off
	s_waitcnt vmcnt(10)
	s_barrier
	s_setprio 1
	v_mfma_f32_16x16x32_bf16 v[32:35], v[230:233], v[198:201], v[32:35]
	v_mfma_f32_16x16x32_bf16 v[28:31], v[238:241], v[198:201], v[28:31]
	v_mfma_f32_16x16x32_bf16 v[24:27], v[230:233], v[206:209], v[24:27]
	v_mfma_f32_16x16x32_bf16 v[20:23], v[238:241], v[206:209], v[20:23]
	v_mfma_f32_16x16x32_bf16 v[16:19], v[230:233], v[214:217], v[16:19]
	v_mfma_f32_16x16x32_bf16 v[12:15], v[238:241], v[214:217], v[12:15]
	v_mfma_f32_16x16x32_bf16 v[8:11], v[230:233], v[222:225], v[8:11]
	v_mfma_f32_16x16x32_bf16 v[4:7], v[238:241], v[222:225], v[4:7]
	v_mfma_f32_16x16x32_bf16 v[32:35], v[234:237], v[202:205], v[32:35]
	v_mfma_f32_16x16x32_bf16 v[28:31], v[242:245], v[202:205], v[28:31]
	v_mfma_f32_16x16x32_bf16 v[24:27], v[234:237], v[210:213], v[24:27]
	v_mfma_f32_16x16x32_bf16 v[20:23], v[242:245], v[210:213], v[20:23]
	v_mfma_f32_16x16x32_bf16 v[16:19], v[234:237], v[218:221], v[16:19]
	v_mfma_f32_16x16x32_bf16 v[12:15], v[242:245], v[218:221], v[12:15]
	v_mfma_f32_16x16x32_bf16 v[8:11], v[234:237], v[226:229], v[8:11]
	v_mfma_f32_16x16x32_bf16 v[4:7], v[242:245], v[226:229], v[4:7]
	s_setprio 0
	s_barrier
	ds_read_b128 v[182:185], v170
	ds_read_b128 v[186:189], v170 offset:1024
	ds_read_b128 v[190:193], v170 offset:2048
	ds_read_b128 v[194:197], v170 offset:3072
	v_readfirstlane_b32 s5, v169
	v_lshl_add_u64 v[132:133], v[246:247], 0, s[30:31]
	s_mov_b32 m0, s5
	v_readfirstlane_b32 s5, v171
	ds_read_b128 v[198:201], v161 offset:32768
	ds_read_b128 v[202:205], v161 offset:33792
	ds_read_b128 v[206:209], v160 offset:32768
	ds_read_b128 v[210:213], v160 offset:33792
	ds_read_b128 v[214:217], v159 offset:32768
	ds_read_b128 v[218:221], v159 offset:33792
	ds_read_b128 v[222:225], v158 offset:32768
	ds_read_b128 v[226:229], v158 offset:33792
	global_load_lds_dwordx4 v[132:133], off
	v_lshl_add_u64 v[132:133], v[248:249], 0, s[30:31]
	s_mov_b32 m0, s5
	s_nop 0
	global_load_lds_dwordx4 v[132:133], off
	s_waitcnt vmcnt(10)
	s_waitcnt lgkmcnt(8)
	s_barrier
	s_waitcnt lgkmcnt(0)
	s_setprio 1
	s_waitcnt lgkmcnt(0)
	v_mfma_f32_16x16x32_bf16 v[128:131], v[182:185], v[198:201], v[128:131]
	v_mfma_f32_16x16x32_bf16 v[124:127], v[190:193], v[198:201], v[124:127]
	v_mfma_f32_16x16x32_bf16 v[120:123], v[182:185], v[206:209], v[120:123]
	v_mfma_f32_16x16x32_bf16 v[116:119], v[190:193], v[206:209], v[116:119]
	v_mfma_f32_16x16x32_bf16 v[112:115], v[182:185], v[214:217], v[112:115]
	v_mfma_f32_16x16x32_bf16 v[108:111], v[190:193], v[214:217], v[108:111]
	v_mfma_f32_16x16x32_bf16 v[104:107], v[182:185], v[222:225], v[104:107]
	v_mfma_f32_16x16x32_bf16 v[100:103], v[190:193], v[222:225], v[100:103]
	v_mfma_f32_16x16x32_bf16 v[128:131], v[186:189], v[202:205], v[128:131]
	v_mfma_f32_16x16x32_bf16 v[124:127], v[194:197], v[202:205], v[124:127]
	v_mfma_f32_16x16x32_bf16 v[120:123], v[186:189], v[210:213], v[120:123]
	v_mfma_f32_16x16x32_bf16 v[116:119], v[194:197], v[210:213], v[116:119]
	v_mfma_f32_16x16x32_bf16 v[112:115], v[186:189], v[218:221], v[112:115]
	v_mfma_f32_16x16x32_bf16 v[108:111], v[194:197], v[218:221], v[108:111]
	v_mfma_f32_16x16x32_bf16 v[104:107], v[186:189], v[226:229], v[104:107]
	v_mfma_f32_16x16x32_bf16 v[100:103], v[194:197], v[226:229], v[100:103]
	s_setprio 0
	s_barrier
	v_readfirstlane_b32 s5, v172
	v_lshl_add_u64 v[132:133], v[250:251], 0, s[34:35]
	s_mov_b32 m0, s5
	v_readfirstlane_b32 s5, v173
	ds_read_b128 v[230:233], v167
	ds_read_b128 v[234:237], v167 offset:1024
	ds_read_b128 v[238:241], v167 offset:2048
	ds_read_b128 v[242:245], v167 offset:3072
	global_load_lds_dwordx4 v[132:133], off
	v_lshl_add_u64 v[132:133], v[252:253], 0, s[34:35]
	s_mov_b32 m0, s5
	s_nop 0
	global_load_lds_dwordx4 v[132:133], off
	s_waitcnt vmcnt(10)
	s_barrier
	s_waitcnt lgkmcnt(0)
	s_setprio 1
	s_waitcnt lgkmcnt(0)
	v_mfma_f32_16x16x32_bf16 v[96:99], v[230:233], v[198:201], v[96:99]
	v_mfma_f32_16x16x32_bf16 v[92:95], v[238:241], v[198:201], v[92:95]
	v_mfma_f32_16x16x32_bf16 v[88:91], v[230:233], v[206:209], v[88:91]
	v_mfma_f32_16x16x32_bf16 v[84:87], v[238:241], v[206:209], v[84:87]
	v_mfma_f32_16x16x32_bf16 v[80:83], v[230:233], v[214:217], v[80:83]
	v_mfma_f32_16x16x32_bf16 v[76:79], v[238:241], v[214:217], v[76:79]
	v_mfma_f32_16x16x32_bf16 v[72:75], v[230:233], v[222:225], v[72:75]
	v_mfma_f32_16x16x32_bf16 v[68:71], v[238:241], v[222:225], v[68:71]
	v_mfma_f32_16x16x32_bf16 v[96:99], v[234:237], v[202:205], v[96:99]
	v_mfma_f32_16x16x32_bf16 v[92:95], v[242:245], v[202:205], v[92:95]
	v_mfma_f32_16x16x32_bf16 v[88:91], v[234:237], v[210:213], v[88:91]
	v_mfma_f32_16x16x32_bf16 v[84:87], v[242:245], v[210:213], v[84:87]
	v_mfma_f32_16x16x32_bf16 v[80:83], v[234:237], v[218:221], v[80:83]
	v_mfma_f32_16x16x32_bf16 v[76:79], v[242:245], v[218:221], v[76:79]
	v_mfma_f32_16x16x32_bf16 v[72:75], v[234:237], v[226:229], v[72:75]
	v_mfma_f32_16x16x32_bf16 v[68:71], v[242:245], v[226:229], v[68:71]
	s_setprio 0
	v_readfirstlane_b32 s5, v174
	v_lshl_add_u64 v[132:133], v[246:247], 0, s[36:37]
	s_mov_b32 m0, s5
	v_readfirstlane_b32 s5, v175
	s_barrier
	ds_read_b128 v[198:201], v161 offset:49152
	ds_read_b128 v[202:205], v161 offset:50176
	ds_read_b128 v[206:209], v160 offset:49152
	ds_read_b128 v[210:213], v160 offset:50176
	ds_read_b128 v[214:217], v159 offset:49152
	ds_read_b128 v[218:221], v159 offset:50176
	ds_read_b128 v[222:225], v158 offset:49152
	ds_read_b128 v[226:229], v158 offset:50176
	global_load_lds_dwordx4 v[132:133], off
	v_lshl_add_u64 v[132:133], v[248:249], 0, s[36:37]
	s_mov_b32 m0, s5
	s_nop 0
	global_load_lds_dwordx4 v[132:133], off
	s_barrier
	s_waitcnt lgkmcnt(0)
	s_setprio 1
	s_waitcnt lgkmcnt(0)
	v_mfma_f32_16x16x32_bf16 v[64:67], v[182:185], v[198:201], v[64:67]
	v_mfma_f32_16x16x32_bf16 v[60:63], v[190:193], v[198:201], v[60:63]
	v_mfma_f32_16x16x32_bf16 v[56:59], v[182:185], v[206:209], v[56:59]
	v_mfma_f32_16x16x32_bf16 v[52:55], v[190:193], v[206:209], v[52:55]
	v_mfma_f32_16x16x32_bf16 v[48:51], v[182:185], v[214:217], v[48:51]
	v_mfma_f32_16x16x32_bf16 v[44:47], v[190:193], v[214:217], v[44:47]
	v_mfma_f32_16x16x32_bf16 v[40:43], v[182:185], v[222:225], v[40:43]
	v_mfma_f32_16x16x32_bf16 v[36:39], v[190:193], v[222:225], v[36:39]
	v_mfma_f32_16x16x32_bf16 v[64:67], v[186:189], v[202:205], v[64:67]
	v_mfma_f32_16x16x32_bf16 v[60:63], v[194:197], v[202:205], v[60:63]
	v_mfma_f32_16x16x32_bf16 v[56:59], v[186:189], v[210:213], v[56:59]
	v_mfma_f32_16x16x32_bf16 v[52:55], v[194:197], v[210:213], v[52:55]
	v_mfma_f32_16x16x32_bf16 v[48:51], v[186:189], v[218:221], v[48:51]
	v_mfma_f32_16x16x32_bf16 v[44:47], v[194:197], v[218:221], v[44:47]
	v_mfma_f32_16x16x32_bf16 v[40:43], v[186:189], v[226:229], v[40:43]
	v_mfma_f32_16x16x32_bf16 v[36:39], v[194:197], v[226:229], v[36:39]
	s_setprio 0
	s_barrier
	v_readfirstlane_b32 s5, v176
	v_lshl_add_u64 v[132:133], v[250:251], 0, s[38:39]
	s_mov_b32 m0, s5
	v_readfirstlane_b32 s5, v177
	global_load_lds_dwordx4 v[132:133], off
	v_lshl_add_u64 v[132:133], v[252:253], 0, s[38:39]
	s_mov_b32 m0, s5
	s_nop 0
	global_load_lds_dwordx4 v[132:133], off
	s_waitcnt vmcnt(10)
	s_barrier
	s_setprio 1
	v_mfma_f32_16x16x32_bf16 v[32:35], v[230:233], v[198:201], v[32:35]
	v_mfma_f32_16x16x32_bf16 v[28:31], v[238:241], v[198:201], v[28:31]
	v_mfma_f32_16x16x32_bf16 v[24:27], v[230:233], v[206:209], v[24:27]
	v_mfma_f32_16x16x32_bf16 v[20:23], v[238:241], v[206:209], v[20:23]
	v_mfma_f32_16x16x32_bf16 v[16:19], v[230:233], v[214:217], v[16:19]
	v_mfma_f32_16x16x32_bf16 v[12:15], v[238:241], v[214:217], v[12:15]
	v_mfma_f32_16x16x32_bf16 v[8:11], v[230:233], v[222:225], v[8:11]
	v_mfma_f32_16x16x32_bf16 v[4:7], v[238:241], v[222:225], v[4:7]
	v_mfma_f32_16x16x32_bf16 v[32:35], v[234:237], v[202:205], v[32:35]
	v_mfma_f32_16x16x32_bf16 v[28:31], v[242:245], v[202:205], v[28:31]
	v_mfma_f32_16x16x32_bf16 v[24:27], v[234:237], v[210:213], v[24:27]
	v_mfma_f32_16x16x32_bf16 v[20:23], v[242:245], v[210:213], v[20:23]
	v_mfma_f32_16x16x32_bf16 v[16:19], v[234:237], v[218:221], v[16:19]
	v_mfma_f32_16x16x32_bf16 v[12:15], v[242:245], v[218:221], v[12:15]
	v_mfma_f32_16x16x32_bf16 v[8:11], v[234:237], v[226:229], v[8:11]
	v_mfma_f32_16x16x32_bf16 v[4:7], v[242:245], v[226:229], v[4:7]
	s_setprio 0
	s_add_u32 s48, s48, 0x100
	s_addc_u32 s49, s49, 0
	s_cmp_gt_u32 s2, 11
	s_barrier
	s_cbranch_scc1 .LBB0_2802
	s_mov_b32 s2, s4
	s_cmp_lt_i32 s2, 12
	s_cbranch_scc1 .LBB0_2763

.LBB0_2802:
	v_readfirstlane_b32 s2, v0
	v_lshl_add_u64 v[134:135], v[134:135], 0, s[44:45]
	s_mov_b32 m0, s2
	v_readfirstlane_b32 s2, v2
	ds_read_b128 v[138:141], v180
	ds_read_b128 v[142:145], v180 offset:1024
	ds_read_b128 v[172:175], v180 offset:2048
	ds_read_b128 v[180:183], v180 offset:3072
	ds_read_b128 v[184:187], v161
	ds_read_b128 v[188:191], v161 offset:1024
	ds_read_b128 v[192:195], v160
	ds_read_b128 v[196:199], v160 offset:1024
	ds_read_b128 v[200:203], v159
	ds_read_b128 v[204:207], v159 offset:1024
	ds_read_b128 v[208:211], v158
	ds_read_b128 v[212:215], v158 offset:1024
	global_load_lds_dwordx4 v[134:135], off
	v_lshl_add_u64 v[134:135], v[136:137], 0, s[44:45]
	s_mov_b32 m0, s2
	s_nop 0
	global_load_lds_dwordx4 v[134:135], off
	s_waitcnt vmcnt(10)
	s_barrier
	s_waitcnt lgkmcnt(0)
	s_setprio 1
	s_waitcnt lgkmcnt(0)
	v_mfma_f32_16x16x32_bf16 v[128:131], v[138:141], v[184:187], v[128:131]
	v_mfma_f32_16x16x32_bf16 v[124:127], v[172:175], v[184:187], v[124:127]
	v_mfma_f32_16x16x32_bf16 v[120:123], v[138:141], v[192:195], v[120:123]
	v_mfma_f32_16x16x32_bf16 v[116:119], v[172:175], v[192:195], v[116:119]
	v_mfma_f32_16x16x32_bf16 v[112:115], v[138:141], v[200:203], v[112:115]
	v_mfma_f32_16x16x32_bf16 v[108:111], v[172:175], v[200:203], v[108:111]
	v_mfma_f32_16x16x32_bf16 v[104:107], v[138:141], v[208:211], v[104:107]
	v_mfma_f32_16x16x32_bf16 v[100:103], v[172:175], v[208:211], v[100:103]
	v_mfma_f32_16x16x32_bf16 v[128:131], v[142:145], v[188:191], v[128:131]
	v_mfma_f32_16x16x32_bf16 v[124:127], v[180:183], v[188:191], v[124:127]
	v_mfma_f32_16x16x32_bf16 v[120:123], v[142:145], v[196:199], v[120:123]
	v_mfma_f32_16x16x32_bf16 v[116:119], v[180:183], v[196:199], v[116:119]
	v_mfma_f32_16x16x32_bf16 v[112:115], v[142:145], v[204:207], v[112:115]
	v_mfma_f32_16x16x32_bf16 v[108:111], v[180:183], v[204:207], v[108:111]
	v_mfma_f32_16x16x32_bf16 v[104:107], v[142:145], v[212:215], v[104:107]
	v_mfma_f32_16x16x32_bf16 v[100:103], v[180:183], v[212:215], v[100:103]
	s_setprio 0
	s_barrier
	ds_read_b128 v[134:137], v178
	ds_read_b128 v[216:219], v178 offset:1024
	ds_read_b128 v[220:223], v178 offset:2048
	ds_read_b128 v[176:179], v178 offset:3072
	s_waitcnt vmcnt(8)
	s_barrier
	s_waitcnt lgkmcnt(0)
	s_setprio 1
	s_waitcnt lgkmcnt(0)
	v_mfma_f32_16x16x32_bf16 v[96:99], v[134:137], v[184:187], v[96:99]
	v_mfma_f32_16x16x32_bf16 v[92:95], v[220:223], v[184:187], v[92:95]
	v_mfma_f32_16x16x32_bf16 v[88:91], v[134:137], v[192:195], v[88:91]
	v_mfma_f32_16x16x32_bf16 v[84:87], v[220:223], v[192:195], v[84:87]
	v_mfma_f32_16x16x32_bf16 v[80:83], v[134:137], v[200:203], v[80:83]
	v_mfma_f32_16x16x32_bf16 v[76:79], v[220:223], v[200:203], v[76:79]
	v_mfma_f32_16x16x32_bf16 v[72:75], v[134:137], v[208:211], v[72:75]
	v_mfma_f32_16x16x32_bf16 v[68:71], v[220:223], v[208:211], v[68:71]
	v_mfma_f32_16x16x32_bf16 v[96:99], v[216:219], v[188:191], v[96:99]
	v_mfma_f32_16x16x32_bf16 v[92:95], v[176:179], v[188:191], v[92:95]
	v_mfma_f32_16x16x32_bf16 v[88:91], v[216:219], v[196:199], v[88:91]
	v_mfma_f32_16x16x32_bf16 v[84:87], v[176:179], v[196:199], v[84:87]
	v_mfma_f32_16x16x32_bf16 v[80:83], v[216:219], v[204:207], v[80:83]
	v_mfma_f32_16x16x32_bf16 v[76:79], v[176:179], v[204:207], v[76:79]
	v_mfma_f32_16x16x32_bf16 v[72:75], v[216:219], v[212:215], v[72:75]
	v_mfma_f32_16x16x32_bf16 v[68:71], v[176:179], v[212:215], v[68:71]
	s_setprio 0
	s_barrier
	ds_read_b128 v[184:187], v161 offset:16384
	ds_read_b128 v[188:191], v161 offset:17408
	ds_read_b128 v[192:195], v160 offset:16384
	ds_read_b128 v[196:199], v160 offset:17408
	ds_read_b128 v[200:203], v159 offset:16384
	ds_read_b128 v[204:207], v159 offset:17408
	ds_read_b128 v[208:211], v158 offset:16384
	ds_read_b128 v[212:215], v158 offset:17408
	s_waitcnt vmcnt(4)
	s_barrier
	s_waitcnt lgkmcnt(0)
	s_setprio 1
	s_waitcnt lgkmcnt(0)
	v_mfma_f32_16x16x32_bf16 v[64:67], v[138:141], v[184:187], v[64:67]
	v_mfma_f32_16x16x32_bf16 v[56:59], v[138:141], v[192:195], v[56:59]
	v_mfma_f32_16x16x32_bf16 v[48:51], v[138:141], v[200:203], v[48:51]
	v_mfma_f32_16x16x32_bf16 v[40:43], v[138:141], v[208:211], v[40:43]
	v_mfma_f32_16x16x32_bf16 v[36:39], v[172:175], v[208:211], v[36:39]
	v_mfma_f32_16x16x32_bf16 v[224:227], v[142:145], v[188:191], v[64:67]
	v_mfma_f32_16x16x32_bf16 v[60:63], v[172:175], v[184:187], v[60:63]
	v_mfma_f32_16x16x32_bf16 v[232:235], v[142:145], v[196:199], v[56:59]
	v_mfma_f32_16x16x32_bf16 v[52:55], v[172:175], v[192:195], v[52:55]
	v_mfma_f32_16x16x32_bf16 v[240:243], v[142:145], v[204:207], v[48:51]
	v_mfma_f32_16x16x32_bf16 v[44:47], v[172:175], v[200:203], v[44:47]
	v_mfma_f32_16x16x32_bf16 v[138:141], v[142:145], v[212:215], v[40:43]
	v_mfma_f32_16x16x32_bf16 v[142:145], v[180:183], v[212:215], v[36:39]
	v_mfma_f32_16x16x32_bf16 v[228:231], v[180:183], v[188:191], v[60:63]
	v_mfma_f32_16x16x32_bf16 v[236:239], v[180:183], v[196:199], v[52:55]
	v_mfma_f32_16x16x32_bf16 v[244:247], v[180:183], v[204:207], v[44:47]
	s_setprio 0
	s_setprio 1
	v_mfma_f32_16x16x32_bf16 v[8:11], v[134:137], v[208:211], v[8:11]
	v_mfma_f32_16x16x32_bf16 v[32:35], v[134:137], v[184:187], v[32:35]
	v_mfma_f32_16x16x32_bf16 v[28:31], v[220:223], v[184:187], v[28:31]
	v_mfma_f32_16x16x32_bf16 v[24:27], v[134:137], v[192:195], v[24:27]
	v_mfma_f32_16x16x32_bf16 v[20:23], v[220:223], v[192:195], v[20:23]
	v_mfma_f32_16x16x32_bf16 v[16:19], v[134:137], v[200:203], v[16:19]
	v_mfma_f32_16x16x32_bf16 v[12:15], v[220:223], v[200:203], v[12:15]
	v_mfma_f32_16x16x32_bf16 v[134:137], v[216:219], v[212:215], v[8:11]
	v_mfma_f32_16x16x32_bf16 v[2:5], v[220:223], v[208:211], v[4:7]
	v_mfma_f32_16x16x32_bf16 v[172:175], v[216:219], v[188:191], v[32:35]
	v_mfma_f32_16x16x32_bf16 v[180:183], v[176:179], v[188:191], v[28:31]
	v_mfma_f32_16x16x32_bf16 v[184:187], v[216:219], v[196:199], v[24:27]
	v_mfma_f32_16x16x32_bf16 v[188:191], v[176:179], v[196:199], v[20:23]
	v_mfma_f32_16x16x32_bf16 v[192:195], v[216:219], v[204:207], v[16:19]
	v_mfma_f32_16x16x32_bf16 v[196:199], v[176:179], v[204:207], v[12:15]
	v_mfma_f32_16x16x32_bf16 v[176:179], v[176:179], v[212:215], v[2:5]
	s_setprio 0
	s_barrier
	ds_read_b128 v[200:203], v170
	ds_read_b128 v[204:207], v170 offset:1024
	ds_read_b128 v[208:211], v170 offset:2048
	ds_read_b128 v[168:171], v170 offset:3072
	ds_read_b128 v[22:25], v161 offset:32768
	ds_read_b128 v[34:37], v161 offset:33792
	ds_read_b128 v[38:41], v160 offset:32768
	ds_read_b128 v[50:53], v160 offset:33792
	ds_read_b128 v[54:57], v159 offset:32768
	ds_read_b128 v[58:61], v159 offset:33792
	ds_read_b128 v[62:65], v158 offset:32768
	ds_read_b128 v[212:215], v158 offset:33792
	s_waitcnt vmcnt(2)
	s_barrier
	s_waitcnt lgkmcnt(0)
	s_setprio 1
	s_waitcnt lgkmcnt(0)
	v_mfma_f32_16x16x32_bf16 v[18:21], v[200:203], v[54:57], v[112:115]
	v_mfma_f32_16x16x32_bf16 v[26:29], v[204:207], v[58:61], v[18:21]
	v_mfma_f32_16x16x32_bf16 v[18:21], v[208:211], v[54:57], v[108:111]
	v_mfma_f32_16x16x32_bf16 v[30:33], v[168:171], v[58:61], v[18:21]
	v_mfma_f32_16x16x32_bf16 v[18:21], v[200:203], v[62:65], v[104:107]
	v_mfma_f32_16x16x32_bf16 v[2:5], v[200:203], v[22:25], v[128:131]
	v_mfma_f32_16x16x32_bf16 v[6:9], v[208:211], v[22:25], v[124:127]
	v_mfma_f32_16x16x32_bf16 v[10:13], v[200:203], v[38:41], v[120:123]
	v_mfma_f32_16x16x32_bf16 v[14:17], v[208:211], v[38:41], v[116:119]
	v_mfma_f32_16x16x32_bf16 v[42:45], v[204:207], v[212:215], v[18:21]
	v_mfma_f32_16x16x32_bf16 v[18:21], v[208:211], v[62:65], v[100:103]
	v_mfma_f32_16x16x32_bf16 v[2:5], v[204:207], v[34:37], v[2:5]
	v_mfma_f32_16x16x32_bf16 v[6:9], v[168:171], v[34:37], v[6:9]
	v_mfma_f32_16x16x32_bf16 v[10:13], v[204:207], v[50:53], v[10:13]
	v_mfma_f32_16x16x32_bf16 v[14:17], v[168:171], v[50:53], v[14:17]
	v_mfma_f32_16x16x32_bf16 v[46:49], v[168:171], v[212:215], v[18:21]
	s_setprio 0
	s_barrier
	ds_read_b128 v[122:125], v167
	ds_read_b128 v[126:129], v167 offset:1024
	ds_read_b128 v[216:219], v167 offset:2048
	ds_read_b128 v[220:223], v167 offset:3072
	s_waitcnt vmcnt(0)
	s_barrier
	s_waitcnt lgkmcnt(0)
	s_setprio 1
	s_waitcnt lgkmcnt(0)
	v_mfma_f32_16x16x32_bf16 v[18:21], v[122:125], v[22:25], v[96:99]
	v_mfma_f32_16x16x32_bf16 v[22:25], v[216:219], v[22:25], v[92:95]
	v_mfma_f32_16x16x32_bf16 v[18:21], v[126:129], v[34:37], v[18:21]
	v_mfma_f32_16x16x32_bf16 v[22:25], v[220:223], v[34:37], v[22:25]
	v_mfma_f32_16x16x32_bf16 v[34:37], v[122:125], v[38:41], v[88:91]
	v_mfma_f32_16x16x32_bf16 v[38:41], v[216:219], v[38:41], v[84:87]
	v_mfma_f32_16x16x32_bf16 v[34:37], v[126:129], v[50:53], v[34:37]
	v_mfma_f32_16x16x32_bf16 v[38:41], v[220:223], v[50:53], v[38:41]
	v_mfma_f32_16x16x32_bf16 v[50:53], v[122:125], v[54:57], v[80:83]
	v_mfma_f32_16x16x32_bf16 v[54:57], v[216:219], v[54:57], v[76:79]
	v_mfma_f32_16x16x32_bf16 v[50:53], v[126:129], v[58:61], v[50:53]
	v_mfma_f32_16x16x32_bf16 v[54:57], v[220:223], v[58:61], v[54:57]
	v_mfma_f32_16x16x32_bf16 v[58:61], v[122:125], v[62:65], v[72:75]
	v_mfma_f32_16x16x32_bf16 v[62:65], v[216:219], v[62:65], v[68:71]
	v_mfma_f32_16x16x32_bf16 v[58:61], v[126:129], v[212:215], v[58:61]
	v_mfma_f32_16x16x32_bf16 v[62:65], v[220:223], v[212:215], v[62:65]
	s_setprio 0
	s_barrier
	ds_read_b128 v[86:89], v161 offset:49152
	ds_read_b128 v[94:97], v161 offset:50176
	ds_read_b128 v[102:105], v160 offset:49152
	ds_read_b128 v[110:113], v160 offset:50176
	ds_read_b128 v[118:121], v159 offset:49152
	ds_read_b128 v[160:163], v159 offset:50176
	ds_read_b128 v[212:215], v158 offset:49152
	ds_read_b128 v[248:251], v158 offset:50176
	s_barrier
	s_waitcnt lgkmcnt(0)
	s_setprio 1
	s_waitcnt lgkmcnt(0)
	v_mfma_f32_16x16x32_bf16 v[78:81], v[208:211], v[102:105], v[236:239]
	v_mfma_f32_16x16x32_bf16 v[82:85], v[168:171], v[110:113], v[78:81]
	v_mfma_f32_16x16x32_bf16 v[78:81], v[200:203], v[118:121], v[240:243]
	v_mfma_f32_16x16x32_bf16 v[90:93], v[204:207], v[160:163], v[78:81]
	v_mfma_f32_16x16x32_bf16 v[78:81], v[208:211], v[118:121], v[244:247]
	v_mfma_f32_16x16x32_bf16 v[98:101], v[168:171], v[160:163], v[78:81]
	v_mfma_f32_16x16x32_bf16 v[78:81], v[200:203], v[212:215], v[138:141]
	v_mfma_f32_16x16x32_bf16 v[66:69], v[200:203], v[86:89], v[224:227]
	v_mfma_f32_16x16x32_bf16 v[70:73], v[208:211], v[86:89], v[228:231]
	v_mfma_f32_16x16x32_bf16 v[74:77], v[200:203], v[102:105], v[232:235]
	v_mfma_f32_16x16x32_bf16 v[106:109], v[204:207], v[248:251], v[78:81]
	v_mfma_f32_16x16x32_bf16 v[78:81], v[208:211], v[212:215], v[142:145]
	v_mfma_f32_16x16x32_bf16 v[66:69], v[204:207], v[94:97], v[66:69]
	v_mfma_f32_16x16x32_bf16 v[70:73], v[168:171], v[94:97], v[70:73]
	v_mfma_f32_16x16x32_bf16 v[74:77], v[204:207], v[110:113], v[74:77]
	v_mfma_f32_16x16x32_bf16 v[114:117], v[168:171], v[248:251], v[78:81]
	s_setprio 0
	s_setprio 1
	v_mfma_f32_16x16x32_bf16 v[78:81], v[122:125], v[86:89], v[172:175]
	v_mfma_f32_16x16x32_bf16 v[86:89], v[216:219], v[86:89], v[180:183]
	v_mfma_f32_16x16x32_bf16 v[78:81], v[126:129], v[94:97], v[78:81]
	v_mfma_f32_16x16x32_bf16 v[86:89], v[220:223], v[94:97], v[86:89]
	v_mfma_f32_16x16x32_bf16 v[94:97], v[122:125], v[102:105], v[184:187]
	v_mfma_f32_16x16x32_bf16 v[102:105], v[216:219], v[102:105], v[188:191]
	v_mfma_f32_16x16x32_bf16 v[94:97], v[126:129], v[110:113], v[94:97]
	v_mfma_f32_16x16x32_bf16 v[102:105], v[220:223], v[110:113], v[102:105]
	v_mfma_f32_16x16x32_bf16 v[110:113], v[122:125], v[118:121], v[192:195]
	v_mfma_f32_16x16x32_bf16 v[122:125], v[122:125], v[212:215], v[134:137]
	v_mfma_f32_16x16x32_bf16 v[110:113], v[126:129], v[160:163], v[110:113]
	v_mfma_f32_16x16x32_bf16 v[118:121], v[216:219], v[118:121], v[196:199]
	v_mfma_f32_16x16x32_bf16 v[122:125], v[126:129], v[248:251], v[122:125]
	v_mfma_f32_16x16x32_bf16 v[126:129], v[216:219], v[212:215], v[176:179]
	v_mfma_f32_16x16x32_bf16 v[118:121], v[220:223], v[160:163], v[118:121]
	v_mfma_f32_16x16x32_bf16 v[126:129], v[220:223], v[248:251], v[126:129]
	s_setprio 0
	v_and_b32_e32 v0, 0xffffff00, v149
	v_lshlrev_b32_e32 v130, 2, v155
	v_add3_u32 v131, s67, v0, v130
	v_add3_u32 v0, s68, v0, v130
	s_barrier
	ds_read2_b32 v[136:137], v131 offset1:16
	ds_read2_b32 v[138:139], v131 offset0:32 offset1:48
	ds_read2_b32 v[142:143], v0 offset1:16
	ds_read2_b32 v[146:147], v0 offset0:32 offset1:48
	v_cmp_gt_u32_e32 vcc, s60, v149
	s_waitcnt lgkmcnt(0)
	v_mov_b32_e32 v0, v137
	v_mov_b32_e32 v140, v139
	v_mov_b32_e32 v144, v143
	v_mov_b32_e32 v134, v147
	s_and_saveexec_b64 s[6:7], vcc
	s_cbranch_execz .LBB0_2757
	s_barrier
	s_branch .LBB0_2757

.LBB0_2916:
	ds_read_b128 v[180:183], v172
	ds_read_b128 v[184:187], v172 offset:1024
	ds_read_b128 v[188:191], v172 offset:2048
	ds_read_b128 v[192:195], v172 offset:3072
	v_add_u32_e32 v178, 0xc000, v152
	v_lshl_add_u64 v[244:245], s[6:7], 0, v[146:147]
	v_readfirstlane_b32 s4, v178
	v_add_u32_e32 v179, 0xe000, v152
	v_lshl_add_u64 v[224:225], v[244:245], 0, s[12:13]
	s_mov_b32 m0, s4
	v_lshl_add_u64 v[246:247], s[6:7], 0, v[148:149]
	v_readfirstlane_b32 s4, v179
	ds_read_b128 v[174:177], v161
	ds_read_b128 v[196:199], v161 offset:1024
	ds_read_b128 v[200:203], v160
	ds_read_b128 v[204:207], v160 offset:1024
	ds_read_b128 v[208:211], v159
	ds_read_b128 v[212:215], v159 offset:1024
	ds_read_b128 v[216:219], v158
	ds_read_b128 v[220:223], v158 offset:1024
	global_load_lds_dwordx4 v[224:225], off
	v_lshl_add_u64 v[224:225], v[246:247], 0, s[12:13]
	s_mov_b32 m0, s4
	s_nop 0
	global_load_lds_dwordx4 v[224:225], off
	s_waitcnt vmcnt(10)
	s_waitcnt lgkmcnt(8)
	s_barrier
	s_waitcnt lgkmcnt(0)
	s_setprio 1
	s_waitcnt lgkmcnt(0)
	v_mfma_f32_16x16x32_bf16 v[124:127], v[180:183], v[174:177], v[124:127]
	v_mfma_f32_16x16x32_bf16 v[120:123], v[188:191], v[174:177], v[120:123]
	v_mfma_f32_16x16x32_bf16 v[116:119], v[180:183], v[200:203], v[116:119]
	v_mfma_f32_16x16x32_bf16 v[112:115], v[188:191], v[200:203], v[112:115]
	v_mfma_f32_16x16x32_bf16 v[108:111], v[180:183], v[208:211], v[108:111]
	v_mfma_f32_16x16x32_bf16 v[104:107], v[188:191], v[208:211], v[104:107]
	v_mfma_f32_16x16x32_bf16 v[100:103], v[180:183], v[216:219], v[100:103]
	v_mfma_f32_16x16x32_bf16 v[96:99], v[188:191], v[216:219], v[96:99]
	v_mfma_f32_16x16x32_bf16 v[124:127], v[184:187], v[196:199], v[124:127]
	v_mfma_f32_16x16x32_bf16 v[120:123], v[192:195], v[196:199], v[120:123]
	v_mfma_f32_16x16x32_bf16 v[116:119], v[184:187], v[204:207], v[116:119]
	v_mfma_f32_16x16x32_bf16 v[112:115], v[192:195], v[204:207], v[112:115]
	v_mfma_f32_16x16x32_bf16 v[108:111], v[184:187], v[212:215], v[108:111]
	v_mfma_f32_16x16x32_bf16 v[104:107], v[192:195], v[212:215], v[104:107]
	v_mfma_f32_16x16x32_bf16 v[100:103], v[184:187], v[220:223], v[100:103]
	v_mfma_f32_16x16x32_bf16 v[96:99], v[192:195], v[220:223], v[96:99]
	s_setprio 0
	s_barrier
	v_lshl_add_u64 v[248:249], s[6:7], 0, v[142:143]
	v_readfirstlane_b32 s4, v153
	v_add_u32_e32 v173, 0x2000, v153
	v_lshl_add_u64 v[240:241], v[248:249], 0, s[14:15]
	s_mov_b32 m0, s4
	v_lshl_add_u64 v[250:251], s[6:7], 0, v[144:145]
	v_readfirstlane_b32 s4, v173
	ds_read_b128 v[224:227], v168
	ds_read_b128 v[228:231], v168 offset:1024
	ds_read_b128 v[232:235], v168 offset:2048
	ds_read_b128 v[236:239], v168 offset:3072
	global_load_lds_dwordx4 v[240:241], off
	v_lshl_add_u64 v[240:241], v[250:251], 0, s[14:15]
	s_mov_b32 m0, s4
	s_nop 0
	global_load_lds_dwordx4 v[240:241], off
	s_waitcnt vmcnt(10)
	s_barrier
	s_waitcnt lgkmcnt(0)
	s_setprio 1
	s_waitcnt lgkmcnt(0)
	v_mfma_f32_16x16x32_bf16 v[92:95], v[224:227], v[174:177], v[92:95]
	v_mfma_f32_16x16x32_bf16 v[88:91], v[232:235], v[174:177], v[88:91]
	v_mfma_f32_16x16x32_bf16 v[84:87], v[224:227], v[200:203], v[84:87]
	v_mfma_f32_16x16x32_bf16 v[80:83], v[232:235], v[200:203], v[80:83]
	v_mfma_f32_16x16x32_bf16 v[76:79], v[224:227], v[208:211], v[76:79]
	v_mfma_f32_16x16x32_bf16 v[72:75], v[232:235], v[208:211], v[72:75]
	v_mfma_f32_16x16x32_bf16 v[68:71], v[224:227], v[216:219], v[68:71]
	v_mfma_f32_16x16x32_bf16 v[64:67], v[232:235], v[216:219], v[64:67]
	v_mfma_f32_16x16x32_bf16 v[92:95], v[228:231], v[196:199], v[92:95]
	v_mfma_f32_16x16x32_bf16 v[88:91], v[236:239], v[196:199], v[88:91]
	v_mfma_f32_16x16x32_bf16 v[84:87], v[228:231], v[204:207], v[84:87]
	v_mfma_f32_16x16x32_bf16 v[80:83], v[236:239], v[204:207], v[80:83]
	v_mfma_f32_16x16x32_bf16 v[76:79], v[228:231], v[212:215], v[76:79]
	v_mfma_f32_16x16x32_bf16 v[72:75], v[236:239], v[212:215], v[72:75]
	v_mfma_f32_16x16x32_bf16 v[68:71], v[228:231], v[220:223], v[68:71]
	v_mfma_f32_16x16x32_bf16 v[64:67], v[236:239], v[220:223], v[64:67]
	s_setprio 0
	v_readfirstlane_b32 s4, v152
	v_lshl_add_u64 v[174:175], v[244:245], 0, s[16:17]
	s_mov_b32 m0, s4
	s_barrier
	ds_read_b128 v[196:199], v161 offset:16384
	ds_read_b128 v[200:203], v161 offset:17408
	ds_read_b128 v[204:207], v160 offset:16384
	ds_read_b128 v[208:211], v160 offset:17408
	ds_read_b128 v[212:215], v159 offset:16384
	ds_read_b128 v[216:219], v159 offset:17408
	ds_read_b128 v[220:223], v158 offset:16384
	ds_read_b128 v[240:243], v158 offset:17408
	global_load_lds_dwordx4 v[174:175], off
	v_add_u32_e32 v174, 0x2000, v152
	v_lshl_add_u64 v[176:177], v[246:247], 0, s[16:17]
	v_readfirstlane_b32 s4, v174
	s_mov_b32 m0, s4
	s_nop 0
	global_load_lds_dwordx4 v[176:177], off
	s_barrier
	s_waitcnt lgkmcnt(0)
	s_setprio 1
	s_waitcnt lgkmcnt(0)
	v_mfma_f32_16x16x32_bf16 v[60:63], v[180:183], v[196:199], v[60:63]
	v_mfma_f32_16x16x32_bf16 v[56:59], v[188:191], v[196:199], v[56:59]
	v_mfma_f32_16x16x32_bf16 v[52:55], v[180:183], v[204:207], v[52:55]
	v_mfma_f32_16x16x32_bf16 v[48:51], v[188:191], v[204:207], v[48:51]
	v_mfma_f32_16x16x32_bf16 v[44:47], v[180:183], v[212:215], v[44:47]
	v_mfma_f32_16x16x32_bf16 v[40:43], v[188:191], v[212:215], v[40:43]
	v_mfma_f32_16x16x32_bf16 v[36:39], v[180:183], v[220:223], v[36:39]
	v_mfma_f32_16x16x32_bf16 v[32:35], v[188:191], v[220:223], v[32:35]
	v_mfma_f32_16x16x32_bf16 v[60:63], v[184:187], v[200:203], v[60:63]
	v_mfma_f32_16x16x32_bf16 v[56:59], v[192:195], v[200:203], v[56:59]
	v_mfma_f32_16x16x32_bf16 v[52:55], v[184:187], v[208:211], v[52:55]
	v_mfma_f32_16x16x32_bf16 v[48:51], v[192:195], v[208:211], v[48:51]
	v_mfma_f32_16x16x32_bf16 v[44:47], v[184:187], v[216:219], v[44:47]
	v_mfma_f32_16x16x32_bf16 v[40:43], v[192:195], v[216:219], v[40:43]
	v_mfma_f32_16x16x32_bf16 v[36:39], v[184:187], v[240:243], v[36:39]
	v_mfma_f32_16x16x32_bf16 v[32:35], v[192:195], v[240:243], v[32:35]
	s_setprio 0
	s_barrier
	v_readfirstlane_b32 s4, v151
	v_add_u32_e32 v175, 0x2000, v151
	v_lshl_add_u64 v[176:177], v[248:249], 0, s[18:19]
	s_mov_b32 m0, s4
	v_readfirstlane_b32 s4, v175
	global_load_lds_dwordx4 v[176:177], off
	v_lshl_add_u64 v[176:177], v[250:251], 0, s[18:19]
	s_mov_b32 m0, s4
	s_nop 0
	global_load_lds_dwordx4 v[176:177], off
	s_waitcnt vmcnt(10)
	s_barrier
	s_setprio 1
	v_mfma_f32_16x16x32_bf16 v[28:31], v[224:227], v[196:199], v[28:31]
	v_mfma_f32_16x16x32_bf16 v[24:27], v[232:235], v[196:199], v[24:27]
	v_mfma_f32_16x16x32_bf16 v[20:23], v[224:227], v[204:207], v[20:23]
	v_mfma_f32_16x16x32_bf16 v[16:19], v[232:235], v[204:207], v[16:19]
	v_mfma_f32_16x16x32_bf16 v[12:15], v[224:227], v[212:215], v[12:15]
	v_mfma_f32_16x16x32_bf16 v[8:11], v[232:235], v[212:215], v[8:11]
	v_mfma_f32_16x16x32_bf16 v[4:7], v[224:227], v[220:223], v[4:7]
	v_mfma_f32_16x16x32_bf16 v[0:3], v[232:235], v[220:223], v[0:3]
	v_mfma_f32_16x16x32_bf16 v[28:31], v[228:231], v[200:203], v[28:31]
	v_mfma_f32_16x16x32_bf16 v[24:27], v[236:239], v[200:203], v[24:27]
	v_mfma_f32_16x16x32_bf16 v[20:23], v[228:231], v[208:211], v[20:23]
	v_mfma_f32_16x16x32_bf16 v[16:19], v[236:239], v[208:211], v[16:19]
	v_mfma_f32_16x16x32_bf16 v[12:15], v[228:231], v[216:219], v[12:15]
	v_mfma_f32_16x16x32_bf16 v[8:11], v[236:239], v[216:219], v[8:11]
	v_mfma_f32_16x16x32_bf16 v[4:7], v[228:231], v[240:243], v[4:7]
	v_mfma_f32_16x16x32_bf16 v[0:3], v[236:239], v[240:243], v[0:3]
	s_setprio 0
	s_barrier
	ds_read_b128 v[180:183], v163
	ds_read_b128 v[184:187], v163 offset:1024
	ds_read_b128 v[188:191], v163 offset:2048
	ds_read_b128 v[192:195], v163 offset:3072
	v_add_u32_e32 v176, 0x4000, v152
	v_add_u32_e32 v177, 0x6000, v152
	v_readfirstlane_b32 s4, v176
	v_lshl_add_u64 v[228:229], v[244:245], 0, s[20:21]
	s_mov_b32 m0, s4
	v_readfirstlane_b32 s4, v177
	ds_read_b128 v[196:199], v161 offset:32768
	ds_read_b128 v[200:203], v161 offset:33792
	ds_read_b128 v[204:207], v160 offset:32768
	ds_read_b128 v[208:211], v160 offset:33792
	ds_read_b128 v[212:215], v159 offset:32768
	ds_read_b128 v[216:219], v159 offset:33792
	ds_read_b128 v[220:223], v158 offset:32768
	ds_read_b128 v[224:227], v158 offset:33792
	global_load_lds_dwordx4 v[228:229], off
	v_lshl_add_u64 v[228:229], v[246:247], 0, s[20:21]
	s_mov_b32 m0, s4
	s_nop 0
	global_load_lds_dwordx4 v[228:229], off
	s_waitcnt vmcnt(10)
	s_waitcnt lgkmcnt(8)
	s_barrier
	s_waitcnt lgkmcnt(0)
	s_setprio 1
	s_waitcnt lgkmcnt(0)
	v_mfma_f32_16x16x32_bf16 v[124:127], v[180:183], v[196:199], v[124:127]
	v_mfma_f32_16x16x32_bf16 v[120:123], v[188:191], v[196:199], v[120:123]
	v_mfma_f32_16x16x32_bf16 v[116:119], v[180:183], v[204:207], v[116:119]
	v_mfma_f32_16x16x32_bf16 v[112:115], v[188:191], v[204:207], v[112:115]
	v_mfma_f32_16x16x32_bf16 v[108:111], v[180:183], v[212:215], v[108:111]
	v_mfma_f32_16x16x32_bf16 v[104:107], v[188:191], v[212:215], v[104:107]
	v_mfma_f32_16x16x32_bf16 v[100:103], v[180:183], v[220:223], v[100:103]
	v_mfma_f32_16x16x32_bf16 v[96:99], v[188:191], v[220:223], v[96:99]
	v_mfma_f32_16x16x32_bf16 v[124:127], v[184:187], v[200:203], v[124:127]
	v_mfma_f32_16x16x32_bf16 v[120:123], v[192:195], v[200:203], v[120:123]
	v_mfma_f32_16x16x32_bf16 v[116:119], v[184:187], v[208:211], v[116:119]
	v_mfma_f32_16x16x32_bf16 v[112:115], v[192:195], v[208:211], v[112:115]
	v_mfma_f32_16x16x32_bf16 v[108:111], v[184:187], v[216:219], v[108:111]
	v_mfma_f32_16x16x32_bf16 v[104:107], v[192:195], v[216:219], v[104:107]
	v_mfma_f32_16x16x32_bf16 v[100:103], v[184:187], v[224:227], v[100:103]
	v_mfma_f32_16x16x32_bf16 v[96:99], v[192:195], v[224:227], v[96:99]
	s_setprio 0
	s_barrier
	v_readfirstlane_b32 s4, v167
	v_add_u32_e32 v254, 0x2000, v167
	v_lshl_add_u64 v[252:253], v[248:249], 0, s[24:25]
	s_mov_b32 m0, s4
	v_readfirstlane_b32 s4, v254
	ds_read_b128 v[228:231], v162
	ds_read_b128 v[232:235], v162 offset:1024
	ds_read_b128 v[236:239], v162 offset:2048
	ds_read_b128 v[240:243], v162 offset:3072
	global_load_lds_dwordx4 v[252:253], off
	v_lshl_add_u64 v[252:253], v[250:251], 0, s[24:25]
	s_mov_b32 m0, s4
	s_nop 0
	global_load_lds_dwordx4 v[252:253], off
	s_waitcnt vmcnt(10)
	s_barrier
	s_waitcnt lgkmcnt(0)
	s_setprio 1
	s_waitcnt lgkmcnt(0)
	v_mfma_f32_16x16x32_bf16 v[92:95], v[228:231], v[196:199], v[92:95]
	v_mfma_f32_16x16x32_bf16 v[88:91], v[236:239], v[196:199], v[88:91]
	v_mfma_f32_16x16x32_bf16 v[84:87], v[228:231], v[204:207], v[84:87]
	v_mfma_f32_16x16x32_bf16 v[80:83], v[236:239], v[204:207], v[80:83]
	v_mfma_f32_16x16x32_bf16 v[76:79], v[228:231], v[212:215], v[76:79]
	v_mfma_f32_16x16x32_bf16 v[72:75], v[236:239], v[212:215], v[72:75]
	v_mfma_f32_16x16x32_bf16 v[68:71], v[228:231], v[220:223], v[68:71]
	v_mfma_f32_16x16x32_bf16 v[64:67], v[236:239], v[220:223], v[64:67]
	v_mfma_f32_16x16x32_bf16 v[92:95], v[232:235], v[200:203], v[92:95]
	v_mfma_f32_16x16x32_bf16 v[88:91], v[240:243], v[200:203], v[88:91]
	v_mfma_f32_16x16x32_bf16 v[84:87], v[232:235], v[208:211], v[84:87]
	v_mfma_f32_16x16x32_bf16 v[80:83], v[240:243], v[208:211], v[80:83]
	v_mfma_f32_16x16x32_bf16 v[76:79], v[232:235], v[216:219], v[76:79]
	v_mfma_f32_16x16x32_bf16 v[72:75], v[240:243], v[216:219], v[72:75]
	v_mfma_f32_16x16x32_bf16 v[68:71], v[232:235], v[224:227], v[68:71]
	v_mfma_f32_16x16x32_bf16 v[64:67], v[240:243], v[224:227], v[64:67]
	s_setprio 0
	v_readfirstlane_b32 s4, v169
	v_lshl_add_u64 v[244:245], v[244:245], 0, s[26:27]
	s_mov_b32 m0, s4
	v_readfirstlane_b32 s4, v170
	s_barrier
	ds_read_b128 v[196:199], v161 offset:49152
	ds_read_b128 v[200:203], v161 offset:50176
	ds_read_b128 v[204:207], v160 offset:49152
	ds_read_b128 v[208:211], v160 offset:50176
	ds_read_b128 v[212:215], v159 offset:49152
	ds_read_b128 v[216:219], v159 offset:50176
	ds_read_b128 v[220:223], v158 offset:49152
	ds_read_b128 v[224:227], v158 offset:50176
	global_load_lds_dwordx4 v[244:245], off
	v_lshl_add_u64 v[244:245], v[246:247], 0, s[26:27]
	s_mov_b32 m0, s4
	s_nop 0
	global_load_lds_dwordx4 v[244:245], off
	s_barrier
	s_waitcnt lgkmcnt(0)
	s_setprio 1
	s_waitcnt lgkmcnt(0)
	v_mfma_f32_16x16x32_bf16 v[60:63], v[180:183], v[196:199], v[60:63]
	v_mfma_f32_16x16x32_bf16 v[56:59], v[188:191], v[196:199], v[56:59]
	v_mfma_f32_16x16x32_bf16 v[52:55], v[180:183], v[204:207], v[52:55]
	v_mfma_f32_16x16x32_bf16 v[48:51], v[188:191], v[204:207], v[48:51]
	v_mfma_f32_16x16x32_bf16 v[44:47], v[180:183], v[212:215], v[44:47]
	v_mfma_f32_16x16x32_bf16 v[40:43], v[188:191], v[212:215], v[40:43]
	v_mfma_f32_16x16x32_bf16 v[36:39], v[180:183], v[220:223], v[36:39]
	v_mfma_f32_16x16x32_bf16 v[32:35], v[188:191], v[220:223], v[32:35]
	v_mfma_f32_16x16x32_bf16 v[60:63], v[184:187], v[200:203], v[60:63]
	v_mfma_f32_16x16x32_bf16 v[56:59], v[192:195], v[200:203], v[56:59]
	v_mfma_f32_16x16x32_bf16 v[52:55], v[184:187], v[208:211], v[52:55]
	v_mfma_f32_16x16x32_bf16 v[48:51], v[192:195], v[208:211], v[48:51]
	v_mfma_f32_16x16x32_bf16 v[44:47], v[184:187], v[216:219], v[44:47]
	v_mfma_f32_16x16x32_bf16 v[40:43], v[192:195], v[216:219], v[40:43]
	v_mfma_f32_16x16x32_bf16 v[36:39], v[184:187], v[224:227], v[36:39]
	v_mfma_f32_16x16x32_bf16 v[32:35], v[192:195], v[224:227], v[32:35]
	s_setprio 0
	s_barrier
	v_readfirstlane_b32 s4, v171
	v_add_u32_e32 v182, 0x2000, v171
	v_lshl_add_u64 v[180:181], v[248:249], 0, s[28:29]
	s_mov_b32 m0, s4
	v_readfirstlane_b32 s4, v182
	global_load_lds_dwordx4 v[180:181], off
	v_lshl_add_u64 v[180:181], v[250:251], 0, s[28:29]
	s_mov_b32 m0, s4
	s_nop 0
	global_load_lds_dwordx4 v[180:181], off
	s_waitcnt vmcnt(10)
	s_barrier
	s_setprio 1
	v_mfma_f32_16x16x32_bf16 v[28:31], v[228:231], v[196:199], v[28:31]
	v_mfma_f32_16x16x32_bf16 v[24:27], v[236:239], v[196:199], v[24:27]
	v_mfma_f32_16x16x32_bf16 v[20:23], v[228:231], v[204:207], v[20:23]
	v_mfma_f32_16x16x32_bf16 v[16:19], v[236:239], v[204:207], v[16:19]
	v_mfma_f32_16x16x32_bf16 v[12:15], v[228:231], v[212:215], v[12:15]
	v_mfma_f32_16x16x32_bf16 v[8:11], v[236:239], v[212:215], v[8:11]
	v_mfma_f32_16x16x32_bf16 v[4:7], v[228:231], v[220:223], v[4:7]
	v_mfma_f32_16x16x32_bf16 v[0:3], v[236:239], v[220:223], v[0:3]
	v_mfma_f32_16x16x32_bf16 v[28:31], v[232:235], v[200:203], v[28:31]
	v_mfma_f32_16x16x32_bf16 v[24:27], v[240:243], v[200:203], v[24:27]
	v_mfma_f32_16x16x32_bf16 v[20:23], v[232:235], v[208:211], v[20:23]
	v_mfma_f32_16x16x32_bf16 v[16:19], v[240:243], v[208:211], v[16:19]
	v_mfma_f32_16x16x32_bf16 v[12:15], v[232:235], v[216:219], v[12:15]
	v_mfma_f32_16x16x32_bf16 v[8:11], v[240:243], v[216:219], v[8:11]
	v_mfma_f32_16x16x32_bf16 v[4:7], v[232:235], v[224:227], v[4:7]
	v_mfma_f32_16x16x32_bf16 v[0:3], v[240:243], v[224:227], v[0:3]
	s_setprio 0
	s_add_i32 s2, s2, 2
	v_lshl_add_u64 v[142:143], v[142:143], 0, s[30:31]
	v_lshl_add_u64 v[144:145], v[144:145], 0, s[30:31]
	v_lshl_add_u64 v[146:147], v[146:147], 0, s[30:31]
	s_cmp_lt_u32 s2, 12
	v_lshl_add_u64 v[148:149], v[148:149], 0, s[30:31]
	s_barrier
	s_cbranch_scc1 .LBB0_2916
	s_or_b32 s4, s36, 0x80
	s_ashr_i32 s5, s4, 31
	s_lshl_b64 s[4:5], s[4:5], 11
	s_add_u32 s4, s1, s4
	s_addc_u32 s5, s23, s5
	v_lshl_add_u64 v[170:171], s[4:5], 0, v[130:131]
	v_lshl_add_u64 v[138:139], v[138:139], 1, v[170:171]
	v_readfirstlane_b32 s2, v178
	v_lshl_add_u64 v[138:139], v[138:139], 0, s[34:35]
	s_mov_b32 m0, s2
	ds_read_b128 v[142:145], v172
	ds_read_b128 v[146:149], v172 offset:1024
	ds_read_b128 v[180:183], v172 offset:2048
	ds_read_b128 v[184:187], v172 offset:3072
	ds_read_b128 v[188:191], v161
	ds_read_b128 v[192:195], v161 offset:1024
	ds_read_b128 v[196:199], v160
	ds_read_b128 v[200:203], v160 offset:1024
	ds_read_b128 v[204:207], v159
	ds_read_b128 v[208:211], v159 offset:1024
	ds_read_b128 v[212:215], v158
	ds_read_b128 v[216:219], v158 offset:1024
	global_load_lds_dwordx4 v[138:139], off
	v_lshl_add_u64 v[138:139], s[4:5], 0, v[134:135]
	v_lshl_add_u64 v[138:139], v[140:141], 1, v[138:139]
	v_readfirstlane_b32 s2, v179
	v_lshl_add_u64 v[138:139], v[138:139], 0, s[34:35]
	s_mov_b32 m0, s2
	v_readlane_b32 s2, v255, 11
	global_load_lds_dwordx4 v[138:139], off
	s_waitcnt vmcnt(10)
	s_add_i32 s60, s60, s2
	s_barrier
	s_waitcnt lgkmcnt(0)
	s_cmpk_gt_i32 s60, 0x7f
	s_cselect_b64 s[38:39], -1, 0
	s_setprio 1
	s_waitcnt lgkmcnt(0)
	v_mfma_f32_16x16x32_bf16 v[124:127], v[142:145], v[188:191], v[124:127]
	v_mfma_f32_16x16x32_bf16 v[120:123], v[180:183], v[188:191], v[120:123]
	v_mfma_f32_16x16x32_bf16 v[116:119], v[142:145], v[196:199], v[116:119]
	v_mfma_f32_16x16x32_bf16 v[112:115], v[180:183], v[196:199], v[112:115]
	v_mfma_f32_16x16x32_bf16 v[108:111], v[142:145], v[204:207], v[108:111]
	v_mfma_f32_16x16x32_bf16 v[104:107], v[180:183], v[204:207], v[104:107]
	v_mfma_f32_16x16x32_bf16 v[100:103], v[142:145], v[212:215], v[100:103]
	v_mfma_f32_16x16x32_bf16 v[96:99], v[180:183], v[212:215], v[96:99]
	v_mfma_f32_16x16x32_bf16 v[124:127], v[146:149], v[192:195], v[124:127]
	v_mfma_f32_16x16x32_bf16 v[120:123], v[184:187], v[192:195], v[120:123]
	v_mfma_f32_16x16x32_bf16 v[116:119], v[146:149], v[200:203], v[116:119]
	v_mfma_f32_16x16x32_bf16 v[112:115], v[184:187], v[200:203], v[112:115]
	v_mfma_f32_16x16x32_bf16 v[108:111], v[146:149], v[208:211], v[108:111]
	v_mfma_f32_16x16x32_bf16 v[104:107], v[184:187], v[208:211], v[104:107]
	v_mfma_f32_16x16x32_bf16 v[100:103], v[146:149], v[216:219], v[100:103]
	v_mfma_f32_16x16x32_bf16 v[96:99], v[184:187], v[216:219], v[96:99]
	s_setprio 0
	s_barrier
	ds_read_b128 v[138:141], v168
	ds_read_b128 v[220:223], v168 offset:1024
	ds_read_b128 v[224:227], v168 offset:2048
	ds_read_b128 v[168:171], v168 offset:3072
	s_waitcnt vmcnt(8)
	s_barrier
	s_waitcnt lgkmcnt(0)
	s_setprio 1
	s_waitcnt lgkmcnt(0)
	v_mfma_f32_16x16x32_bf16 v[92:95], v[138:141], v[188:191], v[92:95]
	v_mfma_f32_16x16x32_bf16 v[88:91], v[224:227], v[188:191], v[88:91]
	v_mfma_f32_16x16x32_bf16 v[84:87], v[138:141], v[196:199], v[84:87]
	v_mfma_f32_16x16x32_bf16 v[80:83], v[224:227], v[196:199], v[80:83]
	v_mfma_f32_16x16x32_bf16 v[76:79], v[138:141], v[204:207], v[76:79]
	v_mfma_f32_16x16x32_bf16 v[72:75], v[224:227], v[204:207], v[72:75]
	v_mfma_f32_16x16x32_bf16 v[68:71], v[138:141], v[212:215], v[68:71]
	v_mfma_f32_16x16x32_bf16 v[64:67], v[224:227], v[212:215], v[64:67]
	v_mfma_f32_16x16x32_bf16 v[92:95], v[220:223], v[192:195], v[92:95]
	v_mfma_f32_16x16x32_bf16 v[88:91], v[168:171], v[192:195], v[88:91]
	v_mfma_f32_16x16x32_bf16 v[84:87], v[220:223], v[200:203], v[84:87]
	v_mfma_f32_16x16x32_bf16 v[80:83], v[168:171], v[200:203], v[80:83]
	v_mfma_f32_16x16x32_bf16 v[76:79], v[220:223], v[208:211], v[76:79]
	v_mfma_f32_16x16x32_bf16 v[72:75], v[168:171], v[208:211], v[72:75]
	v_mfma_f32_16x16x32_bf16 v[68:71], v[220:223], v[216:219], v[68:71]
	v_mfma_f32_16x16x32_bf16 v[64:67], v[168:171], v[216:219], v[64:67]
	s_setprio 0
	s_barrier
	ds_read_b128 v[188:191], v161 offset:16384
	ds_read_b128 v[192:195], v161 offset:17408
	ds_read_b128 v[196:199], v160 offset:16384
	ds_read_b128 v[200:203], v160 offset:17408
	ds_read_b128 v[204:207], v159 offset:16384
	ds_read_b128 v[208:211], v159 offset:17408
	ds_read_b128 v[212:215], v158 offset:16384
	ds_read_b128 v[216:219], v158 offset:17408
	s_waitcnt vmcnt(4)
	s_barrier
	s_waitcnt lgkmcnt(0)
	s_setprio 1
	s_waitcnt lgkmcnt(0)
	v_mfma_f32_16x16x32_bf16 v[60:63], v[142:145], v[188:191], v[60:63]
	v_mfma_f32_16x16x32_bf16 v[56:59], v[180:183], v[188:191], v[56:59]
	v_mfma_f32_16x16x32_bf16 v[52:55], v[142:145], v[196:199], v[52:55]
	v_mfma_f32_16x16x32_bf16 v[48:51], v[180:183], v[196:199], v[48:51]
	v_mfma_f32_16x16x32_bf16 v[44:47], v[142:145], v[204:207], v[44:47]
	v_mfma_f32_16x16x32_bf16 v[40:43], v[180:183], v[204:207], v[40:43]
	v_mfma_f32_16x16x32_bf16 v[36:39], v[142:145], v[212:215], v[36:39]
	v_mfma_f32_16x16x32_bf16 v[32:35], v[180:183], v[212:215], v[32:35]
	v_mfma_f32_16x16x32_bf16 v[60:63], v[146:149], v[192:195], v[60:63]
	v_mfma_f32_16x16x32_bf16 v[56:59], v[184:187], v[192:195], v[56:59]
	v_mfma_f32_16x16x32_bf16 v[52:55], v[146:149], v[200:203], v[52:55]
	v_mfma_f32_16x16x32_bf16 v[48:51], v[184:187], v[200:203], v[48:51]
	v_mfma_f32_16x16x32_bf16 v[44:47], v[146:149], v[208:211], v[44:47]
	v_mfma_f32_16x16x32_bf16 v[40:43], v[184:187], v[208:211], v[40:43]
	v_mfma_f32_16x16x32_bf16 v[36:39], v[146:149], v[216:219], v[36:39]
	v_mfma_f32_16x16x32_bf16 v[32:35], v[184:187], v[216:219], v[32:35]
	s_setprio 0
	s_setprio 1
	v_mfma_f32_16x16x32_bf16 v[28:31], v[138:141], v[188:191], v[28:31]
	v_mfma_f32_16x16x32_bf16 v[24:27], v[224:227], v[188:191], v[24:27]
	v_mfma_f32_16x16x32_bf16 v[20:23], v[138:141], v[196:199], v[20:23]
	v_mfma_f32_16x16x32_bf16 v[16:19], v[224:227], v[196:199], v[16:19]
	v_mfma_f32_16x16x32_bf16 v[12:15], v[138:141], v[204:207], v[12:15]
	v_mfma_f32_16x16x32_bf16 v[8:11], v[224:227], v[204:207], v[8:11]
	v_mfma_f32_16x16x32_bf16 v[4:7], v[138:141], v[212:215], v[4:7]
	v_mfma_f32_16x16x32_bf16 v[0:3], v[224:227], v[212:215], v[0:3]
	v_mfma_f32_16x16x32_bf16 v[28:31], v[220:223], v[192:195], v[28:31]
	v_mfma_f32_16x16x32_bf16 v[24:27], v[168:171], v[192:195], v[24:27]
	v_mfma_f32_16x16x32_bf16 v[20:23], v[220:223], v[200:203], v[20:23]
	v_mfma_f32_16x16x32_bf16 v[16:19], v[168:171], v[200:203], v[16:19]
	v_mfma_f32_16x16x32_bf16 v[12:15], v[220:223], v[208:211], v[12:15]
	v_mfma_f32_16x16x32_bf16 v[8:11], v[168:171], v[208:211], v[8:11]
	v_mfma_f32_16x16x32_bf16 v[4:7], v[220:223], v[216:219], v[4:7]
	v_mfma_f32_16x16x32_bf16 v[0:3], v[168:171], v[216:219], v[0:3]
	s_setprio 0
	s_barrier
	ds_read_b128 v[138:141], v163
	ds_read_b128 v[142:145], v163 offset:1024
	ds_read_b128 v[146:149], v163 offset:2048
	ds_read_b128 v[168:171], v163 offset:3072
	ds_read_b128 v[178:181], v161 offset:32768
	ds_read_b128 v[182:185], v161 offset:33792
	ds_read_b128 v[186:189], v160 offset:32768
	ds_read_b128 v[190:193], v160 offset:33792
	ds_read_b128 v[194:197], v159 offset:32768
	ds_read_b128 v[198:201], v159 offset:33792
	ds_read_b128 v[202:205], v158 offset:32768
	ds_read_b128 v[206:209], v158 offset:33792
	s_waitcnt vmcnt(2)
	s_barrier
	s_waitcnt lgkmcnt(0)
	s_setprio 1
	s_waitcnt lgkmcnt(0)
	v_mfma_f32_16x16x32_bf16 v[124:127], v[138:141], v[178:181], v[124:127]
	v_mfma_f32_16x16x32_bf16 v[120:123], v[146:149], v[178:181], v[120:123]
	v_mfma_f32_16x16x32_bf16 v[116:119], v[138:141], v[186:189], v[116:119]
	v_mfma_f32_16x16x32_bf16 v[112:115], v[146:149], v[186:189], v[112:115]
	v_mfma_f32_16x16x32_bf16 v[108:111], v[138:141], v[194:197], v[108:111]
	v_mfma_f32_16x16x32_bf16 v[104:107], v[146:149], v[194:197], v[104:107]
	v_mfma_f32_16x16x32_bf16 v[100:103], v[138:141], v[202:205], v[100:103]
	v_mfma_f32_16x16x32_bf16 v[96:99], v[146:149], v[202:205], v[96:99]
	v_mfma_f32_16x16x32_bf16 v[124:127], v[142:145], v[182:185], v[124:127]
	v_mfma_f32_16x16x32_bf16 v[120:123], v[168:171], v[182:185], v[120:123]
	v_mfma_f32_16x16x32_bf16 v[116:119], v[142:145], v[190:193], v[116:119]
	v_mfma_f32_16x16x32_bf16 v[112:115], v[168:171], v[190:193], v[112:115]
	v_mfma_f32_16x16x32_bf16 v[108:111], v[142:145], v[198:201], v[108:111]
	v_mfma_f32_16x16x32_bf16 v[104:107], v[168:171], v[198:201], v[104:107]
	v_mfma_f32_16x16x32_bf16 v[100:103], v[142:145], v[206:209], v[100:103]
	v_mfma_f32_16x16x32_bf16 v[96:99], v[168:171], v[206:209], v[96:99]
	s_setprio 0
	s_barrier
	ds_read_b128 v[210:213], v162
	ds_read_b128 v[214:217], v162 offset:1024
	ds_read_b128 v[218:221], v162 offset:2048
	ds_read_b128 v[222:225], v162 offset:3072
	s_waitcnt vmcnt(0)
	s_barrier
	s_waitcnt lgkmcnt(0)
	s_setprio 1
	s_waitcnt lgkmcnt(0)
	v_mfma_f32_16x16x32_bf16 v[92:95], v[210:213], v[178:181], v[92:95]
	v_mfma_f32_16x16x32_bf16 v[88:91], v[218:221], v[178:181], v[88:91]
	v_mfma_f32_16x16x32_bf16 v[84:87], v[210:213], v[186:189], v[84:87]
	v_mfma_f32_16x16x32_bf16 v[80:83], v[218:221], v[186:189], v[80:83]
	v_mfma_f32_16x16x32_bf16 v[76:79], v[210:213], v[194:197], v[76:79]
	v_mfma_f32_16x16x32_bf16 v[72:75], v[218:221], v[194:197], v[72:75]
	v_mfma_f32_16x16x32_bf16 v[68:71], v[210:213], v[202:205], v[68:71]
	v_mfma_f32_16x16x32_bf16 v[64:67], v[218:221], v[202:205], v[64:67]
	v_mfma_f32_16x16x32_bf16 v[92:95], v[214:217], v[182:185], v[92:95]
	v_mfma_f32_16x16x32_bf16 v[88:91], v[222:225], v[182:185], v[88:91]
	v_mfma_f32_16x16x32_bf16 v[84:87], v[214:217], v[190:193], v[84:87]
	v_mfma_f32_16x16x32_bf16 v[80:83], v[222:225], v[190:193], v[80:83]
	v_mfma_f32_16x16x32_bf16 v[76:79], v[214:217], v[198:201], v[76:79]
	v_mfma_f32_16x16x32_bf16 v[72:75], v[222:225], v[198:201], v[72:75]
	v_mfma_f32_16x16x32_bf16 v[68:71], v[214:217], v[206:209], v[68:71]
	v_mfma_f32_16x16x32_bf16 v[64:67], v[222:225], v[206:209], v[64:67]
	s_setprio 0
	s_barrier
	ds_read_b128 v[178:181], v161 offset:49152
	ds_read_b128 v[182:185], v161 offset:50176
	ds_read_b128 v[186:189], v160 offset:49152
	ds_read_b128 v[160:163], v160 offset:50176
	ds_read_b128 v[190:193], v159 offset:49152
	ds_read_b128 v[194:197], v159 offset:50176
	ds_read_b128 v[198:201], v158 offset:49152
	ds_read_b128 v[202:205], v158 offset:50176
	s_barrier
	s_waitcnt lgkmcnt(0)
	s_setprio 1
	s_waitcnt lgkmcnt(0)
	v_mfma_f32_16x16x32_bf16 v[60:63], v[138:141], v[178:181], v[60:63]
	v_mfma_f32_16x16x32_bf16 v[56:59], v[146:149], v[178:181], v[56:59]
	v_mfma_f32_16x16x32_bf16 v[52:55], v[138:141], v[186:189], v[52:55]
	v_mfma_f32_16x16x32_bf16 v[48:51], v[146:149], v[186:189], v[48:51]
	v_mfma_f32_16x16x32_bf16 v[44:47], v[138:141], v[190:193], v[44:47]
	v_mfma_f32_16x16x32_bf16 v[40:43], v[146:149], v[190:193], v[40:43]
	v_mfma_f32_16x16x32_bf16 v[36:39], v[138:141], v[198:201], v[36:39]
	v_mfma_f32_16x16x32_bf16 v[32:35], v[146:149], v[198:201], v[32:35]
	v_mfma_f32_16x16x32_bf16 v[60:63], v[142:145], v[182:185], v[60:63]
	v_mfma_f32_16x16x32_bf16 v[56:59], v[168:171], v[182:185], v[56:59]
	v_mfma_f32_16x16x32_bf16 v[52:55], v[142:145], v[160:163], v[52:55]
	v_mfma_f32_16x16x32_bf16 v[48:51], v[168:171], v[160:163], v[48:51]
	v_mfma_f32_16x16x32_bf16 v[44:47], v[142:145], v[194:197], v[44:47]
	v_mfma_f32_16x16x32_bf16 v[40:43], v[168:171], v[194:197], v[40:43]
	v_mfma_f32_16x16x32_bf16 v[36:39], v[142:145], v[202:205], v[36:39]
	v_mfma_f32_16x16x32_bf16 v[32:35], v[168:171], v[202:205], v[32:35]
	s_setprio 0
	s_setprio 1
	v_mfma_f32_16x16x32_bf16 v[28:31], v[210:213], v[178:181], v[28:31]
	v_mfma_f32_16x16x32_bf16 v[24:27], v[218:221], v[178:181], v[24:27]
	v_mfma_f32_16x16x32_bf16 v[20:23], v[210:213], v[186:189], v[20:23]
	v_mfma_f32_16x16x32_bf16 v[16:19], v[218:221], v[186:189], v[16:19]
	v_mfma_f32_16x16x32_bf16 v[12:15], v[210:213], v[190:193], v[12:15]
	v_mfma_f32_16x16x32_bf16 v[8:11], v[218:221], v[190:193], v[8:11]
	v_mfma_f32_16x16x32_bf16 v[4:7], v[210:213], v[198:201], v[4:7]
	v_mfma_f32_16x16x32_bf16 v[0:3], v[218:221], v[198:201], v[0:3]
	v_mfma_f32_16x16x32_bf16 v[28:31], v[214:217], v[182:185], v[28:31]
	v_mfma_f32_16x16x32_bf16 v[24:27], v[222:225], v[182:185], v[24:27]
	v_mfma_f32_16x16x32_bf16 v[20:23], v[214:217], v[160:163], v[20:23]
	v_mfma_f32_16x16x32_bf16 v[16:19], v[222:225], v[160:163], v[16:19]
	v_mfma_f32_16x16x32_bf16 v[12:15], v[214:217], v[194:197], v[12:15]
	v_mfma_f32_16x16x32_bf16 v[8:11], v[222:225], v[194:197], v[8:11]
	v_mfma_f32_16x16x32_bf16 v[4:7], v[214:217], v[202:205], v[4:7]
	v_mfma_f32_16x16x32_bf16 v[0:3], v[222:225], v[202:205], v[0:3]
	s_setprio 0
	s_and_b64 vcc, exec, s[38:39]
	s_barrier
	s_cbranch_vccnz .LBB0_2919
	s_lshr_b32 s2, s60, 2
	s_and_b32 s4, s60, 3
	s_add_i32 s2, s2, s56
	s_or_b32 s5, s4, s53
	s_lshl_b32 s4, s2, 8
	s_lshl_b32 s2, s5, 19
	s_add_u32 s42, s40, s2
	s_addc_u32 s43, s46, 0
	v_lshl_add_u64 v[138:139], s[42:43], 0, v[130:131]
	v_readfirstlane_b32 s2, v153
	s_ashr_i32 s5, s4, 31
	v_lshl_add_u64 v[138:139], v[138:139], 0, v[132:133]
	s_mov_b32 m0, s2
	s_lshl_b64 s[44:45], s[4:5], 11
	global_load_lds_dwordx4 v[138:139], off
	v_lshl_add_u64 v[138:139], s[42:43], 0, v[134:135]
	v_readfirstlane_b32 s2, v173
	s_add_u32 s44, s1, s44
	v_lshl_add_u64 v[138:139], v[138:139], 0, v[136:137]
	s_mov_b32 m0, s2
	s_addc_u32 s45, s23, s45
	global_load_lds_dwordx4 v[138:139], off
	v_lshl_add_u64 v[138:139], s[44:45], 0, v[130:131]
	v_readfirstlane_b32 s2, v152
	v_lshl_add_u64 v[138:139], v[138:139], 0, v[132:133]
	s_mov_b32 m0, s2
	s_add_u32 s42, s42, 0x40000
	global_load_lds_dwordx4 v[138:139], off
	v_lshl_add_u64 v[138:139], s[44:45], 0, v[134:135]
	v_readfirstlane_b32 s2, v174
	s_addc_u32 s43, s43, 0
	s_bitset1_b32 s4, 7
	v_lshl_add_u64 v[138:139], v[138:139], 0, v[136:137]
	s_mov_b32 m0, s2
	s_ashr_i32 s5, s4, 31
	global_load_lds_dwordx4 v[138:139], off
	v_lshl_add_u64 v[138:139], s[42:43], 0, v[130:131]
	v_readfirstlane_b32 s2, v151
	s_lshl_b64 s[4:5], s[4:5], 11
	v_lshl_add_u64 v[138:139], v[138:139], 0, v[132:133]
	s_mov_b32 m0, s2
	s_add_u32 s4, s1, s4
	global_load_lds_dwordx4 v[138:139], off
	v_lshl_add_u64 v[138:139], s[42:43], 0, v[134:135]
	v_readfirstlane_b32 s2, v175
	s_addc_u32 s5, s23, s5
	v_lshl_add_u64 v[138:139], v[138:139], 0, v[136:137]
	s_mov_b32 m0, s2
	v_lshl_add_u64 v[130:131], s[4:5], 0, v[130:131]
	v_readfirstlane_b32 s2, v176
	global_load_lds_dwordx4 v[138:139], off
	v_lshl_add_u64 v[130:131], v[130:131], 0, v[132:133]
	s_mov_b32 m0, s2
	v_readfirstlane_b32 s2, v177
	global_load_lds_dwordx4 v[130:131], off
	v_lshl_add_u64 v[130:131], s[4:5], 0, v[134:135]
	v_lshl_add_u64 v[130:131], v[130:131], 0, v[136:137]
	s_mov_b32 m0, s2
	s_nop 0
	global_load_lds_dwordx4 v[130:131], off

.LBB0_2971:
	ds_read_b128 v[176:179], v173
	ds_read_b128 v[180:183], v173 offset:1024
	ds_read_b128 v[184:187], v173 offset:2048
	ds_read_b128 v[188:191], v173 offset:3072
	v_add_u32_e32 v174, 0xc000, v157
	v_lshl_add_u64 v[240:241], s[2:3], 0, v[142:143]
	v_readfirstlane_b32 s31, v174
	v_add_u32_e32 v175, 0xe000, v157
	v_lshl_add_u64 v[224:225], v[240:241], 0, s[10:11]
	s_mov_b32 m0, s31
	v_lshl_add_u64 v[242:243], s[2:3], 0, v[144:145]
	v_readfirstlane_b32 s31, v175
	ds_read_b128 v[192:195], v155
	ds_read_b128 v[196:199], v155 offset:1024
	ds_read_b128 v[200:203], v154
	ds_read_b128 v[204:207], v154 offset:1024
	ds_read_b128 v[208:211], v153
	ds_read_b128 v[212:215], v153 offset:1024
	ds_read_b128 v[216:219], v152
	ds_read_b128 v[220:223], v152 offset:1024
	global_load_lds_dwordx4 v[224:225], off
	v_lshl_add_u64 v[224:225], v[242:243], 0, s[10:11]
	s_mov_b32 m0, s31
	s_nop 0
	global_load_lds_dwordx4 v[224:225], off
	s_waitcnt vmcnt(10)
	s_waitcnt lgkmcnt(8)
	s_barrier
	s_waitcnt lgkmcnt(0)
	s_setprio 1
	s_waitcnt lgkmcnt(0)
	v_mfma_f32_16x16x32_bf16 v[124:127], v[176:179], v[192:195], v[124:127]
	v_mfma_f32_16x16x32_bf16 v[120:123], v[184:187], v[192:195], v[120:123]
	v_mfma_f32_16x16x32_bf16 v[116:119], v[176:179], v[200:203], v[116:119]
	v_mfma_f32_16x16x32_bf16 v[112:115], v[184:187], v[200:203], v[112:115]
	v_mfma_f32_16x16x32_bf16 v[108:111], v[176:179], v[208:211], v[108:111]
	v_mfma_f32_16x16x32_bf16 v[104:107], v[184:187], v[208:211], v[104:107]
	v_mfma_f32_16x16x32_bf16 v[100:103], v[176:179], v[216:219], v[100:103]
	v_mfma_f32_16x16x32_bf16 v[96:99], v[184:187], v[216:219], v[96:99]
	v_mfma_f32_16x16x32_bf16 v[124:127], v[180:183], v[196:199], v[124:127]
	v_mfma_f32_16x16x32_bf16 v[120:123], v[188:191], v[196:199], v[120:123]
	v_mfma_f32_16x16x32_bf16 v[116:119], v[180:183], v[204:207], v[116:119]
	v_mfma_f32_16x16x32_bf16 v[112:115], v[188:191], v[204:207], v[112:115]
	v_mfma_f32_16x16x32_bf16 v[108:111], v[180:183], v[212:215], v[108:111]
	v_mfma_f32_16x16x32_bf16 v[104:107], v[188:191], v[212:215], v[104:107]
	v_mfma_f32_16x16x32_bf16 v[100:103], v[180:183], v[220:223], v[100:103]
	v_mfma_f32_16x16x32_bf16 v[96:99], v[188:191], v[220:223], v[96:99]
	s_setprio 0
	s_barrier
	v_lshl_add_u64 v[244:245], s[2:3], 0, v[138:139]
	v_readfirstlane_b32 s31, v151
	v_lshl_add_u64 v[246:247], v[244:245], 0, s[12:13]
	s_mov_b32 m0, s31
	v_add_u32_e32 v250, 0x2000, v151
	ds_read_b128 v[224:227], v170
	ds_read_b128 v[228:231], v170 offset:1024
	ds_read_b128 v[232:235], v170 offset:2048
	ds_read_b128 v[236:239], v170 offset:3072
	global_load_lds_dwordx4 v[246:247], off
	v_lshl_add_u64 v[246:247], s[2:3], 0, v[140:141]
	v_readfirstlane_b32 s31, v250
	v_lshl_add_u64 v[248:249], v[246:247], 0, s[12:13]
	s_mov_b32 m0, s31
	s_nop 0
	global_load_lds_dwordx4 v[248:249], off
	s_waitcnt vmcnt(10)
	s_barrier
	s_waitcnt lgkmcnt(0)
	s_setprio 1
	s_waitcnt lgkmcnt(0)
	v_mfma_f32_16x16x32_bf16 v[92:95], v[224:227], v[192:195], v[92:95]
	v_mfma_f32_16x16x32_bf16 v[88:91], v[232:235], v[192:195], v[88:91]
	v_mfma_f32_16x16x32_bf16 v[84:87], v[224:227], v[200:203], v[84:87]
	v_mfma_f32_16x16x32_bf16 v[80:83], v[232:235], v[200:203], v[80:83]
	v_mfma_f32_16x16x32_bf16 v[76:79], v[224:227], v[208:211], v[76:79]
	v_mfma_f32_16x16x32_bf16 v[72:75], v[232:235], v[208:211], v[72:75]
	v_mfma_f32_16x16x32_bf16 v[68:71], v[224:227], v[216:219], v[68:71]
	v_mfma_f32_16x16x32_bf16 v[64:67], v[232:235], v[216:219], v[64:67]
	v_mfma_f32_16x16x32_bf16 v[92:95], v[228:231], v[196:199], v[92:95]
	v_mfma_f32_16x16x32_bf16 v[88:91], v[236:239], v[196:199], v[88:91]
	v_mfma_f32_16x16x32_bf16 v[84:87], v[228:231], v[204:207], v[84:87]
	v_mfma_f32_16x16x32_bf16 v[80:83], v[236:239], v[204:207], v[80:83]
	v_mfma_f32_16x16x32_bf16 v[76:79], v[228:231], v[212:215], v[76:79]
	v_mfma_f32_16x16x32_bf16 v[72:75], v[236:239], v[212:215], v[72:75]
	v_mfma_f32_16x16x32_bf16 v[68:71], v[228:231], v[220:223], v[68:71]
	v_mfma_f32_16x16x32_bf16 v[64:67], v[236:239], v[220:223], v[64:67]
	s_setprio 0
	v_readfirstlane_b32 s31, v157
	v_lshl_add_u64 v[248:249], v[240:241], 0, s[14:15]
	s_mov_b32 m0, s31
	v_readfirstlane_b32 s31, v158
	s_barrier
	ds_read_b128 v[192:195], v155 offset:16384
	ds_read_b128 v[196:199], v155 offset:17408
	ds_read_b128 v[200:203], v154 offset:16384
	ds_read_b128 v[204:207], v154 offset:17408
	ds_read_b128 v[208:211], v153 offset:16384
	ds_read_b128 v[212:215], v153 offset:17408
	ds_read_b128 v[216:219], v152 offset:16384
	ds_read_b128 v[220:223], v152 offset:17408
	global_load_lds_dwordx4 v[248:249], off
	v_lshl_add_u64 v[248:249], v[242:243], 0, s[14:15]
	s_mov_b32 m0, s31
	s_nop 0
	global_load_lds_dwordx4 v[248:249], off
	s_barrier
	s_waitcnt lgkmcnt(0)
	s_setprio 1
	s_waitcnt lgkmcnt(0)
	v_mfma_f32_16x16x32_bf16 v[60:63], v[176:179], v[192:195], v[60:63]
	v_mfma_f32_16x16x32_bf16 v[56:59], v[184:187], v[192:195], v[56:59]
	v_mfma_f32_16x16x32_bf16 v[52:55], v[176:179], v[200:203], v[52:55]
	v_mfma_f32_16x16x32_bf16 v[48:51], v[184:187], v[200:203], v[48:51]
	v_mfma_f32_16x16x32_bf16 v[44:47], v[176:179], v[208:211], v[44:47]
	v_mfma_f32_16x16x32_bf16 v[40:43], v[184:187], v[208:211], v[40:43]
	v_mfma_f32_16x16x32_bf16 v[36:39], v[176:179], v[216:219], v[36:39]
	v_mfma_f32_16x16x32_bf16 v[32:35], v[184:187], v[216:219], v[32:35]
	v_mfma_f32_16x16x32_bf16 v[60:63], v[180:183], v[196:199], v[60:63]
	v_mfma_f32_16x16x32_bf16 v[56:59], v[188:191], v[196:199], v[56:59]
	v_mfma_f32_16x16x32_bf16 v[52:55], v[180:183], v[204:207], v[52:55]
	v_mfma_f32_16x16x32_bf16 v[48:51], v[188:191], v[204:207], v[48:51]
	v_mfma_f32_16x16x32_bf16 v[44:47], v[180:183], v[212:215], v[44:47]
	v_mfma_f32_16x16x32_bf16 v[40:43], v[188:191], v[212:215], v[40:43]
	v_mfma_f32_16x16x32_bf16 v[36:39], v[180:183], v[220:223], v[36:39]
	v_mfma_f32_16x16x32_bf16 v[32:35], v[188:191], v[220:223], v[32:35]
	s_setprio 0
	s_barrier
	v_readfirstlane_b32 s31, v159
	v_add_u32_e32 v178, 0x2000, v159
	v_lshl_add_u64 v[176:177], v[244:245], 0, s[16:17]
	s_mov_b32 m0, s31
	v_readfirstlane_b32 s31, v178
	global_load_lds_dwordx4 v[176:177], off
	v_lshl_add_u64 v[176:177], v[246:247], 0, s[16:17]
	s_mov_b32 m0, s31
	s_nop 0
	global_load_lds_dwordx4 v[176:177], off
	s_waitcnt vmcnt(10)
	s_barrier
	s_setprio 1
	v_mfma_f32_16x16x32_bf16 v[28:31], v[224:227], v[192:195], v[28:31]
	v_mfma_f32_16x16x32_bf16 v[24:27], v[232:235], v[192:195], v[24:27]
	v_mfma_f32_16x16x32_bf16 v[20:23], v[224:227], v[200:203], v[20:23]
	v_mfma_f32_16x16x32_bf16 v[16:19], v[232:235], v[200:203], v[16:19]
	v_mfma_f32_16x16x32_bf16 v[12:15], v[224:227], v[208:211], v[12:15]
	v_mfma_f32_16x16x32_bf16 v[8:11], v[232:235], v[208:211], v[8:11]
	v_mfma_f32_16x16x32_bf16 v[4:7], v[224:227], v[216:219], v[4:7]
	v_mfma_f32_16x16x32_bf16 v[0:3], v[232:235], v[216:219], v[0:3]
	v_mfma_f32_16x16x32_bf16 v[28:31], v[228:231], v[196:199], v[28:31]
	v_mfma_f32_16x16x32_bf16 v[24:27], v[236:239], v[196:199], v[24:27]
	v_mfma_f32_16x16x32_bf16 v[20:23], v[228:231], v[204:207], v[20:23]
	v_mfma_f32_16x16x32_bf16 v[16:19], v[236:239], v[204:207], v[16:19]
	v_mfma_f32_16x16x32_bf16 v[12:15], v[228:231], v[212:215], v[12:15]
	v_mfma_f32_16x16x32_bf16 v[8:11], v[236:239], v[212:215], v[8:11]
	v_mfma_f32_16x16x32_bf16 v[4:7], v[228:231], v[220:223], v[4:7]
	v_mfma_f32_16x16x32_bf16 v[0:3], v[236:239], v[220:223], v[0:3]
	s_setprio 0
	s_barrier
	ds_read_b128 v[176:179], v160
	ds_read_b128 v[180:183], v160 offset:1024
	ds_read_b128 v[184:187], v160 offset:2048
	ds_read_b128 v[188:191], v160 offset:3072
	v_readfirstlane_b32 s31, v161
	v_lshl_add_u64 v[224:225], v[240:241], 0, s[18:19]
	s_mov_b32 m0, s31
	v_readfirstlane_b32 s31, v162
	ds_read_b128 v[192:195], v155 offset:32768
	ds_read_b128 v[196:199], v155 offset:33792
	ds_read_b128 v[200:203], v154 offset:32768
	ds_read_b128 v[204:207], v154 offset:33792
	ds_read_b128 v[208:211], v153 offset:32768
	ds_read_b128 v[212:215], v153 offset:33792
	ds_read_b128 v[216:219], v152 offset:32768
	ds_read_b128 v[220:223], v152 offset:33792
	global_load_lds_dwordx4 v[224:225], off
	v_lshl_add_u64 v[224:225], v[242:243], 0, s[18:19]
	s_mov_b32 m0, s31
	s_nop 0
	global_load_lds_dwordx4 v[224:225], off
	s_waitcnt vmcnt(10)
	s_waitcnt lgkmcnt(8)
	s_barrier
	s_waitcnt lgkmcnt(0)
	s_setprio 1
	s_waitcnt lgkmcnt(0)
	v_mfma_f32_16x16x32_bf16 v[124:127], v[176:179], v[192:195], v[124:127]
	v_mfma_f32_16x16x32_bf16 v[120:123], v[184:187], v[192:195], v[120:123]
	v_mfma_f32_16x16x32_bf16 v[116:119], v[176:179], v[200:203], v[116:119]
	v_mfma_f32_16x16x32_bf16 v[112:115], v[184:187], v[200:203], v[112:115]
	v_mfma_f32_16x16x32_bf16 v[108:111], v[176:179], v[208:211], v[108:111]
	v_mfma_f32_16x16x32_bf16 v[104:107], v[184:187], v[208:211], v[104:107]
	v_mfma_f32_16x16x32_bf16 v[100:103], v[176:179], v[216:219], v[100:103]
	v_mfma_f32_16x16x32_bf16 v[96:99], v[184:187], v[216:219], v[96:99]
	v_mfma_f32_16x16x32_bf16 v[124:127], v[180:183], v[196:199], v[124:127]
	v_mfma_f32_16x16x32_bf16 v[120:123], v[188:191], v[196:199], v[120:123]
	v_mfma_f32_16x16x32_bf16 v[116:119], v[180:183], v[204:207], v[116:119]
	v_mfma_f32_16x16x32_bf16 v[112:115], v[188:191], v[204:207], v[112:115]
	v_mfma_f32_16x16x32_bf16 v[108:111], v[180:183], v[212:215], v[108:111]
	v_mfma_f32_16x16x32_bf16 v[104:107], v[188:191], v[212:215], v[104:107]
	v_mfma_f32_16x16x32_bf16 v[100:103], v[180:183], v[220:223], v[100:103]
	v_mfma_f32_16x16x32_bf16 v[96:99], v[188:191], v[220:223], v[96:99]
	s_setprio 0
	s_barrier
	v_readfirstlane_b32 s31, v163
	v_lshl_add_u64 v[248:249], v[244:245], 0, s[20:21]
	s_mov_b32 m0, s31
	v_readfirstlane_b32 s31, v167
	ds_read_b128 v[224:227], v156
	ds_read_b128 v[228:231], v156 offset:1024
	ds_read_b128 v[232:235], v156 offset:2048
	ds_read_b128 v[236:239], v156 offset:3072
	global_load_lds_dwordx4 v[248:249], off
	v_lshl_add_u64 v[248:249], v[246:247], 0, s[20:21]
	s_mov_b32 m0, s31
	s_nop 0
	global_load_lds_dwordx4 v[248:249], off
	s_waitcnt vmcnt(10)
	s_barrier
	s_waitcnt lgkmcnt(0)
	s_setprio 1
	s_waitcnt lgkmcnt(0)
	v_mfma_f32_16x16x32_bf16 v[92:95], v[224:227], v[192:195], v[92:95]
	v_mfma_f32_16x16x32_bf16 v[88:91], v[232:235], v[192:195], v[88:91]
	v_mfma_f32_16x16x32_bf16 v[84:87], v[224:227], v[200:203], v[84:87]
	v_mfma_f32_16x16x32_bf16 v[80:83], v[232:235], v[200:203], v[80:83]
	v_mfma_f32_16x16x32_bf16 v[76:79], v[224:227], v[208:211], v[76:79]
	v_mfma_f32_16x16x32_bf16 v[72:75], v[232:235], v[208:211], v[72:75]
	v_mfma_f32_16x16x32_bf16 v[68:71], v[224:227], v[216:219], v[68:71]
	v_mfma_f32_16x16x32_bf16 v[64:67], v[232:235], v[216:219], v[64:67]
	v_mfma_f32_16x16x32_bf16 v[92:95], v[228:231], v[196:199], v[92:95]
	v_mfma_f32_16x16x32_bf16 v[88:91], v[236:239], v[196:199], v[88:91]
	v_mfma_f32_16x16x32_bf16 v[84:87], v[228:231], v[204:207], v[84:87]
	v_mfma_f32_16x16x32_bf16 v[80:83], v[236:239], v[204:207], v[80:83]
	v_mfma_f32_16x16x32_bf16 v[76:79], v[228:231], v[212:215], v[76:79]
	v_mfma_f32_16x16x32_bf16 v[72:75], v[236:239], v[212:215], v[72:75]
	v_mfma_f32_16x16x32_bf16 v[68:71], v[228:231], v[220:223], v[68:71]
	v_mfma_f32_16x16x32_bf16 v[64:67], v[236:239], v[220:223], v[64:67]
	s_setprio 0
	v_readfirstlane_b32 s31, v168
	v_lshl_add_u64 v[240:241], v[240:241], 0, s[24:25]
	s_mov_b32 m0, s31
	v_readfirstlane_b32 s31, v169
	s_barrier
	ds_read_b128 v[192:195], v155 offset:49152
	ds_read_b128 v[196:199], v155 offset:50176
	ds_read_b128 v[200:203], v154 offset:49152
	ds_read_b128 v[204:207], v154 offset:50176
	ds_read_b128 v[208:211], v153 offset:49152
	ds_read_b128 v[212:215], v153 offset:50176
	ds_read_b128 v[216:219], v152 offset:49152
	ds_read_b128 v[220:223], v152 offset:50176
	global_load_lds_dwordx4 v[240:241], off
	v_lshl_add_u64 v[240:241], v[242:243], 0, s[24:25]
	s_mov_b32 m0, s31
	s_nop 0
	global_load_lds_dwordx4 v[240:241], off
	s_barrier
	s_waitcnt lgkmcnt(0)
	s_setprio 1
	s_waitcnt lgkmcnt(0)
	v_mfma_f32_16x16x32_bf16 v[60:63], v[176:179], v[192:195], v[60:63]
	v_mfma_f32_16x16x32_bf16 v[56:59], v[184:187], v[192:195], v[56:59]
	v_mfma_f32_16x16x32_bf16 v[52:55], v[176:179], v[200:203], v[52:55]
	v_mfma_f32_16x16x32_bf16 v[48:51], v[184:187], v[200:203], v[48:51]
	v_mfma_f32_16x16x32_bf16 v[44:47], v[176:179], v[208:211], v[44:47]
	v_mfma_f32_16x16x32_bf16 v[40:43], v[184:187], v[208:211], v[40:43]
	v_mfma_f32_16x16x32_bf16 v[36:39], v[176:179], v[216:219], v[36:39]
	v_mfma_f32_16x16x32_bf16 v[32:35], v[184:187], v[216:219], v[32:35]
	v_mfma_f32_16x16x32_bf16 v[60:63], v[180:183], v[196:199], v[60:63]
	v_mfma_f32_16x16x32_bf16 v[56:59], v[188:191], v[196:199], v[56:59]
	v_mfma_f32_16x16x32_bf16 v[52:55], v[180:183], v[204:207], v[52:55]
	v_mfma_f32_16x16x32_bf16 v[48:51], v[188:191], v[204:207], v[48:51]
	v_mfma_f32_16x16x32_bf16 v[44:47], v[180:183], v[212:215], v[44:47]
	v_mfma_f32_16x16x32_bf16 v[40:43], v[188:191], v[212:215], v[40:43]
	v_mfma_f32_16x16x32_bf16 v[36:39], v[180:183], v[220:223], v[36:39]
	v_mfma_f32_16x16x32_bf16 v[32:35], v[188:191], v[220:223], v[32:35]
	s_setprio 0
	s_barrier
	v_readfirstlane_b32 s31, v171
	v_lshl_add_u64 v[176:177], v[244:245], 0, s[26:27]
	s_mov_b32 m0, s31
	v_readfirstlane_b32 s31, v172
	global_load_lds_dwordx4 v[176:177], off
	v_lshl_add_u64 v[176:177], v[246:247], 0, s[26:27]
	s_mov_b32 m0, s31
	s_nop 0
	global_load_lds_dwordx4 v[176:177], off
	s_waitcnt vmcnt(10)
	s_barrier
	s_setprio 1
	v_mfma_f32_16x16x32_bf16 v[28:31], v[224:227], v[192:195], v[28:31]
	v_mfma_f32_16x16x32_bf16 v[24:27], v[232:235], v[192:195], v[24:27]
	v_mfma_f32_16x16x32_bf16 v[20:23], v[224:227], v[200:203], v[20:23]
	v_mfma_f32_16x16x32_bf16 v[16:19], v[232:235], v[200:203], v[16:19]
	v_mfma_f32_16x16x32_bf16 v[12:15], v[224:227], v[208:211], v[12:15]
	v_mfma_f32_16x16x32_bf16 v[8:11], v[232:235], v[208:211], v[8:11]
	v_mfma_f32_16x16x32_bf16 v[4:7], v[224:227], v[216:219], v[4:7]
	v_mfma_f32_16x16x32_bf16 v[0:3], v[232:235], v[216:219], v[0:3]
	v_mfma_f32_16x16x32_bf16 v[28:31], v[228:231], v[196:199], v[28:31]
	v_mfma_f32_16x16x32_bf16 v[24:27], v[236:239], v[196:199], v[24:27]
	v_mfma_f32_16x16x32_bf16 v[20:23], v[228:231], v[204:207], v[20:23]
	v_mfma_f32_16x16x32_bf16 v[16:19], v[236:239], v[204:207], v[16:19]
	v_mfma_f32_16x16x32_bf16 v[12:15], v[228:231], v[212:215], v[12:15]
	v_mfma_f32_16x16x32_bf16 v[8:11], v[236:239], v[212:215], v[8:11]
	v_mfma_f32_16x16x32_bf16 v[4:7], v[228:231], v[220:223], v[4:7]
	v_mfma_f32_16x16x32_bf16 v[0:3], v[236:239], v[220:223], v[0:3]
	s_setprio 0
	s_add_i32 s6, s6, 2
	v_lshl_add_u64 v[138:139], v[138:139], 0, s[28:29]
	v_lshl_add_u64 v[140:141], v[140:141], 0, s[28:29]
	v_lshl_add_u64 v[142:143], v[142:143], 0, s[28:29]
	s_cmp_lt_u32 s6, 60
	v_lshl_add_u64 v[144:145], v[144:145], 0, s[28:29]
	s_barrier
	s_cbranch_scc1 .LBB0_2971
	s_add_u32 s34, s34, 0x1f80
	s_addc_u32 s35, s35, 0
	v_lshl_add_u64 v[132:133], s[34:35], 0, v[132:133]
	v_readfirstlane_b32 s6, v174
	v_lshl_add_u64 v[130:131], v[130:131], 1, v[132:133]
	s_mov_b32 m0, s6
	ds_read_b128 v[138:141], v173
	ds_read_b128 v[142:145], v173 offset:1024
	ds_read_b128 v[176:179], v173 offset:2048
	ds_read_b128 v[180:183], v173 offset:3072
	ds_read_b128 v[184:187], v155
	ds_read_b128 v[188:191], v155 offset:1024
	ds_read_b128 v[192:195], v154
	ds_read_b128 v[196:199], v154 offset:1024
	ds_read_b128 v[200:203], v153
	ds_read_b128 v[204:207], v153 offset:1024
	ds_read_b128 v[208:211], v152
	ds_read_b128 v[212:215], v152 offset:1024
	global_load_lds_dwordx4 v[130:131], off
	v_lshl_add_u64 v[130:131], s[34:35], 0, v[136:137]
	v_readfirstlane_b32 s6, v175
	v_lshl_add_u64 v[130:131], v[134:135], 1, v[130:131]
	s_mov_b32 m0, s6
	s_nop 0
	global_load_lds_dwordx4 v[130:131], off
	s_waitcnt vmcnt(10)
	s_barrier
	s_waitcnt lgkmcnt(0)
	s_setprio 1
	s_waitcnt lgkmcnt(0)
	v_mfma_f32_16x16x32_bf16 v[124:127], v[138:141], v[184:187], v[124:127]
	v_mfma_f32_16x16x32_bf16 v[116:119], v[138:141], v[192:195], v[116:119]
	v_mfma_f32_16x16x32_bf16 v[108:111], v[138:141], v[200:203], v[108:111]
	v_mfma_f32_16x16x32_bf16 v[100:103], v[138:141], v[208:211], v[100:103]
	v_mfma_f32_16x16x32_bf16 v[124:127], v[142:145], v[188:191], v[124:127]
	v_mfma_f32_16x16x32_bf16 v[120:123], v[176:179], v[184:187], v[120:123]
	v_mfma_f32_16x16x32_bf16 v[116:119], v[142:145], v[196:199], v[116:119]
	v_mfma_f32_16x16x32_bf16 v[112:115], v[176:179], v[192:195], v[112:115]
	v_mfma_f32_16x16x32_bf16 v[108:111], v[142:145], v[204:207], v[108:111]
	v_mfma_f32_16x16x32_bf16 v[104:107], v[176:179], v[200:203], v[104:107]
	v_mfma_f32_16x16x32_bf16 v[100:103], v[142:145], v[212:215], v[100:103]
	v_mfma_f32_16x16x32_bf16 v[96:99], v[176:179], v[208:211], v[96:99]
	v_mfma_f32_16x16x32_bf16 v[130:133], v[180:183], v[188:191], v[120:123]
	v_mfma_f32_16x16x32_bf16 v[134:137], v[180:183], v[196:199], v[112:115]
	v_mfma_f32_16x16x32_bf16 v[172:175], v[180:183], v[204:207], v[104:107]
	v_mfma_f32_16x16x32_bf16 v[216:219], v[180:183], v[212:215], v[96:99]
	s_setprio 0
	s_barrier
	s_nop 1
	ds_read_b128 v[96:99], v170
	ds_read_b128 v[104:107], v170 offset:1024
	ds_read_b128 v[112:115], v170 offset:2048
	ds_read_b128 v[120:123], v170 offset:3072
	s_waitcnt vmcnt(8)
	s_barrier
	s_waitcnt lgkmcnt(0)
	s_setprio 1
	s_waitcnt lgkmcnt(0)
	v_mfma_f32_16x16x32_bf16 v[92:95], v[96:99], v[184:187], v[92:95]
	v_mfma_f32_16x16x32_bf16 v[84:87], v[96:99], v[192:195], v[84:87]
	v_mfma_f32_16x16x32_bf16 v[76:79], v[96:99], v[200:203], v[76:79]
	v_mfma_f32_16x16x32_bf16 v[68:71], v[96:99], v[208:211], v[68:71]
	v_mfma_f32_16x16x32_bf16 v[92:95], v[104:107], v[188:191], v[92:95]
	v_mfma_f32_16x16x32_bf16 v[88:91], v[112:115], v[184:187], v[88:91]
	v_mfma_f32_16x16x32_bf16 v[84:87], v[104:107], v[196:199], v[84:87]
	v_mfma_f32_16x16x32_bf16 v[80:83], v[112:115], v[192:195], v[80:83]
	v_mfma_f32_16x16x32_bf16 v[76:79], v[104:107], v[204:207], v[76:79]
	v_mfma_f32_16x16x32_bf16 v[72:75], v[112:115], v[200:203], v[72:75]
	v_mfma_f32_16x16x32_bf16 v[68:71], v[104:107], v[212:215], v[68:71]
	v_mfma_f32_16x16x32_bf16 v[64:67], v[112:115], v[208:211], v[64:67]
	v_mfma_f32_16x16x32_bf16 v[168:171], v[120:123], v[188:191], v[88:91]
	v_mfma_f32_16x16x32_bf16 v[184:187], v[120:123], v[196:199], v[80:83]
	v_mfma_f32_16x16x32_bf16 v[188:191], v[120:123], v[204:207], v[72:75]
	v_mfma_f32_16x16x32_bf16 v[192:195], v[120:123], v[212:215], v[64:67]
	s_setprio 0
	s_barrier
	s_nop 1
	ds_read_b128 v[64:67], v155 offset:16384
	ds_read_b128 v[72:75], v155 offset:17408
	ds_read_b128 v[80:83], v154 offset:16384
	ds_read_b128 v[88:91], v154 offset:17408
	ds_read_b128 v[196:199], v153 offset:16384
	ds_read_b128 v[200:203], v153 offset:17408
	ds_read_b128 v[204:207], v152 offset:16384
	ds_read_b128 v[208:211], v152 offset:17408
	s_waitcnt vmcnt(4)
	s_barrier
	s_waitcnt lgkmcnt(0)
	s_setprio 1
	s_waitcnt lgkmcnt(0)
	v_mfma_f32_16x16x32_bf16 v[60:63], v[138:141], v[64:67], v[60:63]
	v_mfma_f32_16x16x32_bf16 v[52:55], v[138:141], v[80:83], v[52:55]
	v_mfma_f32_16x16x32_bf16 v[44:47], v[138:141], v[196:199], v[44:47]
	v_mfma_f32_16x16x32_bf16 v[36:39], v[138:141], v[204:207], v[36:39]
	v_mfma_f32_16x16x32_bf16 v[60:63], v[142:145], v[72:75], v[60:63]
	v_mfma_f32_16x16x32_bf16 v[56:59], v[176:179], v[64:67], v[56:59]
	v_mfma_f32_16x16x32_bf16 v[52:55], v[142:145], v[88:91], v[52:55]
	v_mfma_f32_16x16x32_bf16 v[48:51], v[176:179], v[80:83], v[48:51]
	v_mfma_f32_16x16x32_bf16 v[44:47], v[142:145], v[200:203], v[44:47]
	v_mfma_f32_16x16x32_bf16 v[40:43], v[176:179], v[196:199], v[40:43]
	v_mfma_f32_16x16x32_bf16 v[36:39], v[142:145], v[208:211], v[36:39]
	v_mfma_f32_16x16x32_bf16 v[32:35], v[176:179], v[204:207], v[32:35]
	v_mfma_f32_16x16x32_bf16 v[212:215], v[180:183], v[72:75], v[56:59]
	v_mfma_f32_16x16x32_bf16 v[220:223], v[180:183], v[88:91], v[48:51]
	v_mfma_f32_16x16x32_bf16 v[224:227], v[180:183], v[200:203], v[40:43]
	v_mfma_f32_16x16x32_bf16 v[138:141], v[180:183], v[208:211], v[32:35]
	s_setprio 0
	s_setprio 1
	v_mfma_f32_16x16x32_bf16 v[28:31], v[96:99], v[64:67], v[28:31]
	v_mfma_f32_16x16x32_bf16 v[20:23], v[96:99], v[80:83], v[20:23]
	v_mfma_f32_16x16x32_bf16 v[12:15], v[96:99], v[196:199], v[12:15]
	v_mfma_f32_16x16x32_bf16 v[4:7], v[96:99], v[204:207], v[4:7]
	v_mfma_f32_16x16x32_bf16 v[28:31], v[104:107], v[72:75], v[28:31]
	v_mfma_f32_16x16x32_bf16 v[24:27], v[112:115], v[64:67], v[24:27]
	v_mfma_f32_16x16x32_bf16 v[20:23], v[104:107], v[88:91], v[20:23]
	v_mfma_f32_16x16x32_bf16 v[16:19], v[112:115], v[80:83], v[16:19]
	v_mfma_f32_16x16x32_bf16 v[12:15], v[104:107], v[200:203], v[12:15]
	v_mfma_f32_16x16x32_bf16 v[8:11], v[112:115], v[196:199], v[8:11]
	v_mfma_f32_16x16x32_bf16 v[4:7], v[104:107], v[208:211], v[4:7]
	v_mfma_f32_16x16x32_bf16 v[0:3], v[112:115], v[204:207], v[0:3]
	v_mfma_f32_16x16x32_bf16 v[142:145], v[120:123], v[72:75], v[24:27]
	v_mfma_f32_16x16x32_bf16 v[176:179], v[120:123], v[88:91], v[16:19]
	v_mfma_f32_16x16x32_bf16 v[180:183], v[120:123], v[200:203], v[8:11]
	v_mfma_f32_16x16x32_bf16 v[196:199], v[120:123], v[208:211], v[0:3]
	s_setprio 0
	s_barrier
	s_nop 1
	ds_read_b128 v[0:3], v160
	ds_read_b128 v[8:11], v160 offset:1024
	ds_read_b128 v[16:19], v160 offset:2048
	ds_read_b128 v[24:27], v160 offset:3072
	ds_read_b128 v[32:35], v155 offset:32768
	ds_read_b128 v[40:43], v155 offset:33792
	ds_read_b128 v[48:51], v154 offset:32768
	ds_read_b128 v[56:59], v154 offset:33792
	ds_read_b128 v[64:67], v153 offset:32768
	ds_read_b128 v[158:161], v153 offset:33792
	ds_read_b128 v[200:203], v152 offset:32768
	ds_read_b128 v[204:207], v152 offset:33792
	s_waitcnt vmcnt(2)
	s_barrier
	s_waitcnt lgkmcnt(0)
	s_setprio 1
	s_waitcnt lgkmcnt(0)
	v_mfma_f32_16x16x32_bf16 v[72:75], v[0:3], v[32:35], v[124:127]
	v_mfma_f32_16x16x32_bf16 v[120:123], v[8:11], v[40:43], v[72:75]
	v_mfma_f32_16x16x32_bf16 v[72:75], v[16:19], v[32:35], v[130:133]
	v_mfma_f32_16x16x32_bf16 v[124:127], v[24:27], v[40:43], v[72:75]
	v_mfma_f32_16x16x32_bf16 v[72:75], v[0:3], v[48:51], v[116:119]
	v_mfma_f32_16x16x32_bf16 v[112:115], v[8:11], v[56:59], v[72:75]
	v_mfma_f32_16x16x32_bf16 v[72:75], v[16:19], v[48:51], v[134:137]
	v_mfma_f32_16x16x32_bf16 v[116:119], v[24:27], v[56:59], v[72:75]
	v_mfma_f32_16x16x32_bf16 v[72:75], v[0:3], v[64:67], v[108:111]
	v_mfma_f32_16x16x32_bf16 v[104:107], v[8:11], v[158:161], v[72:75]
	v_mfma_f32_16x16x32_bf16 v[72:75], v[16:19], v[64:67], v[172:175]
	v_mfma_f32_16x16x32_bf16 v[108:111], v[24:27], v[158:161], v[72:75]
	v_mfma_f32_16x16x32_bf16 v[72:75], v[0:3], v[200:203], v[100:103]
	v_mfma_f32_16x16x32_bf16 v[96:99], v[8:11], v[204:207], v[72:75]
	v_mfma_f32_16x16x32_bf16 v[72:75], v[16:19], v[200:203], v[216:219]
	v_mfma_f32_16x16x32_bf16 v[100:103], v[24:27], v[204:207], v[72:75]
	s_setprio 0
	s_barrier
	ds_read_b128 v[130:133], v156
	ds_read_b128 v[134:137], v156 offset:1024
	ds_read_b128 v[172:175], v156 offset:2048
	ds_read_b128 v[208:211], v156 offset:3072
	s_waitcnt vmcnt(0)
	s_barrier
	s_waitcnt lgkmcnt(0)
	s_setprio 1
	s_waitcnt lgkmcnt(0)
	v_mfma_f32_16x16x32_bf16 v[72:75], v[130:133], v[32:35], v[92:95]
	v_mfma_f32_16x16x32_bf16 v[32:35], v[172:175], v[32:35], v[168:171]
	v_mfma_f32_16x16x32_bf16 v[92:95], v[208:211], v[40:43], v[32:35]
	v_mfma_f32_16x16x32_bf16 v[32:35], v[130:133], v[48:51], v[84:87]
	v_mfma_f32_16x16x32_bf16 v[80:83], v[134:137], v[56:59], v[32:35]
	v_mfma_f32_16x16x32_bf16 v[32:35], v[172:175], v[48:51], v[184:187]
	v_mfma_f32_16x16x32_bf16 v[84:87], v[208:211], v[56:59], v[32:35]
	v_mfma_f32_16x16x32_bf16 v[32:35], v[130:133], v[64:67], v[76:79]
	v_mfma_f32_16x16x32_bf16 v[88:91], v[134:137], v[40:43], v[72:75]
	v_mfma_f32_16x16x32_bf16 v[72:75], v[134:137], v[158:161], v[32:35]
	v_mfma_f32_16x16x32_bf16 v[32:35], v[172:175], v[64:67], v[188:191]
	v_mfma_f32_16x16x32_bf16 v[76:79], v[208:211], v[158:161], v[32:35]
	v_mfma_f32_16x16x32_bf16 v[32:35], v[130:133], v[200:203], v[68:71]
	v_mfma_f32_16x16x32_bf16 v[64:67], v[134:137], v[204:207], v[32:35]
	v_mfma_f32_16x16x32_bf16 v[32:35], v[172:175], v[200:203], v[192:195]
	v_mfma_f32_16x16x32_bf16 v[68:71], v[208:211], v[204:207], v[32:35]
	s_setprio 0
	s_barrier
	ds_read_b128 v[156:159], v155 offset:49152
	ds_read_b128 v[160:163], v155 offset:50176
	ds_read_b128 v[168:171], v154 offset:49152
	ds_read_b128 v[184:187], v154 offset:50176
	ds_read_b128 v[188:191], v153 offset:49152
	ds_read_b128 v[192:195], v153 offset:50176
	ds_read_b128 v[200:203], v152 offset:49152
	ds_read_b128 v[152:155], v152 offset:50176
	s_barrier
	s_waitcnt lgkmcnt(0)
	s_setprio 1
	s_waitcnt lgkmcnt(0)
	v_mfma_f32_16x16x32_bf16 v[32:35], v[0:3], v[156:159], v[60:63]
	v_mfma_f32_16x16x32_bf16 v[56:59], v[8:11], v[160:163], v[32:35]
	v_mfma_f32_16x16x32_bf16 v[32:35], v[16:19], v[156:159], v[212:215]
	v_mfma_f32_16x16x32_bf16 v[60:63], v[24:27], v[160:163], v[32:35]
	v_mfma_f32_16x16x32_bf16 v[32:35], v[0:3], v[168:171], v[52:55]
	v_mfma_f32_16x16x32_bf16 v[48:51], v[8:11], v[184:187], v[32:35]
	v_mfma_f32_16x16x32_bf16 v[32:35], v[16:19], v[168:171], v[220:223]
	v_mfma_f32_16x16x32_bf16 v[52:55], v[24:27], v[184:187], v[32:35]
	v_mfma_f32_16x16x32_bf16 v[32:35], v[0:3], v[188:191], v[44:47]
	v_mfma_f32_16x16x32_bf16 v[40:43], v[8:11], v[192:195], v[32:35]
	v_mfma_f32_16x16x32_bf16 v[32:35], v[16:19], v[188:191], v[224:227]
	v_mfma_f32_16x16x32_bf16 v[0:3], v[0:3], v[200:203], v[36:39]
	v_mfma_f32_16x16x32_bf16 v[44:47], v[24:27], v[192:195], v[32:35]
	v_mfma_f32_16x16x32_bf16 v[32:35], v[8:11], v[152:155], v[0:3]
	v_mfma_f32_16x16x32_bf16 v[0:3], v[16:19], v[200:203], v[138:141]
	v_mfma_f32_16x16x32_bf16 v[36:39], v[24:27], v[152:155], v[0:3]
	s_setprio 0
	s_setprio 1
	v_mfma_f32_16x16x32_bf16 v[0:3], v[130:133], v[156:159], v[28:31]
	v_mfma_f32_16x16x32_bf16 v[24:27], v[134:137], v[160:163], v[0:3]
	v_mfma_f32_16x16x32_bf16 v[0:3], v[172:175], v[156:159], v[142:145]
	v_mfma_f32_16x16x32_bf16 v[28:31], v[208:211], v[160:163], v[0:3]
	v_mfma_f32_16x16x32_bf16 v[0:3], v[130:133], v[168:171], v[20:23]
	v_mfma_f32_16x16x32_bf16 v[16:19], v[134:137], v[184:187], v[0:3]
	v_mfma_f32_16x16x32_bf16 v[0:3], v[172:175], v[168:171], v[176:179]
	v_mfma_f32_16x16x32_bf16 v[20:23], v[208:211], v[184:187], v[0:3]
	v_mfma_f32_16x16x32_bf16 v[0:3], v[130:133], v[188:191], v[12:15]
	v_mfma_f32_16x16x32_bf16 v[8:11], v[134:137], v[192:195], v[0:3]
	v_mfma_f32_16x16x32_bf16 v[0:3], v[172:175], v[188:191], v[180:183]
	v_mfma_f32_16x16x32_bf16 v[12:15], v[208:211], v[192:195], v[0:3]
	v_mfma_f32_16x16x32_bf16 v[0:3], v[130:133], v[200:203], v[4:7]
	v_mfma_f32_16x16x32_bf16 v[4:7], v[172:175], v[200:203], v[196:199]
	v_mfma_f32_16x16x32_bf16 v[0:3], v[134:137], v[152:155], v[0:3]
	v_mfma_f32_16x16x32_bf16 v[4:7], v[208:211], v[152:155], v[4:7]
	s_setprio 0
	v_cmp_gt_u32_e32 vcc, s56, v128
	s_barrier
	s_and_saveexec_b64 s[34:35], vcc
	s_cbranch_execz .LBB0_2967
	s_barrier
	s_branch .LBB0_2967
